# also drop the mid-block setprio 0/1 pair and move the trailing setprio 0 after the post-MFMA barrier
# baseline (speedup 1.0000x reference)
; #define PG8_STAGE(bufoff, gbase, VO) do { _Pragma("unroll") for (int _i = 0; _i < 2; ++_i) \
;         __builtin_amdgcn_global_load_lds((const unsigned*)((const char*)(gbase) + VO[_i]), (LAS unsigned*)(lds + (bufoff) + ldsw + _i * 8192), 16, 0, 0); } while (0)
; #define PG8_LDA(dst, b, h) do { _Pragma("unroll") for (int m = 0; m < 4; ++m) _Pragma("unroll") for (int k = 0; k < 2; ++k) dst[m][k] = *(const LAS bf16x8*)(lds + PG8_SA(b, h) + aoff + m * 2048 + k * 1024); } while (0)
; #define PG8_LDB(dst, b, h) do { _Pragma("unroll") for (int n = 0; n < 2; ++n) _Pragma("unroll") for (int k = 0; k < 2; ++k) dst[n][k] = *(const LAS bf16x8*)(lds + PG8_SB(b, h) + boff + n * 2048 + k * 1024); } while (0)
; #define PG8_MMA(ai, bj, At, Bt) do { __builtin_amdgcn_s_setprio(1); _Pragma("unroll") for (int m = 0; m < 4; ++m) _Pragma("unroll") for (int n = 0; n < 2; ++n) _Pragma("unroll") for (int k = 0; k < 2; ++k) \
;         acc[ai][bj][m][n] = __builtin_amdgcn_mfma_f32_16x16x32_bf16(Bt[n][k], At[m][k], acc[ai][bj][m][n], 0, 0, 0); __builtin_amdgcn_s_setprio(0); } while (0)
; #define PG8_WAIT_V(n) asm volatile("s_waitcnt vmcnt(" #n ")" ::: "memory")
; #define PG8_WAIT_L(n) asm volatile("s_waitcnt lgkmcnt(" #n ")" ::: "memory")
; #define PG8_BAR __builtin_amdgcn_s_barrier()
; #define PG8_SCHED __builtin_amdgcn_sched_barrier(0)
; template <int NSEG, class Epi, bool ALIGN_EPI = PG8_ALIGN, bool SP2 = PG8_SP2>
; DI void gemm_phase(LAS unsigned char* lds, const Gemm g, const StaticOrder& S, const Epi& E) {
;     ...
;             PG8_LDB(B0, 0, 0); PG8_LDB(B1, 0, 1); PG8_SCHED; PG8_LDA(At, 0, 0); PG8_STAGE(PG8_SA(1, 1), a1 + hstepC, voffC);
;             PG8_WAIT_V(8); PG8_WAIT_L(0); PG8_BAR; PG8_MMA(0, 0, At, B0); PG8_MMA(0, 1, At, B1); PG8_BAR; PG8_SCHED;
;             PG8_LDA(At, 0, 1); PG8_STAGE(PG8_SB(0, 0), b2, v2); PG8_STAGE(PG8_SB(0, 1), b2 + h2, v2); PG8_STAGE(PG8_SA(0, 0), a2, v2);
.LBB0_139:
	v_add_u32_e32 v134, s62, v157
	ds_read_b128 v[144:147], v178
	ds_read_b128 v[148:151], v178 offset:1024
	ds_read_b128 v[152:155], v178 offset:2048
	ds_read_b128 v[182:185], v178 offset:3072
	ds_read_b128 v[186:189], v134
	ds_read_b128 v[190:193], v134 offset:1024
	ds_read_b128 v[194:197], v134 offset:2048
	ds_read_b128 v[198:201], v134 offset:3072
	s_add_u32 s36, s34, 0xfff80080
	s_addc_u32 s37, s35, -1
	s_cmp_eq_u32 s72, 28
	s_cselect_b32 s41, s3, s37
	s_cselect_b32 s40, s25, s36
	s_cselect_b32 s37, s27, s71
	s_cselect_b32 s36, s69, s70
	v_lshl_add_u64 v[234:235], s[34:35], 0, v[136:137]
	s_add_i32 m0, s45, 0xc000
	ds_read_b128 v[202:205], v179
	ds_read_b128 v[206:209], v179 offset:1024
	ds_read_b128 v[210:213], v179 offset:2048
	ds_read_b128 v[214:217], v179 offset:3072
	ds_read_b128 v[218:221], v179 offset:4096
	ds_read_b128 v[222:225], v179 offset:5120
	ds_read_b128 v[226:229], v179 offset:6144
	ds_read_b128 v[230:233], v179 offset:7168
	global_load_lds_dwordx4 v[234:235], off
	v_lshl_add_u64 v[234:235], s[34:35], 0, v[138:139]
	s_add_i32 m0, s45, 0xe000
	s_nop 0
	global_load_lds_dwordx4 v[234:235], off
	s_waitcnt vmcnt(8)
	s_waitcnt lgkmcnt(0)
	s_setprio 1
	s_barrier
	v_mfma_f32_16x16x32_bf16 v[126:129], v[144:147], v[202:205], v[126:129]
	v_mfma_f32_16x16x32_bf16 v[122:125], v[152:155], v[202:205], v[122:125]
	v_mfma_f32_16x16x32_bf16 v[110:113], v[144:147], v[210:213], v[110:113]
	v_mfma_f32_16x16x32_bf16 v[106:109], v[152:155], v[210:213], v[106:109]
	v_mfma_f32_16x16x32_bf16 v[94:97], v[144:147], v[218:221], v[94:97]
	v_mfma_f32_16x16x32_bf16 v[90:93], v[152:155], v[218:221], v[90:93]
	v_mfma_f32_16x16x32_bf16 v[78:81], v[144:147], v[226:229], v[78:81]
	v_mfma_f32_16x16x32_bf16 v[74:77], v[152:155], v[226:229], v[74:77]
	v_mfma_f32_16x16x32_bf16 v[126:129], v[148:151], v[206:209], v[126:129]
	v_mfma_f32_16x16x32_bf16 v[122:125], v[182:185], v[206:209], v[122:125]
	v_mfma_f32_16x16x32_bf16 v[110:113], v[148:151], v[214:217], v[110:113]
	v_mfma_f32_16x16x32_bf16 v[106:109], v[182:185], v[214:217], v[106:109]
	v_mfma_f32_16x16x32_bf16 v[94:97], v[148:151], v[222:225], v[94:97]
	v_mfma_f32_16x16x32_bf16 v[90:93], v[182:185], v[222:225], v[90:93]
	v_mfma_f32_16x16x32_bf16 v[78:81], v[148:151], v[230:233], v[78:81]
	v_mfma_f32_16x16x32_bf16 v[74:77], v[182:185], v[230:233], v[74:77]
	v_mfma_f32_16x16x32_bf16 v[118:121], v[186:189], v[202:205], v[118:121]
	v_mfma_f32_16x16x32_bf16 v[114:117], v[194:197], v[202:205], v[114:117]
	v_mfma_f32_16x16x32_bf16 v[102:105], v[186:189], v[210:213], v[102:105]
	v_mfma_f32_16x16x32_bf16 v[98:101], v[194:197], v[210:213], v[98:101]
	v_mfma_f32_16x16x32_bf16 v[86:89], v[186:189], v[218:221], v[86:89]
	v_mfma_f32_16x16x32_bf16 v[82:85], v[194:197], v[218:221], v[82:85]
	v_mfma_f32_16x16x32_bf16 v[70:73], v[186:189], v[226:229], v[70:73]
	v_mfma_f32_16x16x32_bf16 v[66:69], v[194:197], v[226:229], v[66:69]
	v_mfma_f32_16x16x32_bf16 v[118:121], v[190:193], v[206:209], v[118:121]
	v_mfma_f32_16x16x32_bf16 v[114:117], v[198:201], v[206:209], v[114:117]
	v_mfma_f32_16x16x32_bf16 v[102:105], v[190:193], v[214:217], v[102:105]
	v_mfma_f32_16x16x32_bf16 v[98:101], v[198:201], v[214:217], v[98:101]
	v_mfma_f32_16x16x32_bf16 v[86:89], v[190:193], v[222:225], v[86:89]
	v_mfma_f32_16x16x32_bf16 v[82:85], v[198:201], v[222:225], v[82:85]
	v_mfma_f32_16x16x32_bf16 v[70:73], v[190:193], v[230:233], v[70:73]
	v_mfma_f32_16x16x32_bf16 v[66:69], v[198:201], v[230:233], v[66:69]
	s_barrier
	s_setprio 0
	s_add_i32 s73, s61, s51
	v_lshl_add_u64 v[234:235], s[36:37], 0, v[130:131]
	s_mov_b32 m0, s73
	ds_read_b128 v[202:205], v179 offset:16384
	ds_read_b128 v[206:209], v179 offset:17408
	ds_read_b128 v[210:213], v179 offset:18432
	ds_read_b128 v[214:217], v179 offset:19456
	ds_read_b128 v[218:221], v179 offset:20480
	ds_read_b128 v[222:225], v179 offset:21504
	ds_read_b128 v[226:229], v179 offset:22528
	ds_read_b128 v[230:233], v179 offset:23552
	global_load_lds_dwordx4 v[234:235], off
	s_add_i32 m0, s73, 0x2000
	s_add_u32 s74, s36, 0x80000
	v_lshl_add_u64 v[236:237], s[36:37], 0, v[132:133]
	s_addc_u32 s75, s37, 0
	s_add_i32 s73, s62, s51
	global_load_lds_dwordx4 v[236:237], off
	v_lshl_add_u64 v[238:239], s[74:75], 0, v[130:131]
	s_mov_b32 m0, s73
	v_lshl_add_u64 v[240:241], s[40:41], 0, v[132:133]
	global_load_lds_dwordx4 v[238:239], off
	v_lshl_add_u64 v[238:239], s[74:75], 0, v[132:133]
	s_add_i32 m0, s73, 0x2000
	s_nop 0
	global_load_lds_dwordx4 v[238:239], off
	v_lshl_add_u64 v[238:239], s[40:41], 0, v[130:131]
	s_mov_b32 m0, s45
	s_nop 0
	global_load_lds_dwordx4 v[238:239], off
	s_mov_b32 m0, s54
	s_nop 0
	global_load_lds_dwordx4 v[240:241], off
	s_waitcnt vmcnt(8)
	s_waitcnt lgkmcnt(0)
	s_setprio 1
	s_barrier
; #define PG8_STAGE(bufoff, gbase, VO) do { _Pragma("unroll") for (int _i = 0; _i < 2; ++_i) \
;         __builtin_amdgcn_global_load_lds((const unsigned*)((const char*)(gbase) + VO[_i]), (LAS unsigned*)(lds + (bufoff) + ldsw + _i * 8192), 16, 0, 0); } while (0)
; #define PG8_LDA(dst, b, h) do { _Pragma("unroll") for (int m = 0; m < 4; ++m) _Pragma("unroll") for (int k = 0; k < 2; ++k) dst[m][k] = *(const LAS bf16x8*)(lds + PG8_SA(b, h) + aoff + m * 2048 + k * 1024); } while (0)
; #define PG8_LDB(dst, b, h) do { _Pragma("unroll") for (int n = 0; n < 2; ++n) _Pragma("unroll") for (int k = 0; k < 2; ++k) dst[n][k] = *(const LAS bf16x8*)(lds + PG8_SB(b, h) + boff + n * 2048 + k * 1024); } while (0)
; #define PG8_MMA(ai, bj, At, Bt) do { __builtin_amdgcn_s_setprio(1); _Pragma("unroll") for (int m = 0; m < 4; ++m) _Pragma("unroll") for (int n = 0; n < 2; ++n) _Pragma("unroll") for (int k = 0; k < 2; ++k) \
;         acc[ai][bj][m][n] = __builtin_amdgcn_mfma_f32_16x16x32_bf16(Bt[n][k], At[m][k], acc[ai][bj][m][n], 0, 0, 0); __builtin_amdgcn_s_setprio(0); } while (0)
; #define PG8_WAIT_V(n) asm volatile("s_waitcnt vmcnt(" #n ")" ::: "memory")
; #define PG8_WAIT_L(n) asm volatile("s_waitcnt lgkmcnt(" #n ")" ::: "memory")
; #define PG8_BAR __builtin_amdgcn_s_barrier()
; #define PG8_SCHED __builtin_amdgcn_sched_barrier(0)
; template <int NSEG, class Epi, bool ALIGN_EPI = PG8_ALIGN, bool SP2 = PG8_SP2>
; DI void gemm_phase(LAS unsigned char* lds, const Gemm g, const StaticOrder& S, const Epi& E) {
;     ...
;             PG8_WAIT_V(8); PG8_WAIT_L(0); PG8_BAR; PG8_MMA(1, 0, At, B0); PG8_MMA(1, 1, At, B1); PG8_BAR; PG8_SCHED;
;             PG8_LDB(B0, 1, 0); PG8_LDB(B1, 1, 1); PG8_SCHED; PG8_LDA(At, 1, 0); PG8_STAGE(PG8_SA(0, 1), a2 + h2, v2);
;             PG8_WAIT_V(8); PG8_WAIT_L(0); PG8_BAR; PG8_MMA(0, 0, At, B0); PG8_MMA(0, 1, At, B1); PG8_BAR; PG8_SCHED;
	v_mfma_f32_16x16x32_bf16 v[62:65], v[144:147], v[202:205], v[62:65]
	v_mfma_f32_16x16x32_bf16 v[58:61], v[152:155], v[202:205], v[58:61]
	v_mfma_f32_16x16x32_bf16 v[46:49], v[144:147], v[210:213], v[46:49]
	v_mfma_f32_16x16x32_bf16 v[42:45], v[152:155], v[210:213], v[42:45]
	v_mfma_f32_16x16x32_bf16 v[22:25], v[144:147], v[218:221], v[22:25]
	v_mfma_f32_16x16x32_bf16 v[18:21], v[152:155], v[218:221], v[18:21]
	v_mfma_f32_16x16x32_bf16 v[6:9], v[144:147], v[226:229], v[6:9]
	v_mfma_f32_16x16x32_bf16 v[2:5], v[152:155], v[226:229], v[2:5]
	v_mfma_f32_16x16x32_bf16 v[62:65], v[148:151], v[206:209], v[62:65]
	v_mfma_f32_16x16x32_bf16 v[58:61], v[182:185], v[206:209], v[58:61]
	v_mfma_f32_16x16x32_bf16 v[46:49], v[148:151], v[214:217], v[46:49]
	v_mfma_f32_16x16x32_bf16 v[42:45], v[182:185], v[214:217], v[42:45]
	v_mfma_f32_16x16x32_bf16 v[22:25], v[148:151], v[222:225], v[22:25]
	v_mfma_f32_16x16x32_bf16 v[18:21], v[182:185], v[222:225], v[18:21]
	v_mfma_f32_16x16x32_bf16 v[6:9], v[148:151], v[230:233], v[6:9]
	v_mfma_f32_16x16x32_bf16 v[2:5], v[182:185], v[230:233], v[2:5]
	v_mfma_f32_16x16x32_bf16 v[54:57], v[186:189], v[202:205], v[54:57]
	v_mfma_f32_16x16x32_bf16 v[50:53], v[194:197], v[202:205], v[50:53]
	v_mfma_f32_16x16x32_bf16 v[38:41], v[186:189], v[210:213], v[38:41]
	v_mfma_f32_16x16x32_bf16 v[26:29], v[194:197], v[210:213], v[26:29]
	v_mfma_f32_16x16x32_bf16 v[34:37], v[186:189], v[218:221], v[34:37]
	v_mfma_f32_16x16x32_bf16 v[30:33], v[194:197], v[218:221], v[30:33]
	v_mfma_f32_16x16x32_bf16 v[14:17], v[186:189], v[226:229], v[14:17]
	v_mfma_f32_16x16x32_bf16 v[10:13], v[194:197], v[226:229], v[10:13]
	v_mfma_f32_16x16x32_bf16 v[54:57], v[190:193], v[206:209], v[54:57]
	v_mfma_f32_16x16x32_bf16 v[50:53], v[198:201], v[206:209], v[50:53]
	v_mfma_f32_16x16x32_bf16 v[38:41], v[190:193], v[214:217], v[38:41]
	v_mfma_f32_16x16x32_bf16 v[26:29], v[198:201], v[214:217], v[26:29]
	v_mfma_f32_16x16x32_bf16 v[34:37], v[190:193], v[222:225], v[34:37]
	v_mfma_f32_16x16x32_bf16 v[30:33], v[198:201], v[222:225], v[30:33]
	v_mfma_f32_16x16x32_bf16 v[14:17], v[190:193], v[230:233], v[14:17]
	v_mfma_f32_16x16x32_bf16 v[10:13], v[198:201], v[230:233], v[10:13]
	s_barrier
	s_setprio 0
	s_add_i32 s73, 0, 0x18000
	v_add_u32_e32 v134, s73, v157
	s_add_i32 s74, 0, 0x1c000
	ds_read_b128 v[144:147], v134
	ds_read_b128 v[148:151], v134 offset:1024
	ds_read_b128 v[152:155], v134 offset:2048
	ds_read_b128 v[182:185], v134 offset:3072
	v_add_u32_e32 v134, s74, v157
	ds_read_b128 v[186:189], v134
	ds_read_b128 v[190:193], v134 offset:1024
	ds_read_b128 v[194:197], v134 offset:2048
	ds_read_b128 v[198:201], v134 offset:3072
	s_add_u32 s40, s40, 0x80000
	s_addc_u32 s41, s41, 0
	s_mov_b32 m0, s55
	v_lshl_add_u64 v[242:243], s[40:41], 0, v[130:131]
	ds_read_b128 v[202:205], v179 offset:32768
	ds_read_b128 v[206:209], v179 offset:33792
	ds_read_b128 v[210:213], v179 offset:34816
	ds_read_b128 v[214:217], v179 offset:35840
	ds_read_b128 v[218:221], v179 offset:36864
	ds_read_b128 v[222:225], v179 offset:37888
	ds_read_b128 v[226:229], v179 offset:38912
	ds_read_b128 v[230:233], v179 offset:39936
	global_load_lds_dwordx4 v[242:243], off
	v_lshl_add_u64 v[242:243], s[40:41], 0, v[132:133]
	s_mov_b32 m0, s56
	s_nop 0
	global_load_lds_dwordx4 v[242:243], off
	s_waitcnt vmcnt(8)
	s_waitcnt lgkmcnt(0)
	s_setprio 1
	s_barrier
	v_mfma_f32_16x16x32_bf16 v[126:129], v[144:147], v[202:205], v[126:129]
	v_mfma_f32_16x16x32_bf16 v[122:125], v[152:155], v[202:205], v[122:125]
	v_mfma_f32_16x16x32_bf16 v[110:113], v[144:147], v[210:213], v[110:113]
	v_mfma_f32_16x16x32_bf16 v[106:109], v[152:155], v[210:213], v[106:109]
	v_mfma_f32_16x16x32_bf16 v[94:97], v[144:147], v[218:221], v[94:97]
	v_mfma_f32_16x16x32_bf16 v[90:93], v[152:155], v[218:221], v[90:93]
	v_mfma_f32_16x16x32_bf16 v[78:81], v[144:147], v[226:229], v[78:81]
	v_mfma_f32_16x16x32_bf16 v[74:77], v[152:155], v[226:229], v[74:77]
	v_mfma_f32_16x16x32_bf16 v[126:129], v[148:151], v[206:209], v[126:129]
	v_mfma_f32_16x16x32_bf16 v[122:125], v[182:185], v[206:209], v[122:125]
	v_mfma_f32_16x16x32_bf16 v[110:113], v[148:151], v[214:217], v[110:113]
	v_mfma_f32_16x16x32_bf16 v[106:109], v[182:185], v[214:217], v[106:109]
	v_mfma_f32_16x16x32_bf16 v[94:97], v[148:151], v[222:225], v[94:97]
	v_mfma_f32_16x16x32_bf16 v[90:93], v[182:185], v[222:225], v[90:93]
	v_mfma_f32_16x16x32_bf16 v[78:81], v[148:151], v[230:233], v[78:81]
	v_mfma_f32_16x16x32_bf16 v[74:77], v[182:185], v[230:233], v[74:77]
	v_mfma_f32_16x16x32_bf16 v[118:121], v[186:189], v[202:205], v[118:121]
	v_mfma_f32_16x16x32_bf16 v[114:117], v[194:197], v[202:205], v[114:117]
	v_mfma_f32_16x16x32_bf16 v[102:105], v[186:189], v[210:213], v[102:105]
	v_mfma_f32_16x16x32_bf16 v[98:101], v[194:197], v[210:213], v[98:101]
	v_mfma_f32_16x16x32_bf16 v[86:89], v[186:189], v[218:221], v[86:89]
	v_mfma_f32_16x16x32_bf16 v[82:85], v[194:197], v[218:221], v[82:85]
	v_mfma_f32_16x16x32_bf16 v[70:73], v[186:189], v[226:229], v[70:73]
	v_mfma_f32_16x16x32_bf16 v[66:69], v[194:197], v[226:229], v[66:69]
	v_mfma_f32_16x16x32_bf16 v[118:121], v[190:193], v[206:209], v[118:121]
	v_mfma_f32_16x16x32_bf16 v[114:117], v[198:201], v[206:209], v[114:117]
	v_mfma_f32_16x16x32_bf16 v[102:105], v[190:193], v[214:217], v[102:105]
	v_mfma_f32_16x16x32_bf16 v[98:101], v[198:201], v[214:217], v[98:101]
	v_mfma_f32_16x16x32_bf16 v[86:89], v[190:193], v[222:225], v[86:89]
	v_mfma_f32_16x16x32_bf16 v[82:85], v[198:201], v[222:225], v[82:85]
	v_mfma_f32_16x16x32_bf16 v[70:73], v[190:193], v[230:233], v[70:73]
	v_mfma_f32_16x16x32_bf16 v[66:69], v[198:201], v[230:233], v[66:69]
	s_barrier
; #define PG8_STAGE(bufoff, gbase, VO) do { _Pragma("unroll") for (int _i = 0; _i < 2; ++_i) \
;         __builtin_amdgcn_global_load_lds((const unsigned*)((const char*)(gbase) + VO[_i]), (LAS unsigned*)(lds + (bufoff) + ldsw + _i * 8192), 16, 0, 0); } while (0)
; #define PG8_LDA(dst, b, h) do { _Pragma("unroll") for (int m = 0; m < 4; ++m) _Pragma("unroll") for (int k = 0; k < 2; ++k) dst[m][k] = *(const LAS bf16x8*)(lds + PG8_SA(b, h) + aoff + m * 2048 + k * 1024); } while (0)
; #define PG8_MMA(ai, bj, At, Bt) do { __builtin_amdgcn_s_setprio(1); _Pragma("unroll") for (int m = 0; m < 4; ++m) _Pragma("unroll") for (int n = 0; n < 2; ++n) _Pragma("unroll") for (int k = 0; k < 2; ++k) \
;         acc[ai][bj][m][n] = __builtin_amdgcn_mfma_f32_16x16x32_bf16(Bt[n][k], At[m][k], acc[ai][bj][m][n], 0, 0, 0); __builtin_amdgcn_s_setprio(0); } while (0)
; #define PG8_WAIT_V(n) asm volatile("s_waitcnt vmcnt(" #n ")" ::: "memory")
; #define PG8_WAIT_L(n) asm volatile("s_waitcnt lgkmcnt(" #n ")" ::: "memory")
; #define PG8_BAR __builtin_amdgcn_s_barrier()
; #define PG8_SCHED __builtin_amdgcn_sched_barrier(0)
; template <int NSEG, class Epi, bool ALIGN_EPI = PG8_ALIGN, bool SP2 = PG8_SP2>
; DI void gemm_phase(LAS unsigned char* lds, const Gemm g, const StaticOrder& S, const Epi& E) {
;     ...
;             PG8_LDA(At, 1, 1); PG8_STAGE(PG8_SB(1, 0), b3, v2); PG8_STAGE(PG8_SB(1, 1), b3 + h2, v2); PG8_STAGE(PG8_SA(1, 0), a3, v2);
;             PG8_WAIT_V(8); PG8_WAIT_L(0); PG8_BAR; PG8_MMA(1, 0, At, B0); PG8_MMA(1, 1, At, B1); PG8_BAR; PG8_SCHED;
	s_setprio 0
	s_add_i32 s40, s73, s51
	v_lshl_add_u64 v[234:235], v[234:235], 0, s[12:13]
	s_mov_b32 m0, s40
	ds_read_b128 v[202:205], v179 offset:49152
	ds_read_b128 v[206:209], v179 offset:50176
	ds_read_b128 v[210:213], v179 offset:51200
	ds_read_b128 v[214:217], v179 offset:52224
	ds_read_b128 v[218:221], v179 offset:53248
	ds_read_b128 v[222:225], v179 offset:54272
	ds_read_b128 v[226:229], v179 offset:55296
	ds_read_b128 v[230:233], v179 offset:56320
	global_load_lds_dwordx4 v[234:235], off
	s_add_i32 m0, s40, 0x2000
	s_add_u32 s36, s36, 0x80080
	v_lshl_add_u64 v[234:235], v[236:237], 0, s[12:13]
	s_addc_u32 s37, s37, 0
	s_add_i32 s40, s74, s51
	global_load_lds_dwordx4 v[234:235], off
	v_lshl_add_u64 v[234:235], s[36:37], 0, v[130:131]
	s_mov_b32 m0, s40
	s_nop 0
	global_load_lds_dwordx4 v[234:235], off
	v_lshl_add_u64 v[234:235], s[36:37], 0, v[132:133]
	s_add_i32 m0, s40, 0x2000
	s_nop 0
	global_load_lds_dwordx4 v[234:235], off
	v_lshl_add_u64 v[234:235], v[238:239], 0, s[12:13]
	s_mov_b32 m0, s57
	s_nop 0
	global_load_lds_dwordx4 v[234:235], off
	v_lshl_add_u64 v[234:235], v[240:241], 0, s[12:13]
	s_mov_b32 m0, s58
	s_nop 0
	global_load_lds_dwordx4 v[234:235], off
	s_waitcnt vmcnt(8)
	s_waitcnt lgkmcnt(0)
	s_setprio 1
	s_barrier
	v_mfma_f32_16x16x32_bf16 v[62:65], v[144:147], v[202:205], v[62:65]
	v_mfma_f32_16x16x32_bf16 v[58:61], v[152:155], v[202:205], v[58:61]
	v_mfma_f32_16x16x32_bf16 v[46:49], v[144:147], v[210:213], v[46:49]
	v_mfma_f32_16x16x32_bf16 v[42:45], v[152:155], v[210:213], v[42:45]
	v_mfma_f32_16x16x32_bf16 v[22:25], v[144:147], v[218:221], v[22:25]
	v_mfma_f32_16x16x32_bf16 v[18:21], v[152:155], v[218:221], v[18:21]
	v_mfma_f32_16x16x32_bf16 v[6:9], v[144:147], v[226:229], v[6:9]
	v_mfma_f32_16x16x32_bf16 v[2:5], v[152:155], v[226:229], v[2:5]
	v_mfma_f32_16x16x32_bf16 v[62:65], v[148:151], v[206:209], v[62:65]
	v_mfma_f32_16x16x32_bf16 v[58:61], v[182:185], v[206:209], v[58:61]
	v_mfma_f32_16x16x32_bf16 v[46:49], v[148:151], v[214:217], v[46:49]
	v_mfma_f32_16x16x32_bf16 v[42:45], v[182:185], v[214:217], v[42:45]
	v_mfma_f32_16x16x32_bf16 v[22:25], v[148:151], v[222:225], v[22:25]
	v_mfma_f32_16x16x32_bf16 v[18:21], v[182:185], v[222:225], v[18:21]
	v_mfma_f32_16x16x32_bf16 v[6:9], v[148:151], v[230:233], v[6:9]
	v_mfma_f32_16x16x32_bf16 v[2:5], v[182:185], v[230:233], v[2:5]
	v_mfma_f32_16x16x32_bf16 v[54:57], v[186:189], v[202:205], v[54:57]
	v_mfma_f32_16x16x32_bf16 v[50:53], v[194:197], v[202:205], v[50:53]
	v_mfma_f32_16x16x32_bf16 v[38:41], v[186:189], v[210:213], v[38:41]
	v_mfma_f32_16x16x32_bf16 v[26:29], v[194:197], v[210:213], v[26:29]
	v_mfma_f32_16x16x32_bf16 v[34:37], v[186:189], v[218:221], v[34:37]
	v_mfma_f32_16x16x32_bf16 v[30:33], v[194:197], v[218:221], v[30:33]
	v_mfma_f32_16x16x32_bf16 v[14:17], v[186:189], v[226:229], v[14:17]
	v_mfma_f32_16x16x32_bf16 v[10:13], v[194:197], v[226:229], v[10:13]
	v_mfma_f32_16x16x32_bf16 v[54:57], v[190:193], v[206:209], v[54:57]
	v_mfma_f32_16x16x32_bf16 v[50:53], v[198:201], v[206:209], v[50:53]
	v_mfma_f32_16x16x32_bf16 v[38:41], v[190:193], v[214:217], v[38:41]
	v_mfma_f32_16x16x32_bf16 v[26:29], v[198:201], v[214:217], v[26:29]
	v_mfma_f32_16x16x32_bf16 v[34:37], v[190:193], v[222:225], v[34:37]
	v_mfma_f32_16x16x32_bf16 v[30:33], v[198:201], v[222:225], v[30:33]
	v_mfma_f32_16x16x32_bf16 v[14:17], v[190:193], v[230:233], v[14:17]
	v_mfma_f32_16x16x32_bf16 v[10:13], v[198:201], v[230:233], v[10:13]
	s_barrier
	s_setprio 0
	s_add_i32 s72, s72, 2
	s_add_u32 s34, s34, 0x100
	s_addc_u32 s35, s35, 0
	s_add_u32 s70, s70, 0x100
	s_addc_u32 s71, s71, 0
	s_cmp_gt_u32 s72, 29
	s_cbranch_scc0 .LBB0_139
	s_and_b64 vcc, exec, s[14:15]
	s_cbranch_vccnz .LBB0_144
	v_lshl_add_u32 v144, s2, 8, v1
	s_cmp_gt_i32 s44, 15
	s_mov_b64 s[2:3], -1
	s_cbranch_scc1 .LBB0_145

; #define PG8_STAGE(bufoff, gbase, VO) do { _Pragma("unroll") for (int _i = 0; _i < 2; ++_i) \
;         __builtin_amdgcn_global_load_lds((const unsigned*)((const char*)(gbase) + VO[_i]), (LAS unsigned*)(lds + (bufoff) + ldsw + _i * 8192), 16, 0, 0); } while (0)
; #define PG8_LDA(dst, b, h) do { _Pragma("unroll") for (int m = 0; m < 4; ++m) _Pragma("unroll") for (int k = 0; k < 2; ++k) dst[m][k] = *(const LAS bf16x8*)(lds + PG8_SA(b, h) + aoff + m * 2048 + k * 1024); } while (0)
; #define PG8_LDB(dst, b, h) do { _Pragma("unroll") for (int n = 0; n < 2; ++n) _Pragma("unroll") for (int k = 0; k < 2; ++k) dst[n][k] = *(const LAS bf16x8*)(lds + PG8_SB(b, h) + boff + n * 2048 + k * 1024); } while (0)
; #define PG8_MMA(ai, bj, At, Bt) do { __builtin_amdgcn_s_setprio(1); _Pragma("unroll") for (int m = 0; m < 4; ++m) _Pragma("unroll") for (int n = 0; n < 2; ++n) _Pragma("unroll") for (int k = 0; k < 2; ++k) \
;         acc[ai][bj][m][n] = __builtin_amdgcn_mfma_f32_16x16x32_bf16(Bt[n][k], At[m][k], acc[ai][bj][m][n], 0, 0, 0); __builtin_amdgcn_s_setprio(0); } while (0)
; #define PG8_WAIT_V(n) asm volatile("s_waitcnt vmcnt(" #n ")" ::: "memory")
; #define PG8_WAIT_L(n) asm volatile("s_waitcnt lgkmcnt(" #n ")" ::: "memory")
; #define PG8_BAR __builtin_amdgcn_s_barrier()
; #define PG8_SCHED __builtin_amdgcn_sched_barrier(0)
; template <int NSEG, class Epi, bool ALIGN_EPI = PG8_ALIGN, bool SP2 = PG8_SP2>
; DI void gemm_phase(LAS unsigned char* lds, const Gemm g, const StaticOrder& S, const Epi& E) {
;     ...
;             PG8_LDB(B0, 0, 0); PG8_LDB(B1, 0, 1); PG8_SCHED; PG8_LDA(At, 0, 0); PG8_STAGE(PG8_SA(1, 1), a1 + hstepC, voffC);
;             PG8_WAIT_V(8); PG8_WAIT_L(0); PG8_BAR; PG8_MMA(0, 0, At, B0); PG8_MMA(0, 1, At, B1); PG8_BAR; PG8_SCHED;
;             PG8_LDA(At, 0, 1); PG8_STAGE(PG8_SB(0, 0), b2, v2); PG8_STAGE(PG8_SB(0, 1), b2 + h2, v2); PG8_STAGE(PG8_SA(0, 0), a2, v2);
.LBB0_281:
	ds_read_b128 v[42:45], v250
	ds_read_b128 v[46:49], v250 offset:1024
	ds_read_b128 v[58:61], v250 offset:2048
	ds_read_b128 v[62:65], v250 offset:3072
	ds_read_b128 v[122:125], v251
	ds_read_b128 v[134:137], v251 offset:1024
	ds_read_b128 v[146:149], v251 offset:2048
	ds_read_b128 v[150:153], v251 offset:3072
	s_add_u32 s24, s22, 0xfff80080
	s_addc_u32 s25, s23, -1
	s_cmp_eq_u32 s56, 28
	s_cselect_b32 s27, s15, s25
	s_cselect_b32 s26, s17, s24
	s_cselect_b32 s25, s52, s55
	s_cselect_b32 s24, s53, s54
	v_lshl_add_u64 v[194:195], s[22:23], 0, v[206:207]
	s_add_i32 m0, s37, 0xc000
	ds_read_b128 v[154:157], v252
	ds_read_b128 v[166:169], v252 offset:1024
	ds_read_b128 v[170:173], v252 offset:2048
	ds_read_b128 v[174:177], v252 offset:3072
	ds_read_b128 v[178:181], v252 offset:4096
	ds_read_b128 v[182:185], v252 offset:5120
	ds_read_b128 v[186:189], v252 offset:6144
	ds_read_b128 v[190:193], v252 offset:7168
	global_load_lds_dwordx4 v[194:195], off
	v_lshl_add_u64 v[194:195], s[22:23], 0, v[208:209]
	s_add_i32 m0, s37, 0xe000
	s_nop 0
	global_load_lds_dwordx4 v[194:195], off
	s_waitcnt vmcnt(8)
	s_waitcnt lgkmcnt(0)
	s_setprio 1
	s_barrier
	v_mfma_f32_16x16x32_bf16 v[162:165], v[42:45], v[154:157], v[162:165]
	v_mfma_f32_16x16x32_bf16 v[158:161], v[58:61], v[154:157], v[158:161]
	v_mfma_f32_16x16x32_bf16 v[130:133], v[42:45], v[170:173], v[130:133]
	v_mfma_f32_16x16x32_bf16 v[126:129], v[58:61], v[170:173], v[126:129]
	v_mfma_f32_16x16x32_bf16 v[110:113], v[42:45], v[178:181], v[110:113]
	v_mfma_f32_16x16x32_bf16 v[106:109], v[58:61], v[178:181], v[106:109]
	v_mfma_f32_16x16x32_bf16 v[94:97], v[42:45], v[186:189], v[94:97]
	v_mfma_f32_16x16x32_bf16 v[90:93], v[58:61], v[186:189], v[90:93]
	v_mfma_f32_16x16x32_bf16 v[162:165], v[46:49], v[166:169], v[162:165]
	v_mfma_f32_16x16x32_bf16 v[158:161], v[62:65], v[166:169], v[158:161]
	v_mfma_f32_16x16x32_bf16 v[130:133], v[46:49], v[174:177], v[130:133]
	v_mfma_f32_16x16x32_bf16 v[126:129], v[62:65], v[174:177], v[126:129]
	v_mfma_f32_16x16x32_bf16 v[110:113], v[46:49], v[182:185], v[110:113]
	v_mfma_f32_16x16x32_bf16 v[106:109], v[62:65], v[182:185], v[106:109]
	v_mfma_f32_16x16x32_bf16 v[94:97], v[46:49], v[190:193], v[94:97]
	v_mfma_f32_16x16x32_bf16 v[90:93], v[62:65], v[190:193], v[90:93]
	v_mfma_f32_16x16x32_bf16 v[142:145], v[122:125], v[154:157], v[142:145]
	v_mfma_f32_16x16x32_bf16 v[138:141], v[146:149], v[154:157], v[138:141]
	v_mfma_f32_16x16x32_bf16 v[118:121], v[122:125], v[170:173], v[118:121]
	v_mfma_f32_16x16x32_bf16 v[114:117], v[146:149], v[170:173], v[114:117]
	v_mfma_f32_16x16x32_bf16 v[102:105], v[122:125], v[178:181], v[102:105]
	v_mfma_f32_16x16x32_bf16 v[98:101], v[146:149], v[178:181], v[98:101]
	v_mfma_f32_16x16x32_bf16 v[86:89], v[122:125], v[186:189], v[86:89]
	v_mfma_f32_16x16x32_bf16 v[82:85], v[146:149], v[186:189], v[82:85]
	v_mfma_f32_16x16x32_bf16 v[142:145], v[134:137], v[166:169], v[142:145]
	v_mfma_f32_16x16x32_bf16 v[138:141], v[150:153], v[166:169], v[138:141]
	v_mfma_f32_16x16x32_bf16 v[118:121], v[134:137], v[174:177], v[118:121]
	v_mfma_f32_16x16x32_bf16 v[114:117], v[150:153], v[174:177], v[114:117]
	v_mfma_f32_16x16x32_bf16 v[102:105], v[134:137], v[182:185], v[102:105]
	v_mfma_f32_16x16x32_bf16 v[98:101], v[150:153], v[182:185], v[98:101]
	v_mfma_f32_16x16x32_bf16 v[86:89], v[134:137], v[190:193], v[86:89]
	v_mfma_f32_16x16x32_bf16 v[82:85], v[150:153], v[190:193], v[82:85]
	s_barrier
	s_setprio 0
	s_add_i32 s57, s50, s36
	v_lshl_add_u64 v[194:195], s[24:25], 0, v[202:203]
	s_mov_b32 m0, s57
	ds_read_b128 v[154:157], v252 offset:16384
	ds_read_b128 v[166:169], v252 offset:17408
	ds_read_b128 v[170:173], v252 offset:18432
	ds_read_b128 v[174:177], v252 offset:19456
	ds_read_b128 v[178:181], v252 offset:20480
	ds_read_b128 v[182:185], v252 offset:21504
	ds_read_b128 v[186:189], v252 offset:22528
	ds_read_b128 v[190:193], v252 offset:23552
	global_load_lds_dwordx4 v[194:195], off
	s_add_i32 m0, s57, 0x2000
	s_add_u32 s58, s24, 0x80000
	v_lshl_add_u64 v[196:197], s[24:25], 0, v[204:205]
	s_addc_u32 s59, s25, 0
	s_add_i32 s57, s51, s36
	global_load_lds_dwordx4 v[196:197], off
	v_lshl_add_u64 v[198:199], s[58:59], 0, v[202:203]
	s_mov_b32 m0, s57
	v_lshl_add_u64 v[200:201], s[26:27], 0, v[204:205]
	global_load_lds_dwordx4 v[198:199], off
	v_lshl_add_u64 v[198:199], s[58:59], 0, v[204:205]
	s_add_i32 m0, s57, 0x2000
	s_nop 0
	global_load_lds_dwordx4 v[198:199], off
	v_lshl_add_u64 v[198:199], s[26:27], 0, v[202:203]
	s_mov_b32 m0, s37
	s_nop 0
	global_load_lds_dwordx4 v[198:199], off
	s_mov_b32 m0, s38
	s_nop 0
	global_load_lds_dwordx4 v[200:201], off
	s_waitcnt vmcnt(8)
	s_waitcnt lgkmcnt(0)
	s_setprio 1
	s_barrier
; #define PG8_STAGE(bufoff, gbase, VO) do { _Pragma("unroll") for (int _i = 0; _i < 2; ++_i) \
;         __builtin_amdgcn_global_load_lds((const unsigned*)((const char*)(gbase) + VO[_i]), (LAS unsigned*)(lds + (bufoff) + ldsw + _i * 8192), 16, 0, 0); } while (0)
; #define PG8_LDA(dst, b, h) do { _Pragma("unroll") for (int m = 0; m < 4; ++m) _Pragma("unroll") for (int k = 0; k < 2; ++k) dst[m][k] = *(const LAS bf16x8*)(lds + PG8_SA(b, h) + aoff + m * 2048 + k * 1024); } while (0)
; #define PG8_LDB(dst, b, h) do { _Pragma("unroll") for (int n = 0; n < 2; ++n) _Pragma("unroll") for (int k = 0; k < 2; ++k) dst[n][k] = *(const LAS bf16x8*)(lds + PG8_SB(b, h) + boff + n * 2048 + k * 1024); } while (0)
; #define PG8_MMA(ai, bj, At, Bt) do { __builtin_amdgcn_s_setprio(1); _Pragma("unroll") for (int m = 0; m < 4; ++m) _Pragma("unroll") for (int n = 0; n < 2; ++n) _Pragma("unroll") for (int k = 0; k < 2; ++k) \
;         acc[ai][bj][m][n] = __builtin_amdgcn_mfma_f32_16x16x32_bf16(Bt[n][k], At[m][k], acc[ai][bj][m][n], 0, 0, 0); __builtin_amdgcn_s_setprio(0); } while (0)
; #define PG8_WAIT_V(n) asm volatile("s_waitcnt vmcnt(" #n ")" ::: "memory")
; #define PG8_WAIT_L(n) asm volatile("s_waitcnt lgkmcnt(" #n ")" ::: "memory")
; #define PG8_BAR __builtin_amdgcn_s_barrier()
; #define PG8_SCHED __builtin_amdgcn_sched_barrier(0)
; template <int NSEG, class Epi, bool ALIGN_EPI = PG8_ALIGN, bool SP2 = PG8_SP2>
; DI void gemm_phase(LAS unsigned char* lds, const Gemm g, const StaticOrder& S, const Epi& E) {
;     ...
;             PG8_WAIT_V(8); PG8_WAIT_L(0); PG8_BAR; PG8_MMA(1, 0, At, B0); PG8_MMA(1, 1, At, B1); PG8_BAR; PG8_SCHED;
;             PG8_LDB(B0, 1, 0); PG8_LDB(B1, 1, 1); PG8_SCHED; PG8_LDA(At, 1, 0); PG8_STAGE(PG8_SA(0, 1), a2 + h2, v2);
;             PG8_WAIT_V(8); PG8_WAIT_L(0); PG8_BAR; PG8_MMA(0, 0, At, B0); PG8_MMA(0, 1, At, B1); PG8_BAR; PG8_SCHED;
	v_mfma_f32_16x16x32_bf16 v[78:81], v[42:45], v[154:157], v[78:81]
	v_mfma_f32_16x16x32_bf16 v[74:77], v[58:61], v[154:157], v[74:77]
	v_mfma_f32_16x16x32_bf16 v[54:57], v[42:45], v[170:173], v[54:57]
	v_mfma_f32_16x16x32_bf16 v[50:53], v[58:61], v[170:173], v[50:53]
	v_mfma_f32_16x16x32_bf16 v[30:33], v[42:45], v[178:181], v[30:33]
	v_mfma_f32_16x16x32_bf16 v[26:29], v[58:61], v[178:181], v[26:29]
	v_mfma_f32_16x16x32_bf16 v[14:17], v[42:45], v[186:189], v[14:17]
	v_mfma_f32_16x16x32_bf16 v[10:13], v[58:61], v[186:189], v[10:13]
	v_mfma_f32_16x16x32_bf16 v[78:81], v[46:49], v[166:169], v[78:81]
	v_mfma_f32_16x16x32_bf16 v[74:77], v[62:65], v[166:169], v[74:77]
	v_mfma_f32_16x16x32_bf16 v[54:57], v[46:49], v[174:177], v[54:57]
	v_mfma_f32_16x16x32_bf16 v[50:53], v[62:65], v[174:177], v[50:53]
	v_mfma_f32_16x16x32_bf16 v[30:33], v[46:49], v[182:185], v[30:33]
	v_mfma_f32_16x16x32_bf16 v[26:29], v[62:65], v[182:185], v[26:29]
	v_mfma_f32_16x16x32_bf16 v[14:17], v[46:49], v[190:193], v[14:17]
	v_mfma_f32_16x16x32_bf16 v[10:13], v[62:65], v[190:193], v[10:13]
	v_mfma_f32_16x16x32_bf16 v[38:41], v[122:125], v[170:173], v[38:41]
	v_mfma_f32_16x16x32_bf16 v[34:37], v[146:149], v[170:173], v[34:37]
	v_mfma_f32_16x16x32_bf16 v[22:25], v[122:125], v[178:181], v[22:25]
	v_mfma_f32_16x16x32_bf16 v[18:21], v[146:149], v[178:181], v[18:21]
	v_mfma_f32_16x16x32_bf16 v[6:9], v[122:125], v[186:189], v[6:9]
	v_mfma_f32_16x16x32_bf16 v[2:5], v[146:149], v[186:189], v[2:5]
	v_mfma_f32_16x16x32_bf16 v[42:45], v[122:125], v[154:157], v[70:73]
	v_mfma_f32_16x16x32_bf16 v[46:49], v[146:149], v[154:157], v[66:69]
	v_mfma_f32_16x16x32_bf16 v[38:41], v[134:137], v[174:177], v[38:41]
	v_mfma_f32_16x16x32_bf16 v[34:37], v[150:153], v[174:177], v[34:37]
	v_mfma_f32_16x16x32_bf16 v[22:25], v[134:137], v[182:185], v[22:25]
	v_mfma_f32_16x16x32_bf16 v[18:21], v[150:153], v[182:185], v[18:21]
	v_mfma_f32_16x16x32_bf16 v[6:9], v[134:137], v[190:193], v[6:9]
	v_mfma_f32_16x16x32_bf16 v[2:5], v[150:153], v[190:193], v[2:5]
	v_mfma_f32_16x16x32_bf16 v[42:45], v[134:137], v[166:169], v[42:45]
	v_mfma_f32_16x16x32_bf16 v[46:49], v[150:153], v[166:169], v[46:49]
	s_barrier
	s_setprio 0
	s_add_i32 s57, 0, 0x18000
	s_add_i32 s58, 0, 0x1c000
	v_add_u32_e32 v70, s57, v248
	v_add_u32_e32 v150, s58, v248
	ds_read_b128 v[58:61], v70
	ds_read_b128 v[62:65], v70 offset:1024
	ds_read_b128 v[66:69], v70 offset:2048
	ds_read_b128 v[70:73], v70 offset:3072
	ds_read_b128 v[122:125], v150
	ds_read_b128 v[134:137], v150 offset:1024
	ds_read_b128 v[146:149], v150 offset:2048
	ds_read_b128 v[150:153], v150 offset:3072
	s_add_u32 s26, s26, 0x80000
	s_addc_u32 s27, s27, 0
	s_mov_b32 m0, s39
	v_lshl_add_u64 v[212:213], s[26:27], 0, v[202:203]
	ds_read_b128 v[154:157], v252 offset:32768
	ds_read_b128 v[166:169], v252 offset:33792
	ds_read_b128 v[170:173], v252 offset:34816
	ds_read_b128 v[174:177], v252 offset:35840
	ds_read_b128 v[178:181], v252 offset:36864
	ds_read_b128 v[182:185], v252 offset:37888
	ds_read_b128 v[186:189], v252 offset:38912
	ds_read_b128 v[190:193], v252 offset:39936
	global_load_lds_dwordx4 v[212:213], off
	v_lshl_add_u64 v[212:213], s[26:27], 0, v[204:205]
	s_mov_b32 m0, s40
	s_nop 0
	global_load_lds_dwordx4 v[212:213], off
	s_waitcnt vmcnt(8)
	s_waitcnt lgkmcnt(0)
	s_setprio 1
	s_barrier
	v_mfma_f32_16x16x32_bf16 v[162:165], v[58:61], v[154:157], v[162:165]
	v_mfma_f32_16x16x32_bf16 v[158:161], v[66:69], v[154:157], v[158:161]
	v_mfma_f32_16x16x32_bf16 v[130:133], v[58:61], v[170:173], v[130:133]
	v_mfma_f32_16x16x32_bf16 v[126:129], v[66:69], v[170:173], v[126:129]
	v_mfma_f32_16x16x32_bf16 v[110:113], v[58:61], v[178:181], v[110:113]
	v_mfma_f32_16x16x32_bf16 v[106:109], v[66:69], v[178:181], v[106:109]
	v_mfma_f32_16x16x32_bf16 v[94:97], v[58:61], v[186:189], v[94:97]
	v_mfma_f32_16x16x32_bf16 v[90:93], v[66:69], v[186:189], v[90:93]
	v_mfma_f32_16x16x32_bf16 v[162:165], v[62:65], v[166:169], v[162:165]
	v_mfma_f32_16x16x32_bf16 v[158:161], v[70:73], v[166:169], v[158:161]
	v_mfma_f32_16x16x32_bf16 v[130:133], v[62:65], v[174:177], v[130:133]
	v_mfma_f32_16x16x32_bf16 v[126:129], v[70:73], v[174:177], v[126:129]
	v_mfma_f32_16x16x32_bf16 v[110:113], v[62:65], v[182:185], v[110:113]
	v_mfma_f32_16x16x32_bf16 v[106:109], v[70:73], v[182:185], v[106:109]
	v_mfma_f32_16x16x32_bf16 v[94:97], v[62:65], v[190:193], v[94:97]
	v_mfma_f32_16x16x32_bf16 v[90:93], v[70:73], v[190:193], v[90:93]
	v_mfma_f32_16x16x32_bf16 v[142:145], v[122:125], v[154:157], v[142:145]
	v_mfma_f32_16x16x32_bf16 v[138:141], v[146:149], v[154:157], v[138:141]
	v_mfma_f32_16x16x32_bf16 v[118:121], v[122:125], v[170:173], v[118:121]
	v_mfma_f32_16x16x32_bf16 v[114:117], v[146:149], v[170:173], v[114:117]
	v_mfma_f32_16x16x32_bf16 v[102:105], v[122:125], v[178:181], v[102:105]
	v_mfma_f32_16x16x32_bf16 v[98:101], v[146:149], v[178:181], v[98:101]
	v_mfma_f32_16x16x32_bf16 v[86:89], v[122:125], v[186:189], v[86:89]
	v_mfma_f32_16x16x32_bf16 v[82:85], v[146:149], v[186:189], v[82:85]
	v_mfma_f32_16x16x32_bf16 v[142:145], v[134:137], v[166:169], v[142:145]
	v_mfma_f32_16x16x32_bf16 v[138:141], v[150:153], v[166:169], v[138:141]
	v_mfma_f32_16x16x32_bf16 v[118:121], v[134:137], v[174:177], v[118:121]
	v_mfma_f32_16x16x32_bf16 v[114:117], v[150:153], v[174:177], v[114:117]
	v_mfma_f32_16x16x32_bf16 v[102:105], v[134:137], v[182:185], v[102:105]
	v_mfma_f32_16x16x32_bf16 v[98:101], v[150:153], v[182:185], v[98:101]
	v_mfma_f32_16x16x32_bf16 v[86:89], v[134:137], v[190:193], v[86:89]
	v_mfma_f32_16x16x32_bf16 v[82:85], v[150:153], v[190:193], v[82:85]
	s_barrier
; #define PG8_STAGE(bufoff, gbase, VO) do { _Pragma("unroll") for (int _i = 0; _i < 2; ++_i) \
;         __builtin_amdgcn_global_load_lds((const unsigned*)((const char*)(gbase) + VO[_i]), (LAS unsigned*)(lds + (bufoff) + ldsw + _i * 8192), 16, 0, 0); } while (0)
; #define PG8_LDA(dst, b, h) do { _Pragma("unroll") for (int m = 0; m < 4; ++m) _Pragma("unroll") for (int k = 0; k < 2; ++k) dst[m][k] = *(const LAS bf16x8*)(lds + PG8_SA(b, h) + aoff + m * 2048 + k * 1024); } while (0)
; #define PG8_MMA(ai, bj, At, Bt) do { __builtin_amdgcn_s_setprio(1); _Pragma("unroll") for (int m = 0; m < 4; ++m) _Pragma("unroll") for (int n = 0; n < 2; ++n) _Pragma("unroll") for (int k = 0; k < 2; ++k) \
;         acc[ai][bj][m][n] = __builtin_amdgcn_mfma_f32_16x16x32_bf16(Bt[n][k], At[m][k], acc[ai][bj][m][n], 0, 0, 0); __builtin_amdgcn_s_setprio(0); } while (0)
; #define PG8_WAIT_V(n) asm volatile("s_waitcnt vmcnt(" #n ")" ::: "memory")
; #define PG8_WAIT_L(n) asm volatile("s_waitcnt lgkmcnt(" #n ")" ::: "memory")
; #define PG8_BAR __builtin_amdgcn_s_barrier()
; #define PG8_SCHED __builtin_amdgcn_sched_barrier(0)
; template <int NSEG, class Epi, bool ALIGN_EPI = PG8_ALIGN, bool SP2 = PG8_SP2>
; DI void gemm_phase(LAS unsigned char* lds, const Gemm g, const StaticOrder& S, const Epi& E) {
;     ...
;             PG8_LDA(At, 1, 1); PG8_STAGE(PG8_SB(1, 0), b3, v2); PG8_STAGE(PG8_SB(1, 1), b3 + h2, v2); PG8_STAGE(PG8_SA(1, 0), a3, v2);
;             PG8_WAIT_V(8); PG8_WAIT_L(0); PG8_BAR; PG8_MMA(1, 0, At, B0); PG8_MMA(1, 1, At, B1); PG8_BAR; PG8_SCHED;
	s_setprio 0
	s_add_i32 s26, s57, s36
	v_lshl_add_u64 v[194:195], v[194:195], 0, s[10:11]
	s_mov_b32 m0, s26
	ds_read_b128 v[154:157], v252 offset:49152
	ds_read_b128 v[166:169], v252 offset:50176
	ds_read_b128 v[170:173], v252 offset:51200
	ds_read_b128 v[174:177], v252 offset:52224
	ds_read_b128 v[178:181], v252 offset:53248
	ds_read_b128 v[182:185], v252 offset:54272
	ds_read_b128 v[186:189], v252 offset:55296
	ds_read_b128 v[190:193], v252 offset:56320
	global_load_lds_dwordx4 v[194:195], off
	s_add_i32 m0, s26, 0x2000
	s_add_u32 s24, s24, 0x80080
	v_lshl_add_u64 v[194:195], v[196:197], 0, s[10:11]
	s_addc_u32 s25, s25, 0
	s_add_i32 s26, s58, s36
	global_load_lds_dwordx4 v[194:195], off
	v_lshl_add_u64 v[194:195], s[24:25], 0, v[202:203]
	s_mov_b32 m0, s26
	s_nop 0
	global_load_lds_dwordx4 v[194:195], off
	v_lshl_add_u64 v[194:195], s[24:25], 0, v[204:205]
	s_add_i32 m0, s26, 0x2000
	s_nop 0
	global_load_lds_dwordx4 v[194:195], off
	v_lshl_add_u64 v[194:195], v[198:199], 0, s[10:11]
	s_mov_b32 m0, s48
	s_nop 0
	global_load_lds_dwordx4 v[194:195], off
	v_lshl_add_u64 v[194:195], v[200:201], 0, s[10:11]
	s_mov_b32 m0, s49
	s_nop 0
	global_load_lds_dwordx4 v[194:195], off
	s_waitcnt vmcnt(8)
	s_waitcnt lgkmcnt(0)
	s_setprio 1
	s_barrier
	v_mfma_f32_16x16x32_bf16 v[78:81], v[58:61], v[154:157], v[78:81]
	v_mfma_f32_16x16x32_bf16 v[74:77], v[66:69], v[154:157], v[74:77]
	v_mfma_f32_16x16x32_bf16 v[54:57], v[58:61], v[170:173], v[54:57]
	v_mfma_f32_16x16x32_bf16 v[50:53], v[66:69], v[170:173], v[50:53]
	v_mfma_f32_16x16x32_bf16 v[30:33], v[58:61], v[178:181], v[30:33]
	v_mfma_f32_16x16x32_bf16 v[26:29], v[66:69], v[178:181], v[26:29]
	v_mfma_f32_16x16x32_bf16 v[14:17], v[58:61], v[186:189], v[14:17]
	v_mfma_f32_16x16x32_bf16 v[10:13], v[66:69], v[186:189], v[10:13]
	v_mfma_f32_16x16x32_bf16 v[78:81], v[62:65], v[166:169], v[78:81]
	v_mfma_f32_16x16x32_bf16 v[74:77], v[70:73], v[166:169], v[74:77]
	v_mfma_f32_16x16x32_bf16 v[54:57], v[62:65], v[174:177], v[54:57]
	v_mfma_f32_16x16x32_bf16 v[50:53], v[70:73], v[174:177], v[50:53]
	v_mfma_f32_16x16x32_bf16 v[30:33], v[62:65], v[182:185], v[30:33]
	v_mfma_f32_16x16x32_bf16 v[26:29], v[70:73], v[182:185], v[26:29]
	v_mfma_f32_16x16x32_bf16 v[14:17], v[62:65], v[190:193], v[14:17]
	v_mfma_f32_16x16x32_bf16 v[10:13], v[70:73], v[190:193], v[10:13]
	v_mfma_f32_16x16x32_bf16 v[42:45], v[122:125], v[154:157], v[42:45]
	v_mfma_f32_16x16x32_bf16 v[70:73], v[134:137], v[166:169], v[42:45]
	v_mfma_f32_16x16x32_bf16 v[42:45], v[146:149], v[154:157], v[46:49]
	v_mfma_f32_16x16x32_bf16 v[38:41], v[122:125], v[170:173], v[38:41]
	v_mfma_f32_16x16x32_bf16 v[34:37], v[146:149], v[170:173], v[34:37]
	v_mfma_f32_16x16x32_bf16 v[22:25], v[122:125], v[178:181], v[22:25]
	v_mfma_f32_16x16x32_bf16 v[18:21], v[146:149], v[178:181], v[18:21]
	v_mfma_f32_16x16x32_bf16 v[6:9], v[122:125], v[186:189], v[6:9]
	v_mfma_f32_16x16x32_bf16 v[2:5], v[146:149], v[186:189], v[2:5]
	v_mfma_f32_16x16x32_bf16 v[66:69], v[150:153], v[166:169], v[42:45]
	v_mfma_f32_16x16x32_bf16 v[38:41], v[134:137], v[174:177], v[38:41]
	v_mfma_f32_16x16x32_bf16 v[34:37], v[150:153], v[174:177], v[34:37]
	v_mfma_f32_16x16x32_bf16 v[22:25], v[134:137], v[182:185], v[22:25]
	v_mfma_f32_16x16x32_bf16 v[18:21], v[150:153], v[182:185], v[18:21]
	v_mfma_f32_16x16x32_bf16 v[6:9], v[134:137], v[190:193], v[6:9]
	v_mfma_f32_16x16x32_bf16 v[2:5], v[150:153], v[190:193], v[2:5]
	s_barrier
	s_setprio 0
	s_add_i32 s56, s56, 2
	s_add_u32 s22, s22, 0x100
	s_addc_u32 s23, s23, 0
	s_add_u32 s54, s54, 0x100
	s_addc_u32 s55, s55, 0
	s_cmp_gt_u32 s56, 29
	s_cbranch_scc0 .LBB0_281
	s_and_b64 vcc, exec, s[12:13]
	s_cbranch_vccz .LBB0_284
	s_barrier

; #define PG8_STAGE(bufoff, gbase, VO) do { _Pragma("unroll") for (int _i = 0; _i < 2; ++_i) \
;         __builtin_amdgcn_global_load_lds((const unsigned*)((const char*)(gbase) + VO[_i]), (LAS unsigned*)(lds + (bufoff) + ldsw + _i * 8192), 16, 0, 0); } while (0)
; #define PG8_LDA(dst, b, h) do { _Pragma("unroll") for (int m = 0; m < 4; ++m) _Pragma("unroll") for (int k = 0; k < 2; ++k) dst[m][k] = *(const LAS bf16x8*)(lds + PG8_SA(b, h) + aoff + m * 2048 + k * 1024); } while (0)
; #define PG8_LDB(dst, b, h) do { _Pragma("unroll") for (int n = 0; n < 2; ++n) _Pragma("unroll") for (int k = 0; k < 2; ++k) dst[n][k] = *(const LAS bf16x8*)(lds + PG8_SB(b, h) + boff + n * 2048 + k * 1024); } while (0)
; #define PG8_MMA(ai, bj, At, Bt) do { __builtin_amdgcn_s_setprio(1); _Pragma("unroll") for (int m = 0; m < 4; ++m) _Pragma("unroll") for (int n = 0; n < 2; ++n) _Pragma("unroll") for (int k = 0; k < 2; ++k) \
;         acc[ai][bj][m][n] = __builtin_amdgcn_mfma_f32_16x16x32_bf16(Bt[n][k], At[m][k], acc[ai][bj][m][n], 0, 0, 0); __builtin_amdgcn_s_setprio(0); } while (0)
; #define PG8_WAIT_V(n) asm volatile("s_waitcnt vmcnt(" #n ")" ::: "memory")
; #define PG8_WAIT_L(n) asm volatile("s_waitcnt lgkmcnt(" #n ")" ::: "memory")
; #define PG8_BAR __builtin_amdgcn_s_barrier()
; #define PG8_SCHED __builtin_amdgcn_sched_barrier(0)
; template <int NSEG, class Epi, bool ALIGN_EPI = PG8_ALIGN, bool SP2 = PG8_SP2>
; DI void gemm_phase(LAS unsigned char* lds, const Gemm g, const StaticOrder& S, const Epi& E) {
;     ...
;             PG8_LDB(B0, 0, 0); PG8_LDB(B1, 0, 1); PG8_SCHED; PG8_LDA(At, 0, 0); PG8_STAGE(PG8_SA(1, 1), a1 + hstepC, voffC);
;             PG8_WAIT_V(8); PG8_WAIT_L(0); PG8_BAR; PG8_MMA(0, 0, At, B0); PG8_MMA(0, 1, At, B1); PG8_BAR; PG8_SCHED;
;             PG8_LDA(At, 0, 1); PG8_STAGE(PG8_SB(0, 0), b2, v2); PG8_STAGE(PG8_SB(0, 1), b2 + h2, v2); PG8_STAGE(PG8_SA(0, 0), a2, v2);
.LBB0_305:
	ds_read_b128 v[130:133], v161
	ds_read_b128 v[134:137], v161 offset:1024
	ds_read_b128 v[150:153], v161 offset:2048
	ds_read_b128 v[154:157], v161 offset:3072
	ds_read_b128 v[164:167], v162
	ds_read_b128 v[168:171], v162 offset:1024
	ds_read_b128 v[172:175], v162 offset:2048
	ds_read_b128 v[176:179], v162 offset:3072
	s_add_u32 s38, s36, 0xfff80080
	s_addc_u32 s39, s37, -1
	s_cmp_eq_u32 s66, 28
	s_cselect_b32 s41, s21, s39
	s_cselect_b32 s40, s23, s38
	s_cselect_b32 s39, s62, s65
	s_cselect_b32 s38, s63, s64
	v_lshl_add_u64 v[212:213], s[36:37], 0, v[142:143]
	s_add_i32 m0, s35, 0xc000
	ds_read_b128 v[180:183], v163
	ds_read_b128 v[184:187], v163 offset:1024
	ds_read_b128 v[188:191], v163 offset:2048
	ds_read_b128 v[192:195], v163 offset:3072
	ds_read_b128 v[196:199], v163 offset:4096
	ds_read_b128 v[200:203], v163 offset:5120
	ds_read_b128 v[204:207], v163 offset:6144
	ds_read_b128 v[208:211], v163 offset:7168
	global_load_lds_dwordx4 v[212:213], off
	v_lshl_add_u64 v[212:213], s[36:37], 0, v[144:145]
	s_add_i32 m0, s35, 0xe000
	s_nop 0
	global_load_lds_dwordx4 v[212:213], off
	s_waitcnt vmcnt(8)
	s_waitcnt lgkmcnt(0)
	s_setprio 1
	s_barrier
	v_mfma_f32_16x16x32_bf16 v[126:129], v[130:133], v[180:183], v[126:129]
	v_mfma_f32_16x16x32_bf16 v[122:125], v[150:153], v[180:183], v[122:125]
	v_mfma_f32_16x16x32_bf16 v[118:121], v[130:133], v[188:191], v[118:121]
	v_mfma_f32_16x16x32_bf16 v[114:117], v[150:153], v[188:191], v[114:117]
	v_mfma_f32_16x16x32_bf16 v[110:113], v[130:133], v[196:199], v[110:113]
	v_mfma_f32_16x16x32_bf16 v[106:109], v[150:153], v[196:199], v[106:109]
	v_mfma_f32_16x16x32_bf16 v[102:105], v[130:133], v[204:207], v[102:105]
	v_mfma_f32_16x16x32_bf16 v[98:101], v[150:153], v[204:207], v[98:101]
	v_mfma_f32_16x16x32_bf16 v[126:129], v[134:137], v[184:187], v[126:129]
	v_mfma_f32_16x16x32_bf16 v[122:125], v[154:157], v[184:187], v[122:125]
	v_mfma_f32_16x16x32_bf16 v[118:121], v[134:137], v[192:195], v[118:121]
	v_mfma_f32_16x16x32_bf16 v[114:117], v[154:157], v[192:195], v[114:117]
	v_mfma_f32_16x16x32_bf16 v[110:113], v[134:137], v[200:203], v[110:113]
	v_mfma_f32_16x16x32_bf16 v[106:109], v[154:157], v[200:203], v[106:109]
	v_mfma_f32_16x16x32_bf16 v[102:105], v[134:137], v[208:211], v[102:105]
	v_mfma_f32_16x16x32_bf16 v[98:101], v[154:157], v[208:211], v[98:101]
	v_mfma_f32_16x16x32_bf16 v[62:65], v[164:167], v[180:183], v[62:65]
	v_mfma_f32_16x16x32_bf16 v[58:61], v[172:175], v[180:183], v[58:61]
	v_mfma_f32_16x16x32_bf16 v[54:57], v[164:167], v[188:191], v[54:57]
	v_mfma_f32_16x16x32_bf16 v[50:53], v[172:175], v[188:191], v[50:53]
	v_mfma_f32_16x16x32_bf16 v[46:49], v[164:167], v[196:199], v[46:49]
	v_mfma_f32_16x16x32_bf16 v[42:45], v[172:175], v[196:199], v[42:45]
	v_mfma_f32_16x16x32_bf16 v[38:41], v[164:167], v[204:207], v[38:41]
	v_mfma_f32_16x16x32_bf16 v[34:37], v[172:175], v[204:207], v[34:37]
	v_mfma_f32_16x16x32_bf16 v[62:65], v[168:171], v[184:187], v[62:65]
	v_mfma_f32_16x16x32_bf16 v[58:61], v[176:179], v[184:187], v[58:61]
	v_mfma_f32_16x16x32_bf16 v[54:57], v[168:171], v[192:195], v[54:57]
	v_mfma_f32_16x16x32_bf16 v[50:53], v[176:179], v[192:195], v[50:53]
	v_mfma_f32_16x16x32_bf16 v[46:49], v[168:171], v[200:203], v[46:49]
	v_mfma_f32_16x16x32_bf16 v[42:45], v[176:179], v[200:203], v[42:45]
	v_mfma_f32_16x16x32_bf16 v[38:41], v[168:171], v[208:211], v[38:41]
	v_mfma_f32_16x16x32_bf16 v[34:37], v[176:179], v[208:211], v[34:37]
	s_barrier
	s_setprio 0
	s_add_i32 s67, s55, s48
	v_lshl_add_u64 v[212:213], s[38:39], 0, v[138:139]
	s_mov_b32 m0, s67
	ds_read_b128 v[180:183], v163 offset:16384
	ds_read_b128 v[184:187], v163 offset:17408
	ds_read_b128 v[188:191], v163 offset:18432
	ds_read_b128 v[192:195], v163 offset:19456
	ds_read_b128 v[196:199], v163 offset:20480
	ds_read_b128 v[200:203], v163 offset:21504
	ds_read_b128 v[204:207], v163 offset:22528
	ds_read_b128 v[208:211], v163 offset:23552
	global_load_lds_dwordx4 v[212:213], off
	s_add_i32 m0, s67, 0x2000
	s_add_u32 s68, s38, 0x80000
	v_lshl_add_u64 v[214:215], s[38:39], 0, v[140:141]
	s_addc_u32 s69, s39, 0
	s_add_i32 s67, s56, s48
	global_load_lds_dwordx4 v[214:215], off
	v_lshl_add_u64 v[216:217], s[68:69], 0, v[138:139]
	s_mov_b32 m0, s67
	v_lshl_add_u64 v[218:219], s[40:41], 0, v[140:141]
	global_load_lds_dwordx4 v[216:217], off
	v_lshl_add_u64 v[216:217], s[68:69], 0, v[140:141]
	s_add_i32 m0, s67, 0x2000
	s_nop 0
	global_load_lds_dwordx4 v[216:217], off
	v_lshl_add_u64 v[216:217], s[40:41], 0, v[138:139]
	s_mov_b32 m0, s35
	s_nop 0
	global_load_lds_dwordx4 v[216:217], off
	s_mov_b32 m0, s49
	s_nop 0
	global_load_lds_dwordx4 v[218:219], off
	s_waitcnt vmcnt(8)
	s_waitcnt lgkmcnt(0)
	s_setprio 1
	s_barrier
; #define PG8_STAGE(bufoff, gbase, VO) do { _Pragma("unroll") for (int _i = 0; _i < 2; ++_i) \
;         __builtin_amdgcn_global_load_lds((const unsigned*)((const char*)(gbase) + VO[_i]), (LAS unsigned*)(lds + (bufoff) + ldsw + _i * 8192), 16, 0, 0); } while (0)
; #define PG8_LDA(dst, b, h) do { _Pragma("unroll") for (int m = 0; m < 4; ++m) _Pragma("unroll") for (int k = 0; k < 2; ++k) dst[m][k] = *(const LAS bf16x8*)(lds + PG8_SA(b, h) + aoff + m * 2048 + k * 1024); } while (0)
; #define PG8_LDB(dst, b, h) do { _Pragma("unroll") for (int n = 0; n < 2; ++n) _Pragma("unroll") for (int k = 0; k < 2; ++k) dst[n][k] = *(const LAS bf16x8*)(lds + PG8_SB(b, h) + boff + n * 2048 + k * 1024); } while (0)
; #define PG8_MMA(ai, bj, At, Bt) do { __builtin_amdgcn_s_setprio(1); _Pragma("unroll") for (int m = 0; m < 4; ++m) _Pragma("unroll") for (int n = 0; n < 2; ++n) _Pragma("unroll") for (int k = 0; k < 2; ++k) \
;         acc[ai][bj][m][n] = __builtin_amdgcn_mfma_f32_16x16x32_bf16(Bt[n][k], At[m][k], acc[ai][bj][m][n], 0, 0, 0); __builtin_amdgcn_s_setprio(0); } while (0)
; #define PG8_WAIT_V(n) asm volatile("s_waitcnt vmcnt(" #n ")" ::: "memory")
; #define PG8_WAIT_L(n) asm volatile("s_waitcnt lgkmcnt(" #n ")" ::: "memory")
; #define PG8_BAR __builtin_amdgcn_s_barrier()
; #define PG8_SCHED __builtin_amdgcn_sched_barrier(0)
; template <int NSEG, class Epi, bool ALIGN_EPI = PG8_ALIGN, bool SP2 = PG8_SP2>
; DI void gemm_phase(LAS unsigned char* lds, const Gemm g, const StaticOrder& S, const Epi& E) {
;     ...
;             PG8_WAIT_V(8); PG8_WAIT_L(0); PG8_BAR; PG8_MMA(1, 0, At, B0); PG8_MMA(1, 1, At, B1); PG8_BAR; PG8_SCHED;
;             PG8_LDB(B0, 1, 0); PG8_LDB(B1, 1, 1); PG8_SCHED; PG8_LDA(At, 1, 0); PG8_STAGE(PG8_SA(0, 1), a2 + h2, v2);
;             PG8_WAIT_V(8); PG8_WAIT_L(0); PG8_BAR; PG8_MMA(0, 0, At, B0); PG8_MMA(0, 1, At, B1); PG8_BAR; PG8_SCHED;
	v_mfma_f32_16x16x32_bf16 v[94:97], v[130:133], v[180:183], v[94:97]
	v_mfma_f32_16x16x32_bf16 v[90:93], v[150:153], v[180:183], v[90:93]
	v_mfma_f32_16x16x32_bf16 v[86:89], v[130:133], v[188:191], v[86:89]
	v_mfma_f32_16x16x32_bf16 v[82:85], v[150:153], v[188:191], v[82:85]
	v_mfma_f32_16x16x32_bf16 v[78:81], v[130:133], v[196:199], v[78:81]
	v_mfma_f32_16x16x32_bf16 v[74:77], v[150:153], v[196:199], v[74:77]
	v_mfma_f32_16x16x32_bf16 v[70:73], v[130:133], v[204:207], v[70:73]
	v_mfma_f32_16x16x32_bf16 v[66:69], v[150:153], v[204:207], v[66:69]
	v_mfma_f32_16x16x32_bf16 v[94:97], v[134:137], v[184:187], v[94:97]
	v_mfma_f32_16x16x32_bf16 v[90:93], v[154:157], v[184:187], v[90:93]
	v_mfma_f32_16x16x32_bf16 v[86:89], v[134:137], v[192:195], v[86:89]
	v_mfma_f32_16x16x32_bf16 v[82:85], v[154:157], v[192:195], v[82:85]
	v_mfma_f32_16x16x32_bf16 v[78:81], v[134:137], v[200:203], v[78:81]
	v_mfma_f32_16x16x32_bf16 v[74:77], v[154:157], v[200:203], v[74:77]
	v_mfma_f32_16x16x32_bf16 v[70:73], v[134:137], v[208:211], v[70:73]
	v_mfma_f32_16x16x32_bf16 v[66:69], v[154:157], v[208:211], v[66:69]
	v_mfma_f32_16x16x32_bf16 v[30:33], v[164:167], v[180:183], v[30:33]
	v_mfma_f32_16x16x32_bf16 v[26:29], v[172:175], v[180:183], v[26:29]
	v_mfma_f32_16x16x32_bf16 v[14:17], v[164:167], v[188:191], v[14:17]
	v_mfma_f32_16x16x32_bf16 v[2:5], v[172:175], v[188:191], v[2:5]
	v_mfma_f32_16x16x32_bf16 v[22:25], v[164:167], v[196:199], v[22:25]
	v_mfma_f32_16x16x32_bf16 v[18:21], v[172:175], v[196:199], v[18:21]
	v_mfma_f32_16x16x32_bf16 v[10:13], v[164:167], v[204:207], v[10:13]
	v_mfma_f32_16x16x32_bf16 v[6:9], v[172:175], v[204:207], v[6:9]
	v_mfma_f32_16x16x32_bf16 v[30:33], v[168:171], v[184:187], v[30:33]
	v_mfma_f32_16x16x32_bf16 v[26:29], v[176:179], v[184:187], v[26:29]
	v_mfma_f32_16x16x32_bf16 v[14:17], v[168:171], v[192:195], v[14:17]
	v_mfma_f32_16x16x32_bf16 v[2:5], v[176:179], v[192:195], v[2:5]
	v_mfma_f32_16x16x32_bf16 v[22:25], v[168:171], v[200:203], v[22:25]
	v_mfma_f32_16x16x32_bf16 v[18:21], v[176:179], v[200:203], v[18:21]
	v_mfma_f32_16x16x32_bf16 v[10:13], v[168:171], v[208:211], v[10:13]
	v_mfma_f32_16x16x32_bf16 v[6:9], v[176:179], v[208:211], v[6:9]
	s_barrier
	s_setprio 0
	s_add_i32 s67, 0, 0x18000
	s_add_i32 s68, 0, 0x1c000
	v_add_u32_e32 v154, s67, v159
	v_add_u32_e32 v176, s68, v159
	ds_read_b128 v[130:133], v154
	ds_read_b128 v[134:137], v154 offset:1024
	ds_read_b128 v[150:153], v154 offset:2048
	ds_read_b128 v[154:157], v154 offset:3072
	ds_read_b128 v[164:167], v176
	ds_read_b128 v[168:171], v176 offset:1024
	ds_read_b128 v[172:175], v176 offset:2048
	ds_read_b128 v[176:179], v176 offset:3072
	s_add_u32 s40, s40, 0x80000
	s_addc_u32 s41, s41, 0
	s_mov_b32 m0, s50
	v_lshl_add_u64 v[220:221], s[40:41], 0, v[138:139]
	ds_read_b128 v[180:183], v163 offset:32768
	ds_read_b128 v[184:187], v163 offset:33792
	ds_read_b128 v[188:191], v163 offset:34816
	ds_read_b128 v[192:195], v163 offset:35840
	ds_read_b128 v[196:199], v163 offset:36864
	ds_read_b128 v[200:203], v163 offset:37888
	ds_read_b128 v[204:207], v163 offset:38912
	ds_read_b128 v[208:211], v163 offset:39936
	global_load_lds_dwordx4 v[220:221], off
	v_lshl_add_u64 v[220:221], s[40:41], 0, v[140:141]
	s_mov_b32 m0, s51
	s_nop 0
	global_load_lds_dwordx4 v[220:221], off
	s_waitcnt vmcnt(8)
	s_waitcnt lgkmcnt(0)
	s_setprio 1
	s_barrier
	v_mfma_f32_16x16x32_bf16 v[126:129], v[130:133], v[180:183], v[126:129]
	v_mfma_f32_16x16x32_bf16 v[122:125], v[150:153], v[180:183], v[122:125]
	v_mfma_f32_16x16x32_bf16 v[118:121], v[130:133], v[188:191], v[118:121]
	v_mfma_f32_16x16x32_bf16 v[114:117], v[150:153], v[188:191], v[114:117]
	v_mfma_f32_16x16x32_bf16 v[110:113], v[130:133], v[196:199], v[110:113]
	v_mfma_f32_16x16x32_bf16 v[106:109], v[150:153], v[196:199], v[106:109]
	v_mfma_f32_16x16x32_bf16 v[102:105], v[130:133], v[204:207], v[102:105]
	v_mfma_f32_16x16x32_bf16 v[98:101], v[150:153], v[204:207], v[98:101]
	v_mfma_f32_16x16x32_bf16 v[126:129], v[134:137], v[184:187], v[126:129]
	v_mfma_f32_16x16x32_bf16 v[122:125], v[154:157], v[184:187], v[122:125]
	v_mfma_f32_16x16x32_bf16 v[118:121], v[134:137], v[192:195], v[118:121]
	v_mfma_f32_16x16x32_bf16 v[114:117], v[154:157], v[192:195], v[114:117]
	v_mfma_f32_16x16x32_bf16 v[110:113], v[134:137], v[200:203], v[110:113]
	v_mfma_f32_16x16x32_bf16 v[106:109], v[154:157], v[200:203], v[106:109]
	v_mfma_f32_16x16x32_bf16 v[102:105], v[134:137], v[208:211], v[102:105]
	v_mfma_f32_16x16x32_bf16 v[98:101], v[154:157], v[208:211], v[98:101]
	v_mfma_f32_16x16x32_bf16 v[62:65], v[164:167], v[180:183], v[62:65]
	v_mfma_f32_16x16x32_bf16 v[58:61], v[172:175], v[180:183], v[58:61]
	v_mfma_f32_16x16x32_bf16 v[54:57], v[164:167], v[188:191], v[54:57]
	v_mfma_f32_16x16x32_bf16 v[50:53], v[172:175], v[188:191], v[50:53]
	v_mfma_f32_16x16x32_bf16 v[46:49], v[164:167], v[196:199], v[46:49]
	v_mfma_f32_16x16x32_bf16 v[42:45], v[172:175], v[196:199], v[42:45]
	v_mfma_f32_16x16x32_bf16 v[38:41], v[164:167], v[204:207], v[38:41]
	v_mfma_f32_16x16x32_bf16 v[34:37], v[172:175], v[204:207], v[34:37]
	v_mfma_f32_16x16x32_bf16 v[62:65], v[168:171], v[184:187], v[62:65]
	v_mfma_f32_16x16x32_bf16 v[58:61], v[176:179], v[184:187], v[58:61]
	v_mfma_f32_16x16x32_bf16 v[54:57], v[168:171], v[192:195], v[54:57]
	v_mfma_f32_16x16x32_bf16 v[50:53], v[176:179], v[192:195], v[50:53]
	v_mfma_f32_16x16x32_bf16 v[46:49], v[168:171], v[200:203], v[46:49]
	v_mfma_f32_16x16x32_bf16 v[42:45], v[176:179], v[200:203], v[42:45]
	v_mfma_f32_16x16x32_bf16 v[38:41], v[168:171], v[208:211], v[38:41]
	v_mfma_f32_16x16x32_bf16 v[34:37], v[176:179], v[208:211], v[34:37]
	s_barrier
; #define PG8_STAGE(bufoff, gbase, VO) do { _Pragma("unroll") for (int _i = 0; _i < 2; ++_i) \
;         __builtin_amdgcn_global_load_lds((const unsigned*)((const char*)(gbase) + VO[_i]), (LAS unsigned*)(lds + (bufoff) + ldsw + _i * 8192), 16, 0, 0); } while (0)
; #define PG8_LDA(dst, b, h) do { _Pragma("unroll") for (int m = 0; m < 4; ++m) _Pragma("unroll") for (int k = 0; k < 2; ++k) dst[m][k] = *(const LAS bf16x8*)(lds + PG8_SA(b, h) + aoff + m * 2048 + k * 1024); } while (0)
; #define PG8_MMA(ai, bj, At, Bt) do { __builtin_amdgcn_s_setprio(1); _Pragma("unroll") for (int m = 0; m < 4; ++m) _Pragma("unroll") for (int n = 0; n < 2; ++n) _Pragma("unroll") for (int k = 0; k < 2; ++k) \
;         acc[ai][bj][m][n] = __builtin_amdgcn_mfma_f32_16x16x32_bf16(Bt[n][k], At[m][k], acc[ai][bj][m][n], 0, 0, 0); __builtin_amdgcn_s_setprio(0); } while (0)
; #define PG8_WAIT_V(n) asm volatile("s_waitcnt vmcnt(" #n ")" ::: "memory")
; #define PG8_WAIT_L(n) asm volatile("s_waitcnt lgkmcnt(" #n ")" ::: "memory")
; #define PG8_BAR __builtin_amdgcn_s_barrier()
; #define PG8_SCHED __builtin_amdgcn_sched_barrier(0)
; template <int NSEG, class Epi, bool ALIGN_EPI = PG8_ALIGN, bool SP2 = PG8_SP2>
; DI void gemm_phase(LAS unsigned char* lds, const Gemm g, const StaticOrder& S, const Epi& E) {
;     ...
;             PG8_LDA(At, 1, 1); PG8_STAGE(PG8_SB(1, 0), b3, v2); PG8_STAGE(PG8_SB(1, 1), b3 + h2, v2); PG8_STAGE(PG8_SA(1, 0), a3, v2);
;             PG8_WAIT_V(8); PG8_WAIT_L(0); PG8_BAR; PG8_MMA(1, 0, At, B0); PG8_MMA(1, 1, At, B1); PG8_BAR; PG8_SCHED;
	s_setprio 0
	s_add_i32 s40, s67, s48
	v_lshl_add_u64 v[212:213], v[212:213], 0, s[8:9]
	s_mov_b32 m0, s40
	ds_read_b128 v[180:183], v163 offset:49152
	ds_read_b128 v[184:187], v163 offset:50176
	ds_read_b128 v[188:191], v163 offset:51200
	ds_read_b128 v[192:195], v163 offset:52224
	ds_read_b128 v[196:199], v163 offset:53248
	ds_read_b128 v[200:203], v163 offset:54272
	ds_read_b128 v[204:207], v163 offset:55296
	ds_read_b128 v[208:211], v163 offset:56320
	global_load_lds_dwordx4 v[212:213], off
	s_add_i32 m0, s40, 0x2000
	s_add_u32 s38, s38, 0x80080
	v_lshl_add_u64 v[212:213], v[214:215], 0, s[8:9]
	s_addc_u32 s39, s39, 0
	s_add_i32 s40, s68, s48
	global_load_lds_dwordx4 v[212:213], off
	v_lshl_add_u64 v[212:213], s[38:39], 0, v[138:139]
	s_mov_b32 m0, s40
	s_nop 0
	global_load_lds_dwordx4 v[212:213], off
	v_lshl_add_u64 v[212:213], s[38:39], 0, v[140:141]
	s_add_i32 m0, s40, 0x2000
	s_nop 0
	global_load_lds_dwordx4 v[212:213], off
	v_lshl_add_u64 v[212:213], v[216:217], 0, s[8:9]
	s_mov_b32 m0, s53
	s_nop 0
	global_load_lds_dwordx4 v[212:213], off
	v_lshl_add_u64 v[212:213], v[218:219], 0, s[8:9]
	s_mov_b32 m0, s54
	s_nop 0
	global_load_lds_dwordx4 v[212:213], off
	s_waitcnt vmcnt(8)
	s_waitcnt lgkmcnt(0)
	s_setprio 1
	s_barrier
	v_mfma_f32_16x16x32_bf16 v[94:97], v[130:133], v[180:183], v[94:97]
	v_mfma_f32_16x16x32_bf16 v[90:93], v[150:153], v[180:183], v[90:93]
	v_mfma_f32_16x16x32_bf16 v[86:89], v[130:133], v[188:191], v[86:89]
	v_mfma_f32_16x16x32_bf16 v[82:85], v[150:153], v[188:191], v[82:85]
	v_mfma_f32_16x16x32_bf16 v[78:81], v[130:133], v[196:199], v[78:81]
	v_mfma_f32_16x16x32_bf16 v[74:77], v[150:153], v[196:199], v[74:77]
	v_mfma_f32_16x16x32_bf16 v[70:73], v[130:133], v[204:207], v[70:73]
	v_mfma_f32_16x16x32_bf16 v[66:69], v[150:153], v[204:207], v[66:69]
	v_mfma_f32_16x16x32_bf16 v[94:97], v[134:137], v[184:187], v[94:97]
	v_mfma_f32_16x16x32_bf16 v[90:93], v[154:157], v[184:187], v[90:93]
	v_mfma_f32_16x16x32_bf16 v[86:89], v[134:137], v[192:195], v[86:89]
	v_mfma_f32_16x16x32_bf16 v[82:85], v[154:157], v[192:195], v[82:85]
	v_mfma_f32_16x16x32_bf16 v[78:81], v[134:137], v[200:203], v[78:81]
	v_mfma_f32_16x16x32_bf16 v[74:77], v[154:157], v[200:203], v[74:77]
	v_mfma_f32_16x16x32_bf16 v[70:73], v[134:137], v[208:211], v[70:73]
	v_mfma_f32_16x16x32_bf16 v[66:69], v[154:157], v[208:211], v[66:69]
	v_mfma_f32_16x16x32_bf16 v[30:33], v[164:167], v[180:183], v[30:33]
	v_mfma_f32_16x16x32_bf16 v[26:29], v[172:175], v[180:183], v[26:29]
	v_mfma_f32_16x16x32_bf16 v[14:17], v[164:167], v[188:191], v[14:17]
	v_mfma_f32_16x16x32_bf16 v[2:5], v[172:175], v[188:191], v[2:5]
	v_mfma_f32_16x16x32_bf16 v[22:25], v[164:167], v[196:199], v[22:25]
	v_mfma_f32_16x16x32_bf16 v[18:21], v[172:175], v[196:199], v[18:21]
	v_mfma_f32_16x16x32_bf16 v[10:13], v[164:167], v[204:207], v[10:13]
	v_mfma_f32_16x16x32_bf16 v[6:9], v[172:175], v[204:207], v[6:9]
	v_mfma_f32_16x16x32_bf16 v[30:33], v[168:171], v[184:187], v[30:33]
	v_mfma_f32_16x16x32_bf16 v[26:29], v[176:179], v[184:187], v[26:29]
	v_mfma_f32_16x16x32_bf16 v[14:17], v[168:171], v[192:195], v[14:17]
	v_mfma_f32_16x16x32_bf16 v[2:5], v[176:179], v[192:195], v[2:5]
	v_mfma_f32_16x16x32_bf16 v[22:25], v[168:171], v[200:203], v[22:25]
	v_mfma_f32_16x16x32_bf16 v[18:21], v[176:179], v[200:203], v[18:21]
	v_mfma_f32_16x16x32_bf16 v[10:13], v[168:171], v[208:211], v[10:13]
	v_mfma_f32_16x16x32_bf16 v[6:9], v[176:179], v[208:211], v[6:9]
	s_barrier
	s_setprio 0
	s_add_i32 s66, s66, 2
	s_add_u32 s36, s36, 0x100
	s_addc_u32 s37, s37, 0
	s_add_u32 s64, s64, 0x100
	s_addc_u32 s65, s65, 0
	s_cmp_gt_u32 s66, 29
	s_cbranch_scc0 .LBB0_305
	s_and_b64 vcc, exec, s[10:11]
	s_cbranch_vccz .LBB0_308
	s_barrier

; #define PG8_STAGE(bufoff, gbase, VO) do { _Pragma("unroll") for (int _i = 0; _i < 2; ++_i) \
;         __builtin_amdgcn_global_load_lds((const unsigned*)((const char*)(gbase) + VO[_i]), (LAS unsigned*)(lds + (bufoff) + ldsw + _i * 8192), 16, 0, 0); } while (0)
; #define PG8_LDA(dst, b, h) do { _Pragma("unroll") for (int m = 0; m < 4; ++m) _Pragma("unroll") for (int k = 0; k < 2; ++k) dst[m][k] = *(const LAS bf16x8*)(lds + PG8_SA(b, h) + aoff + m * 2048 + k * 1024); } while (0)
; #define PG8_LDB(dst, b, h) do { _Pragma("unroll") for (int n = 0; n < 2; ++n) _Pragma("unroll") for (int k = 0; k < 2; ++k) dst[n][k] = *(const LAS bf16x8*)(lds + PG8_SB(b, h) + boff + n * 2048 + k * 1024); } while (0)
; #define PG8_MMA(ai, bj, At, Bt) do { __builtin_amdgcn_s_setprio(1); _Pragma("unroll") for (int m = 0; m < 4; ++m) _Pragma("unroll") for (int n = 0; n < 2; ++n) _Pragma("unroll") for (int k = 0; k < 2; ++k) \
;         acc[ai][bj][m][n] = __builtin_amdgcn_mfma_f32_16x16x32_bf16(Bt[n][k], At[m][k], acc[ai][bj][m][n], 0, 0, 0); __builtin_amdgcn_s_setprio(0); } while (0)
; #define PG8_WAIT_V(n) asm volatile("s_waitcnt vmcnt(" #n ")" ::: "memory")
; #define PG8_WAIT_L(n) asm volatile("s_waitcnt lgkmcnt(" #n ")" ::: "memory")
; #define PG8_BAR __builtin_amdgcn_s_barrier()
; #define PG8_SCHED __builtin_amdgcn_sched_barrier(0)
; template <int NSEG, class Epi, bool ALIGN_EPI = PG8_ALIGN, bool SP2 = PG8_SP2>
; DI void gemm_phase(LAS unsigned char* lds, const Gemm g, const StaticOrder& S, const Epi& E) {
;     ...
;             const char* a1 = cA + (size_t)(t + 1) * kstep;
;             const char* a2 = last ? nA : cA + (size_t)(t + 2) * kstep; const char* b2 = last ? nB : cB + (size_t)(t + 2) * kstep;
;             const char* a3 = a2 + kstep; const char* b3 = b2 + kstep;
;             unsigned v2[2]; v2[0] = (NSEG > 1 && last) ? voffN[0] : voffC[0]; v2[1] = (NSEG > 1 && last) ? voffN[1] : voffC[1];
;             const size_t h2 = (NSEG > 1 && last) ? hstepN : hstepC;
;             if constexpr (SP2) {
;             PG8_LDB(B0, 0, 0); PG8_LDB(B1, 0, 1); PG8_SCHED; PG8_LDA(At, 0, 0); PG8_STAGE(PG8_SA(1, 1), a1 + hstepC, voffC);
;             PG8_WAIT_V(8); PG8_WAIT_L(0); PG8_BAR; PG8_MMA(0, 0, At, B0); PG8_MMA(0, 1, At, B1); PG8_BAR; PG8_SCHED;
;             PG8_LDA(At, 0, 1); PG8_STAGE(PG8_SB(0, 0), b2, v2); PG8_STAGE(PG8_SB(0, 1), b2 + h2, v2); PG8_STAGE(PG8_SA(0, 0), a2, v2);
.LBB0_369:
	v_add_u32_e32 v131, s59, v194
	v_add_u32_e32 v133, s60, v194
	ds_read_b128 v[138:141], v131
	ds_read_b128 v[142:145], v131 offset:1024
	ds_read_b128 v[146:149], v131 offset:2048
	ds_read_b128 v[150:153], v131 offset:3072
	ds_read_b128 v[154:157], v133
	ds_read_b128 v[158:161], v133 offset:1024
	ds_read_b128 v[162:165], v133 offset:2048
	ds_read_b128 v[166:169], v133 offset:3072
	s_cmp_eq_u32 s69, s72
	s_cselect_b64 vcc, -1, 0
	s_add_i32 s72, s72, 2
	s_add_u32 s42, s34, s38
	s_addc_u32 s43, s35, s39
	s_add_u32 s73, s42, 0x100
	s_addc_u32 s74, s43, 0
	s_and_b64 s[42:43], vcc, exec
	s_cselect_b32 s43, s21, s74
	s_cselect_b32 s42, s20, s73
	s_cselect_b32 s73, s25, s37
	s_cselect_b32 s74, s24, s36
	s_add_u32 s75, s70, s38
	s_addc_u32 s78, s71, s39
	s_and_b64 s[76:77], vcc, exec
	v_cndmask_b32_e32 v174, v132, v197, vcc
	v_cndmask_b32_e32 v216, v130, v198, vcc
	s_cselect_b32 s77, s23, s78
	s_cselect_b32 s76, s22, s75
	v_lshl_add_u64 v[218:219], v[134:135], 0, s[38:39]
	s_add_i32 m0, s48, 0xc000
	ds_read_b128 v[170:173], v196
	ds_read_b128 v[178:181], v196 offset:1024
	ds_read_b128 v[182:185], v196 offset:2048
	ds_read_b128 v[186:189], v196 offset:3072
	ds_read_b128 v[200:203], v196 offset:4096
	ds_read_b128 v[204:207], v196 offset:5120
	ds_read_b128 v[208:211], v196 offset:6144
	ds_read_b128 v[212:215], v196 offset:7168
	global_load_lds_dwordx4 v[218:219], off
	v_lshl_add_u64 v[218:219], v[136:137], 0, s[38:39]
	s_add_i32 m0, s48, 0xe000
	s_nop 0
	global_load_lds_dwordx4 v[218:219], off
	s_waitcnt vmcnt(8)
	s_waitcnt lgkmcnt(0)
	s_setprio 1
	s_barrier
	v_mfma_f32_16x16x32_bf16 v[126:129], v[138:141], v[170:173], v[126:129]
	v_mfma_f32_16x16x32_bf16 v[122:125], v[146:149], v[170:173], v[122:125]
	v_mfma_f32_16x16x32_bf16 v[118:121], v[138:141], v[182:185], v[118:121]
	v_mfma_f32_16x16x32_bf16 v[114:117], v[146:149], v[182:185], v[114:117]
	v_mfma_f32_16x16x32_bf16 v[106:109], v[138:141], v[200:203], v[106:109]
	v_mfma_f32_16x16x32_bf16 v[98:101], v[146:149], v[200:203], v[98:101]
	v_mfma_f32_16x16x32_bf16 v[90:93], v[138:141], v[208:211], v[90:93]
	v_mfma_f32_16x16x32_bf16 v[82:85], v[146:149], v[208:211], v[82:85]
	v_mfma_f32_16x16x32_bf16 v[126:129], v[142:145], v[178:181], v[126:129]
	v_mfma_f32_16x16x32_bf16 v[122:125], v[150:153], v[178:181], v[122:125]
	v_mfma_f32_16x16x32_bf16 v[118:121], v[142:145], v[186:189], v[118:121]
	v_mfma_f32_16x16x32_bf16 v[114:117], v[150:153], v[186:189], v[114:117]
	v_mfma_f32_16x16x32_bf16 v[106:109], v[142:145], v[204:207], v[106:109]
	v_mfma_f32_16x16x32_bf16 v[98:101], v[150:153], v[204:207], v[98:101]
	v_mfma_f32_16x16x32_bf16 v[90:93], v[142:145], v[212:215], v[90:93]
	v_mfma_f32_16x16x32_bf16 v[82:85], v[150:153], v[212:215], v[82:85]
	v_mfma_f32_16x16x32_bf16 v[78:81], v[154:157], v[170:173], v[78:81]
	v_mfma_f32_16x16x32_bf16 v[74:77], v[162:165], v[170:173], v[74:77]
	v_mfma_f32_16x16x32_bf16 v[70:73], v[154:157], v[182:185], v[70:73]
	v_mfma_f32_16x16x32_bf16 v[66:69], v[162:165], v[182:185], v[66:69]
	v_mfma_f32_16x16x32_bf16 v[62:65], v[154:157], v[200:203], v[62:65]
	v_mfma_f32_16x16x32_bf16 v[58:61], v[162:165], v[200:203], v[58:61]
	v_mfma_f32_16x16x32_bf16 v[54:57], v[154:157], v[208:211], v[54:57]
	v_mfma_f32_16x16x32_bf16 v[50:53], v[162:165], v[208:211], v[50:53]
	v_mfma_f32_16x16x32_bf16 v[78:81], v[158:161], v[178:181], v[78:81]
	v_mfma_f32_16x16x32_bf16 v[74:77], v[166:169], v[178:181], v[74:77]
	v_mfma_f32_16x16x32_bf16 v[70:73], v[158:161], v[186:189], v[70:73]
	v_mfma_f32_16x16x32_bf16 v[66:69], v[166:169], v[186:189], v[66:69]
	v_mfma_f32_16x16x32_bf16 v[62:65], v[158:161], v[204:207], v[62:65]
	v_mfma_f32_16x16x32_bf16 v[58:61], v[166:169], v[204:207], v[58:61]
	v_mfma_f32_16x16x32_bf16 v[54:57], v[158:161], v[212:215], v[54:57]
	v_mfma_f32_16x16x32_bf16 v[50:53], v[166:169], v[212:215], v[50:53]
	s_barrier
	s_setprio 0
	s_add_i32 s75, s59, s47
	s_mov_b32 m0, s75
	ds_read_b128 v[170:173], v196 offset:16384
	ds_read_b128 v[178:181], v196 offset:17408
	ds_read_b128 v[182:185], v196 offset:18432
	ds_read_b128 v[186:189], v196 offset:19456
	ds_read_b128 v[200:203], v196 offset:20480
	ds_read_b128 v[204:207], v196 offset:21504
	ds_read_b128 v[208:211], v196 offset:22528
	ds_read_b128 v[212:215], v196 offset:23552
	global_load_lds_dwordx4 v174, s[76:77]
	v_mov_b32_e32 v217, v175
	s_add_i32 m0, s75, 0x2000
	v_lshl_add_u64 v[218:219], s[76:77], 0, v[174:175]
	v_lshl_add_u64 v[220:221], s[76:77], 0, v[216:217]
	global_load_lds_dwordx4 v216, s[76:77]
	s_add_u32 s76, s76, s74
	s_addc_u32 s77, s77, s73
	s_add_i32 s75, s60, s47
	s_mov_b32 m0, s75
	v_lshl_add_u64 v[222:223], s[76:77], 0, v[174:175]
	global_load_lds_dwordx4 v174, s[76:77]
	s_add_i32 m0, s75, 0x2000
	v_lshl_add_u64 v[224:225], s[76:77], 0, v[216:217]
	global_load_lds_dwordx4 v216, s[76:77]
	s_mov_b32 m0, s48
	v_lshl_add_u64 v[226:227], s[42:43], 0, v[174:175]
	global_load_lds_dwordx4 v174, s[42:43]
	s_mov_b32 m0, s49
	v_lshl_add_u64 v[228:229], s[42:43], 0, v[216:217]
	global_load_lds_dwordx4 v216, s[42:43]
	s_waitcnt vmcnt(8)
	s_waitcnt lgkmcnt(0)
	s_setprio 1
	s_barrier
; #define PG8_STAGE(bufoff, gbase, VO) do { _Pragma("unroll") for (int _i = 0; _i < 2; ++_i) \
;         __builtin_amdgcn_global_load_lds((const unsigned*)((const char*)(gbase) + VO[_i]), (LAS unsigned*)(lds + (bufoff) + ldsw + _i * 8192), 16, 0, 0); } while (0)
; #define PG8_LDA(dst, b, h) do { _Pragma("unroll") for (int m = 0; m < 4; ++m) _Pragma("unroll") for (int k = 0; k < 2; ++k) dst[m][k] = *(const LAS bf16x8*)(lds + PG8_SA(b, h) + aoff + m * 2048 + k * 1024); } while (0)
; #define PG8_LDB(dst, b, h) do { _Pragma("unroll") for (int n = 0; n < 2; ++n) _Pragma("unroll") for (int k = 0; k < 2; ++k) dst[n][k] = *(const LAS bf16x8*)(lds + PG8_SB(b, h) + boff + n * 2048 + k * 1024); } while (0)
; #define PG8_MMA(ai, bj, At, Bt) do { __builtin_amdgcn_s_setprio(1); _Pragma("unroll") for (int m = 0; m < 4; ++m) _Pragma("unroll") for (int n = 0; n < 2; ++n) _Pragma("unroll") for (int k = 0; k < 2; ++k) \
;         acc[ai][bj][m][n] = __builtin_amdgcn_mfma_f32_16x16x32_bf16(Bt[n][k], At[m][k], acc[ai][bj][m][n], 0, 0, 0); __builtin_amdgcn_s_setprio(0); } while (0)
; #define PG8_WAIT_V(n) asm volatile("s_waitcnt vmcnt(" #n ")" ::: "memory")
; #define PG8_WAIT_L(n) asm volatile("s_waitcnt lgkmcnt(" #n ")" ::: "memory")
; #define PG8_BAR __builtin_amdgcn_s_barrier()
; #define PG8_SCHED __builtin_amdgcn_sched_barrier(0)
; template <int NSEG, class Epi, bool ALIGN_EPI = PG8_ALIGN, bool SP2 = PG8_SP2>
; DI void gemm_phase(LAS unsigned char* lds, const Gemm g, const StaticOrder& S, const Epi& E) {
;     ...
;             PG8_WAIT_V(8); PG8_WAIT_L(0); PG8_BAR; PG8_MMA(1, 0, At, B0); PG8_MMA(1, 1, At, B1); PG8_BAR; PG8_SCHED;
;             PG8_LDB(B0, 1, 0); PG8_LDB(B1, 1, 1); PG8_SCHED; PG8_LDA(At, 1, 0); PG8_STAGE(PG8_SA(0, 1), a2 + h2, v2);
;             PG8_WAIT_V(8); PG8_WAIT_L(0); PG8_BAR; PG8_MMA(0, 0, At, B0); PG8_MMA(0, 1, At, B1); PG8_BAR; PG8_SCHED;
	v_mfma_f32_16x16x32_bf16 v[46:49], v[138:141], v[170:173], v[46:49]
	v_mfma_f32_16x16x32_bf16 v[42:45], v[146:149], v[170:173], v[42:45]
	v_mfma_f32_16x16x32_bf16 v[38:41], v[138:141], v[182:185], v[38:41]
	v_mfma_f32_16x16x32_bf16 v[34:37], v[146:149], v[182:185], v[34:37]
	v_mfma_f32_16x16x32_bf16 v[30:33], v[138:141], v[200:203], v[30:33]
	v_mfma_f32_16x16x32_bf16 v[26:29], v[146:149], v[200:203], v[26:29]
	v_mfma_f32_16x16x32_bf16 v[22:25], v[138:141], v[208:211], v[22:25]
	v_mfma_f32_16x16x32_bf16 v[18:21], v[146:149], v[208:211], v[18:21]
	v_mfma_f32_16x16x32_bf16 v[46:49], v[142:145], v[178:181], v[46:49]
	v_mfma_f32_16x16x32_bf16 v[42:45], v[150:153], v[178:181], v[42:45]
	v_mfma_f32_16x16x32_bf16 v[38:41], v[142:145], v[186:189], v[38:41]
	v_mfma_f32_16x16x32_bf16 v[34:37], v[150:153], v[186:189], v[34:37]
	v_mfma_f32_16x16x32_bf16 v[30:33], v[142:145], v[204:207], v[30:33]
	v_mfma_f32_16x16x32_bf16 v[26:29], v[150:153], v[204:207], v[26:29]
	v_mfma_f32_16x16x32_bf16 v[22:25], v[142:145], v[212:215], v[22:25]
	v_mfma_f32_16x16x32_bf16 v[18:21], v[150:153], v[212:215], v[18:21]
	v_mfma_f32_16x16x32_bf16 v[14:17], v[154:157], v[170:173], v[14:17]
	v_mfma_f32_16x16x32_bf16 v[10:13], v[162:165], v[170:173], v[10:13]
	v_mfma_f32_16x16x32_bf16 v[6:9], v[154:157], v[182:185], v[6:9]
	v_mfma_f32_16x16x32_bf16 v[2:5], v[162:165], v[182:185], v[2:5]
	v_mfma_f32_16x16x32_bf16 v[86:89], v[154:157], v[200:203], v[86:89]
	v_mfma_f32_16x16x32_bf16 v[94:97], v[162:165], v[200:203], v[94:97]
	v_mfma_f32_16x16x32_bf16 v[102:105], v[154:157], v[208:211], v[102:105]
	v_mfma_f32_16x16x32_bf16 v[110:113], v[162:165], v[208:211], v[110:113]
	v_mfma_f32_16x16x32_bf16 v[14:17], v[158:161], v[178:181], v[14:17]
	v_mfma_f32_16x16x32_bf16 v[10:13], v[166:169], v[178:181], v[10:13]
	v_mfma_f32_16x16x32_bf16 v[6:9], v[158:161], v[186:189], v[6:9]
	v_mfma_f32_16x16x32_bf16 v[2:5], v[166:169], v[186:189], v[2:5]
	v_mfma_f32_16x16x32_bf16 v[86:89], v[158:161], v[204:207], v[86:89]
	v_mfma_f32_16x16x32_bf16 v[94:97], v[166:169], v[204:207], v[94:97]
	v_mfma_f32_16x16x32_bf16 v[102:105], v[158:161], v[212:215], v[102:105]
	v_mfma_f32_16x16x32_bf16 v[110:113], v[166:169], v[212:215], v[110:113]
	s_barrier
	s_setprio 0
	s_add_i32 s75, 0, 0x18000
	v_add_u32_e32 v131, s75, v194
	s_add_i32 s76, 0, 0x1c000
	ds_read_b128 v[138:141], v131
	ds_read_b128 v[142:145], v131 offset:1024
	ds_read_b128 v[146:149], v131 offset:2048
	ds_read_b128 v[150:153], v131 offset:3072
	v_add_u32_e32 v131, s76, v194
	ds_read_b128 v[154:157], v131
	ds_read_b128 v[158:161], v131 offset:1024
	ds_read_b128 v[162:165], v131 offset:2048
	ds_read_b128 v[166:169], v131 offset:3072
	s_add_u32 s42, s42, s74
	s_addc_u32 s43, s43, s73
	s_mov_b32 m0, s50
	ds_read_b128 v[170:173], v196 offset:32768
	ds_read_b128 v[178:181], v196 offset:33792
	ds_read_b128 v[182:185], v196 offset:34816
	ds_read_b128 v[186:189], v196 offset:35840
	ds_read_b128 v[200:203], v196 offset:36864
	ds_read_b128 v[204:207], v196 offset:37888
	ds_read_b128 v[208:211], v196 offset:38912
	ds_read_b128 v[212:215], v196 offset:39936
	global_load_lds_dwordx4 v174, s[42:43]
	s_mov_b32 m0, s51
	s_nop 0
	global_load_lds_dwordx4 v216, s[42:43]
	s_waitcnt vmcnt(8)
	s_waitcnt lgkmcnt(0)
	s_setprio 1
	s_barrier
	v_mfma_f32_16x16x32_bf16 v[126:129], v[138:141], v[170:173], v[126:129]
	v_mfma_f32_16x16x32_bf16 v[122:125], v[146:149], v[170:173], v[122:125]
	v_mfma_f32_16x16x32_bf16 v[118:121], v[138:141], v[182:185], v[118:121]
	v_mfma_f32_16x16x32_bf16 v[114:117], v[146:149], v[182:185], v[114:117]
	v_mfma_f32_16x16x32_bf16 v[106:109], v[138:141], v[200:203], v[106:109]
	v_mfma_f32_16x16x32_bf16 v[98:101], v[146:149], v[200:203], v[98:101]
	v_mfma_f32_16x16x32_bf16 v[90:93], v[138:141], v[208:211], v[90:93]
	v_mfma_f32_16x16x32_bf16 v[82:85], v[146:149], v[208:211], v[82:85]
	v_mfma_f32_16x16x32_bf16 v[126:129], v[142:145], v[178:181], v[126:129]
	v_mfma_f32_16x16x32_bf16 v[122:125], v[150:153], v[178:181], v[122:125]
	v_mfma_f32_16x16x32_bf16 v[118:121], v[142:145], v[186:189], v[118:121]
	v_mfma_f32_16x16x32_bf16 v[114:117], v[150:153], v[186:189], v[114:117]
	v_mfma_f32_16x16x32_bf16 v[106:109], v[142:145], v[204:207], v[106:109]
	v_mfma_f32_16x16x32_bf16 v[98:101], v[150:153], v[204:207], v[98:101]
	v_mfma_f32_16x16x32_bf16 v[90:93], v[142:145], v[212:215], v[90:93]
	v_mfma_f32_16x16x32_bf16 v[82:85], v[150:153], v[212:215], v[82:85]
	v_mfma_f32_16x16x32_bf16 v[78:81], v[154:157], v[170:173], v[78:81]
	v_mfma_f32_16x16x32_bf16 v[74:77], v[162:165], v[170:173], v[74:77]
	v_mfma_f32_16x16x32_bf16 v[70:73], v[154:157], v[182:185], v[70:73]
	v_mfma_f32_16x16x32_bf16 v[66:69], v[162:165], v[182:185], v[66:69]
	v_mfma_f32_16x16x32_bf16 v[62:65], v[154:157], v[200:203], v[62:65]
	v_mfma_f32_16x16x32_bf16 v[58:61], v[162:165], v[200:203], v[58:61]
	v_mfma_f32_16x16x32_bf16 v[54:57], v[154:157], v[208:211], v[54:57]
	v_mfma_f32_16x16x32_bf16 v[50:53], v[162:165], v[208:211], v[50:53]
	v_mfma_f32_16x16x32_bf16 v[78:81], v[158:161], v[178:181], v[78:81]
	v_mfma_f32_16x16x32_bf16 v[74:77], v[166:169], v[178:181], v[74:77]
	v_mfma_f32_16x16x32_bf16 v[70:73], v[158:161], v[186:189], v[70:73]
	v_mfma_f32_16x16x32_bf16 v[66:69], v[166:169], v[186:189], v[66:69]
	v_mfma_f32_16x16x32_bf16 v[62:65], v[158:161], v[204:207], v[62:65]
	v_mfma_f32_16x16x32_bf16 v[58:61], v[166:169], v[204:207], v[58:61]
	v_mfma_f32_16x16x32_bf16 v[54:57], v[158:161], v[212:215], v[54:57]
	v_mfma_f32_16x16x32_bf16 v[50:53], v[166:169], v[212:215], v[50:53]
	s_barrier
; #define PG8_STAGE(bufoff, gbase, VO) do { _Pragma("unroll") for (int _i = 0; _i < 2; ++_i) \
;         __builtin_amdgcn_global_load_lds((const unsigned*)((const char*)(gbase) + VO[_i]), (LAS unsigned*)(lds + (bufoff) + ldsw + _i * 8192), 16, 0, 0); } while (0)
; #define PG8_LDA(dst, b, h) do { _Pragma("unroll") for (int m = 0; m < 4; ++m) _Pragma("unroll") for (int k = 0; k < 2; ++k) dst[m][k] = *(const LAS bf16x8*)(lds + PG8_SA(b, h) + aoff + m * 2048 + k * 1024); } while (0)
; #define PG8_MMA(ai, bj, At, Bt) do { __builtin_amdgcn_s_setprio(1); _Pragma("unroll") for (int m = 0; m < 4; ++m) _Pragma("unroll") for (int n = 0; n < 2; ++n) _Pragma("unroll") for (int k = 0; k < 2; ++k) \
;         acc[ai][bj][m][n] = __builtin_amdgcn_mfma_f32_16x16x32_bf16(Bt[n][k], At[m][k], acc[ai][bj][m][n], 0, 0, 0); __builtin_amdgcn_s_setprio(0); } while (0)
; #define PG8_WAIT_V(n) asm volatile("s_waitcnt vmcnt(" #n ")" ::: "memory")
; #define PG8_WAIT_L(n) asm volatile("s_waitcnt lgkmcnt(" #n ")" ::: "memory")
; #define PG8_BAR __builtin_amdgcn_s_barrier()
; #define PG8_SCHED __builtin_amdgcn_sched_barrier(0)
; template <int NSEG, class Epi, bool ALIGN_EPI = PG8_ALIGN, bool SP2 = PG8_SP2>
; DI void gemm_phase(LAS unsigned char* lds, const Gemm g, const StaticOrder& S, const Epi& E) {
;     ...
;             PG8_LDA(At, 1, 1); PG8_STAGE(PG8_SB(1, 0), b3, v2); PG8_STAGE(PG8_SB(1, 1), b3 + h2, v2); PG8_STAGE(PG8_SA(1, 0), a3, v2);
;             PG8_WAIT_V(8); PG8_WAIT_L(0); PG8_BAR; PG8_MMA(1, 0, At, B0); PG8_MMA(1, 1, At, B1); PG8_BAR; PG8_SCHED;
	s_setprio 0
	s_add_i32 s42, s75, s47
	v_lshl_add_u64 v[216:217], v[218:219], 0, s[10:11]
	s_mov_b32 m0, s42
	ds_read_b128 v[170:173], v196 offset:49152
	ds_read_b128 v[178:181], v196 offset:50176
	ds_read_b128 v[182:185], v196 offset:51200
	ds_read_b128 v[186:189], v196 offset:52224
	ds_read_b128 v[200:203], v196 offset:53248
	ds_read_b128 v[204:207], v196 offset:54272
	ds_read_b128 v[208:211], v196 offset:55296
	ds_read_b128 v[212:215], v196 offset:56320
	global_load_lds_dwordx4 v[216:217], off
	v_lshl_add_u64 v[216:217], v[220:221], 0, s[10:11]
	s_add_i32 m0, s42, 0x2000
	s_add_i32 s42, s76, s47
	global_load_lds_dwordx4 v[216:217], off
	v_lshl_add_u64 v[216:217], v[222:223], 0, s[10:11]
	s_mov_b32 m0, s42
	s_nop 0
	global_load_lds_dwordx4 v[216:217], off
	v_lshl_add_u64 v[216:217], v[224:225], 0, s[10:11]
	s_add_i32 m0, s42, 0x2000
	s_nop 0
	global_load_lds_dwordx4 v[216:217], off
	v_lshl_add_u64 v[216:217], v[226:227], 0, s[10:11]
	s_mov_b32 m0, s56
	s_nop 0
	global_load_lds_dwordx4 v[216:217], off
	v_lshl_add_u64 v[216:217], v[228:229], 0, s[10:11]
	s_mov_b32 m0, s57
	s_nop 0
	global_load_lds_dwordx4 v[216:217], off
	s_waitcnt vmcnt(8)
	s_waitcnt lgkmcnt(0)
	s_setprio 1
	s_barrier
	v_mfma_f32_16x16x32_bf16 v[46:49], v[138:141], v[170:173], v[46:49]
	v_mfma_f32_16x16x32_bf16 v[42:45], v[146:149], v[170:173], v[42:45]
	v_mfma_f32_16x16x32_bf16 v[38:41], v[138:141], v[182:185], v[38:41]
	v_mfma_f32_16x16x32_bf16 v[34:37], v[146:149], v[182:185], v[34:37]
	v_mfma_f32_16x16x32_bf16 v[30:33], v[138:141], v[200:203], v[30:33]
	v_mfma_f32_16x16x32_bf16 v[26:29], v[146:149], v[200:203], v[26:29]
	v_mfma_f32_16x16x32_bf16 v[22:25], v[138:141], v[208:211], v[22:25]
	v_mfma_f32_16x16x32_bf16 v[18:21], v[146:149], v[208:211], v[18:21]
	v_mfma_f32_16x16x32_bf16 v[46:49], v[142:145], v[178:181], v[46:49]
	v_mfma_f32_16x16x32_bf16 v[42:45], v[150:153], v[178:181], v[42:45]
	v_mfma_f32_16x16x32_bf16 v[38:41], v[142:145], v[186:189], v[38:41]
	v_mfma_f32_16x16x32_bf16 v[34:37], v[150:153], v[186:189], v[34:37]
	v_mfma_f32_16x16x32_bf16 v[30:33], v[142:145], v[204:207], v[30:33]
	v_mfma_f32_16x16x32_bf16 v[26:29], v[150:153], v[204:207], v[26:29]
	v_mfma_f32_16x16x32_bf16 v[22:25], v[142:145], v[212:215], v[22:25]
	v_mfma_f32_16x16x32_bf16 v[18:21], v[150:153], v[212:215], v[18:21]
	v_mfma_f32_16x16x32_bf16 v[14:17], v[154:157], v[170:173], v[14:17]
	v_mfma_f32_16x16x32_bf16 v[10:13], v[162:165], v[170:173], v[10:13]
	v_mfma_f32_16x16x32_bf16 v[6:9], v[154:157], v[182:185], v[6:9]
	v_mfma_f32_16x16x32_bf16 v[2:5], v[162:165], v[182:185], v[2:5]
	v_mfma_f32_16x16x32_bf16 v[86:89], v[154:157], v[200:203], v[86:89]
	v_mfma_f32_16x16x32_bf16 v[94:97], v[162:165], v[200:203], v[94:97]
	v_mfma_f32_16x16x32_bf16 v[102:105], v[154:157], v[208:211], v[102:105]
	v_mfma_f32_16x16x32_bf16 v[110:113], v[162:165], v[208:211], v[110:113]
	v_mfma_f32_16x16x32_bf16 v[14:17], v[158:161], v[178:181], v[14:17]
	v_mfma_f32_16x16x32_bf16 v[10:13], v[166:169], v[178:181], v[10:13]
	v_mfma_f32_16x16x32_bf16 v[6:9], v[158:161], v[186:189], v[6:9]
	v_mfma_f32_16x16x32_bf16 v[2:5], v[166:169], v[186:189], v[2:5]
	v_mfma_f32_16x16x32_bf16 v[86:89], v[158:161], v[204:207], v[86:89]
	v_mfma_f32_16x16x32_bf16 v[94:97], v[166:169], v[204:207], v[94:97]
	v_mfma_f32_16x16x32_bf16 v[102:105], v[158:161], v[212:215], v[102:105]
	v_mfma_f32_16x16x32_bf16 v[110:113], v[166:169], v[212:215], v[110:113]
	s_barrier
	s_setprio 0
	s_add_u32 s38, s38, 0x100
	s_addc_u32 s39, s39, 0
	s_cmp_ge_u32 s72, s0
	s_cbranch_scc0 .LBB0_369
	s_and_b64 vcc, exec, s[12:13]
	s_cbranch_vccz .LBB0_372
	s_barrier

; #define PG8_STAGE(bufoff, gbase, VO) do { _Pragma("unroll") for (int _i = 0; _i < 2; ++_i) \
;         __builtin_amdgcn_global_load_lds((const unsigned*)((const char*)(gbase) + VO[_i]), (LAS unsigned*)(lds + (bufoff) + ldsw + _i * 8192), 16, 0, 0); } while (0)
; #define PG8_LDA(dst, b, h) do { _Pragma("unroll") for (int m = 0; m < 4; ++m) _Pragma("unroll") for (int k = 0; k < 2; ++k) dst[m][k] = *(const LAS bf16x8*)(lds + PG8_SA(b, h) + aoff + m * 2048 + k * 1024); } while (0)
; #define PG8_LDB(dst, b, h) do { _Pragma("unroll") for (int n = 0; n < 2; ++n) _Pragma("unroll") for (int k = 0; k < 2; ++k) dst[n][k] = *(const LAS bf16x8*)(lds + PG8_SB(b, h) + boff + n * 2048 + k * 1024); } while (0)
; #define PG8_MMA(ai, bj, At, Bt) do { __builtin_amdgcn_s_setprio(1); _Pragma("unroll") for (int m = 0; m < 4; ++m) _Pragma("unroll") for (int n = 0; n < 2; ++n) _Pragma("unroll") for (int k = 0; k < 2; ++k) \
;         acc[ai][bj][m][n] = __builtin_amdgcn_mfma_f32_16x16x32_bf16(Bt[n][k], At[m][k], acc[ai][bj][m][n], 0, 0, 0); __builtin_amdgcn_s_setprio(0); } while (0)
; #define PG8_WAIT_V(n) asm volatile("s_waitcnt vmcnt(" #n ")" ::: "memory")
; #define PG8_WAIT_L(n) asm volatile("s_waitcnt lgkmcnt(" #n ")" ::: "memory")
; #define PG8_BAR __builtin_amdgcn_s_barrier()
; #define PG8_SCHED __builtin_amdgcn_sched_barrier(0)
; template <int NSEG, class Epi, bool ALIGN_EPI = PG8_ALIGN, bool SP2 = PG8_SP2>
; DI void gemm_phase(LAS unsigned char* lds, const Gemm g, const StaticOrder& S, const Epi& E) {
;     ...
;             PG8_LDB(B0, 0, 0); PG8_LDB(B1, 0, 1); PG8_SCHED; PG8_LDA(At, 0, 0); PG8_STAGE(PG8_SA(1, 1), a1 + hstepC, voffC);
;             PG8_WAIT_V(8); PG8_WAIT_L(0); PG8_BAR; PG8_MMA(0, 0, At, B0); PG8_MMA(0, 1, At, B1); PG8_BAR; PG8_SCHED;
;             PG8_LDA(At, 0, 1); PG8_STAGE(PG8_SB(0, 0), b2, v2); PG8_STAGE(PG8_SB(0, 1), b2 + h2, v2); PG8_STAGE(PG8_SA(0, 0), a2, v2);
.LBB0_427:
	ds_read_b128 v[148:151], v145
	ds_read_b128 v[152:155], v145 offset:1024
	ds_read_b128 v[156:159], v145 offset:2048
	ds_read_b128 v[160:163], v145 offset:3072
	ds_read_b128 v[164:167], v146
	ds_read_b128 v[168:171], v146 offset:1024
	ds_read_b128 v[172:175], v146 offset:2048
	ds_read_b128 v[176:179], v146 offset:3072
	s_add_u32 s38, s36, 0xfff80080
	s_addc_u32 s39, s37, -1
	s_cmp_eq_u32 s61, 28
	s_cselect_b32 s41, s5, s39
	s_cselect_b32 s40, s4, s38
	s_cselect_b32 s39, s35, s27
	s_cselect_b32 s38, s34, s25
	v_lshl_add_u64 v[212:213], s[36:37], 0, v[134:135]
	s_add_i32 m0, s23, 0xc000
	ds_read_b128 v[180:183], v147
	ds_read_b128 v[184:187], v147 offset:1024
	ds_read_b128 v[188:191], v147 offset:2048
	ds_read_b128 v[192:195], v147 offset:3072
	ds_read_b128 v[196:199], v147 offset:4096
	ds_read_b128 v[200:203], v147 offset:5120
	ds_read_b128 v[204:207], v147 offset:6144
	ds_read_b128 v[208:211], v147 offset:7168
	global_load_lds_dwordx4 v[212:213], off
	v_lshl_add_u64 v[212:213], s[36:37], 0, v[136:137]
	s_add_i32 m0, s23, 0xe000
	s_nop 0
	global_load_lds_dwordx4 v[212:213], off
	s_waitcnt vmcnt(8)
	s_waitcnt lgkmcnt(0)
	s_setprio 1
	s_barrier
	v_mfma_f32_16x16x32_bf16 v[126:129], v[148:151], v[180:183], v[126:129]
	v_mfma_f32_16x16x32_bf16 v[122:125], v[156:159], v[180:183], v[122:125]
	v_mfma_f32_16x16x32_bf16 v[118:121], v[148:151], v[188:191], v[118:121]
	v_mfma_f32_16x16x32_bf16 v[114:117], v[156:159], v[188:191], v[114:117]
	v_mfma_f32_16x16x32_bf16 v[102:105], v[148:151], v[196:199], v[102:105]
	v_mfma_f32_16x16x32_bf16 v[98:101], v[156:159], v[196:199], v[98:101]
	v_mfma_f32_16x16x32_bf16 v[86:89], v[148:151], v[204:207], v[86:89]
	v_mfma_f32_16x16x32_bf16 v[82:85], v[156:159], v[204:207], v[82:85]
	v_mfma_f32_16x16x32_bf16 v[126:129], v[152:155], v[184:187], v[126:129]
	v_mfma_f32_16x16x32_bf16 v[122:125], v[160:163], v[184:187], v[122:125]
	v_mfma_f32_16x16x32_bf16 v[118:121], v[152:155], v[192:195], v[118:121]
	v_mfma_f32_16x16x32_bf16 v[114:117], v[160:163], v[192:195], v[114:117]
	v_mfma_f32_16x16x32_bf16 v[102:105], v[152:155], v[200:203], v[102:105]
	v_mfma_f32_16x16x32_bf16 v[98:101], v[160:163], v[200:203], v[98:101]
	v_mfma_f32_16x16x32_bf16 v[86:89], v[152:155], v[208:211], v[86:89]
	v_mfma_f32_16x16x32_bf16 v[82:85], v[160:163], v[208:211], v[82:85]
	v_mfma_f32_16x16x32_bf16 v[110:113], v[164:167], v[180:183], v[110:113]
	v_mfma_f32_16x16x32_bf16 v[106:109], v[172:175], v[180:183], v[106:109]
	v_mfma_f32_16x16x32_bf16 v[94:97], v[164:167], v[188:191], v[94:97]
	v_mfma_f32_16x16x32_bf16 v[90:93], v[172:175], v[188:191], v[90:93]
	v_mfma_f32_16x16x32_bf16 v[78:81], v[164:167], v[196:199], v[78:81]
	v_mfma_f32_16x16x32_bf16 v[74:77], v[172:175], v[196:199], v[74:77]
	v_mfma_f32_16x16x32_bf16 v[70:73], v[164:167], v[204:207], v[70:73]
	v_mfma_f32_16x16x32_bf16 v[66:69], v[172:175], v[204:207], v[66:69]
	v_mfma_f32_16x16x32_bf16 v[110:113], v[168:171], v[184:187], v[110:113]
	v_mfma_f32_16x16x32_bf16 v[106:109], v[176:179], v[184:187], v[106:109]
	v_mfma_f32_16x16x32_bf16 v[94:97], v[168:171], v[192:195], v[94:97]
	v_mfma_f32_16x16x32_bf16 v[90:93], v[176:179], v[192:195], v[90:93]
	v_mfma_f32_16x16x32_bf16 v[78:81], v[168:171], v[200:203], v[78:81]
	v_mfma_f32_16x16x32_bf16 v[74:77], v[176:179], v[200:203], v[74:77]
	v_mfma_f32_16x16x32_bf16 v[70:73], v[168:171], v[208:211], v[70:73]
	v_mfma_f32_16x16x32_bf16 v[66:69], v[176:179], v[208:211], v[66:69]
	s_barrier
	s_setprio 0
	s_add_i32 s62, s55, s47
	v_lshl_add_u64 v[212:213], s[38:39], 0, v[130:131]
	s_mov_b32 m0, s62
	ds_read_b128 v[180:183], v147 offset:16384
	ds_read_b128 v[184:187], v147 offset:17408
	ds_read_b128 v[188:191], v147 offset:18432
	ds_read_b128 v[192:195], v147 offset:19456
	ds_read_b128 v[196:199], v147 offset:20480
	ds_read_b128 v[200:203], v147 offset:21504
	ds_read_b128 v[204:207], v147 offset:22528
	ds_read_b128 v[208:211], v147 offset:23552
	global_load_lds_dwordx4 v[212:213], off
	s_add_i32 m0, s62, 0x2000
	s_add_u32 s62, s38, 0x80000
	v_lshl_add_u64 v[214:215], s[38:39], 0, v[132:133]
	s_addc_u32 s63, s39, 0
	s_add_i32 s64, s56, s47
	global_load_lds_dwordx4 v[214:215], off
	v_lshl_add_u64 v[216:217], s[62:63], 0, v[130:131]
	s_mov_b32 m0, s64
	v_lshl_add_u64 v[218:219], s[40:41], 0, v[132:133]
	global_load_lds_dwordx4 v[216:217], off
	v_lshl_add_u64 v[216:217], s[62:63], 0, v[132:133]
	s_add_i32 m0, s64, 0x2000
	s_nop 0
	global_load_lds_dwordx4 v[216:217], off
	v_lshl_add_u64 v[216:217], s[40:41], 0, v[130:131]
	s_mov_b32 m0, s23
	s_nop 0
	global_load_lds_dwordx4 v[216:217], off
	s_mov_b32 m0, s48
	s_nop 0
	global_load_lds_dwordx4 v[218:219], off
	s_waitcnt vmcnt(8)
	s_waitcnt lgkmcnt(0)
	s_setprio 1
	s_barrier
; #define PG8_STAGE(bufoff, gbase, VO) do { _Pragma("unroll") for (int _i = 0; _i < 2; ++_i) \
;         __builtin_amdgcn_global_load_lds((const unsigned*)((const char*)(gbase) + VO[_i]), (LAS unsigned*)(lds + (bufoff) + ldsw + _i * 8192), 16, 0, 0); } while (0)
; #define PG8_LDA(dst, b, h) do { _Pragma("unroll") for (int m = 0; m < 4; ++m) _Pragma("unroll") for (int k = 0; k < 2; ++k) dst[m][k] = *(const LAS bf16x8*)(lds + PG8_SA(b, h) + aoff + m * 2048 + k * 1024); } while (0)
; #define PG8_LDB(dst, b, h) do { _Pragma("unroll") for (int n = 0; n < 2; ++n) _Pragma("unroll") for (int k = 0; k < 2; ++k) dst[n][k] = *(const LAS bf16x8*)(lds + PG8_SB(b, h) + boff + n * 2048 + k * 1024); } while (0)
; #define PG8_MMA(ai, bj, At, Bt) do { __builtin_amdgcn_s_setprio(1); _Pragma("unroll") for (int m = 0; m < 4; ++m) _Pragma("unroll") for (int n = 0; n < 2; ++n) _Pragma("unroll") for (int k = 0; k < 2; ++k) \
;         acc[ai][bj][m][n] = __builtin_amdgcn_mfma_f32_16x16x32_bf16(Bt[n][k], At[m][k], acc[ai][bj][m][n], 0, 0, 0); __builtin_amdgcn_s_setprio(0); } while (0)
; #define PG8_WAIT_V(n) asm volatile("s_waitcnt vmcnt(" #n ")" ::: "memory")
; #define PG8_WAIT_L(n) asm volatile("s_waitcnt lgkmcnt(" #n ")" ::: "memory")
; #define PG8_BAR __builtin_amdgcn_s_barrier()
; #define PG8_SCHED __builtin_amdgcn_sched_barrier(0)
; template <int NSEG, class Epi, bool ALIGN_EPI = PG8_ALIGN, bool SP2 = PG8_SP2>
; DI void gemm_phase(LAS unsigned char* lds, const Gemm g, const StaticOrder& S, const Epi& E) {
;     ...
;             PG8_WAIT_V(8); PG8_WAIT_L(0); PG8_BAR; PG8_MMA(1, 0, At, B0); PG8_MMA(1, 1, At, B1); PG8_BAR; PG8_SCHED;
;             PG8_LDB(B0, 1, 0); PG8_LDB(B1, 1, 1); PG8_SCHED; PG8_LDA(At, 1, 0); PG8_STAGE(PG8_SA(0, 1), a2 + h2, v2);
;             PG8_WAIT_V(8); PG8_WAIT_L(0); PG8_BAR; PG8_MMA(0, 0, At, B0); PG8_MMA(0, 1, At, B1); PG8_BAR; PG8_SCHED;
	v_mfma_f32_16x16x32_bf16 v[54:57], v[148:151], v[180:183], v[54:57]
	v_mfma_f32_16x16x32_bf16 v[46:49], v[156:159], v[180:183], v[46:49]
	v_mfma_f32_16x16x32_bf16 v[38:41], v[148:151], v[188:191], v[38:41]
	v_mfma_f32_16x16x32_bf16 v[34:37], v[156:159], v[188:191], v[34:37]
	v_mfma_f32_16x16x32_bf16 v[22:25], v[148:151], v[196:199], v[22:25]
	v_mfma_f32_16x16x32_bf16 v[18:21], v[156:159], v[196:199], v[18:21]
	v_mfma_f32_16x16x32_bf16 v[6:9], v[148:151], v[204:207], v[6:9]
	v_mfma_f32_16x16x32_bf16 v[2:5], v[156:159], v[204:207], v[2:5]
	v_mfma_f32_16x16x32_bf16 v[54:57], v[152:155], v[184:187], v[54:57]
	v_mfma_f32_16x16x32_bf16 v[46:49], v[160:163], v[184:187], v[46:49]
	v_mfma_f32_16x16x32_bf16 v[38:41], v[152:155], v[192:195], v[38:41]
	v_mfma_f32_16x16x32_bf16 v[34:37], v[160:163], v[192:195], v[34:37]
	v_mfma_f32_16x16x32_bf16 v[22:25], v[152:155], v[200:203], v[22:25]
	v_mfma_f32_16x16x32_bf16 v[18:21], v[160:163], v[200:203], v[18:21]
	v_mfma_f32_16x16x32_bf16 v[6:9], v[152:155], v[208:211], v[6:9]
	v_mfma_f32_16x16x32_bf16 v[2:5], v[160:163], v[208:211], v[2:5]
	v_mfma_f32_16x16x32_bf16 v[30:33], v[164:167], v[180:183], v[30:33]
	v_mfma_f32_16x16x32_bf16 v[26:29], v[172:175], v[180:183], v[26:29]
	v_mfma_f32_16x16x32_bf16 v[14:17], v[164:167], v[188:191], v[14:17]
	v_mfma_f32_16x16x32_bf16 v[10:13], v[172:175], v[188:191], v[10:13]
	v_mfma_f32_16x16x32_bf16 v[58:61], v[164:167], v[196:199], v[58:61]
	v_mfma_f32_16x16x32_bf16 v[62:65], v[172:175], v[196:199], v[62:65]
	v_mfma_f32_16x16x32_bf16 v[42:45], v[164:167], v[204:207], v[42:45]
	v_mfma_f32_16x16x32_bf16 v[50:53], v[172:175], v[204:207], v[50:53]
	v_mfma_f32_16x16x32_bf16 v[30:33], v[168:171], v[184:187], v[30:33]
	v_mfma_f32_16x16x32_bf16 v[26:29], v[176:179], v[184:187], v[26:29]
	v_mfma_f32_16x16x32_bf16 v[14:17], v[168:171], v[192:195], v[14:17]
	v_mfma_f32_16x16x32_bf16 v[10:13], v[176:179], v[192:195], v[10:13]
	v_mfma_f32_16x16x32_bf16 v[58:61], v[168:171], v[200:203], v[58:61]
	v_mfma_f32_16x16x32_bf16 v[62:65], v[176:179], v[200:203], v[62:65]
	v_mfma_f32_16x16x32_bf16 v[42:45], v[168:171], v[208:211], v[42:45]
	v_mfma_f32_16x16x32_bf16 v[50:53], v[176:179], v[208:211], v[50:53]
	s_barrier
	s_setprio 0
	s_add_i32 s62, 0, 0x18000
	s_add_i32 s63, 0, 0x1c000
	v_add_u32_e32 v160, s62, v143
	v_add_u32_e32 v176, s63, v143
	ds_read_b128 v[148:151], v160
	ds_read_b128 v[152:155], v160 offset:1024
	ds_read_b128 v[156:159], v160 offset:2048
	ds_read_b128 v[160:163], v160 offset:3072
	ds_read_b128 v[164:167], v176
	ds_read_b128 v[168:171], v176 offset:1024
	ds_read_b128 v[172:175], v176 offset:2048
	ds_read_b128 v[176:179], v176 offset:3072
	s_add_u32 s40, s40, 0x80000
	s_addc_u32 s41, s41, 0
	s_mov_b32 m0, s49
	v_lshl_add_u64 v[220:221], s[40:41], 0, v[130:131]
	ds_read_b128 v[180:183], v147 offset:32768
	ds_read_b128 v[184:187], v147 offset:33792
	ds_read_b128 v[188:191], v147 offset:34816
	ds_read_b128 v[192:195], v147 offset:35840
	ds_read_b128 v[196:199], v147 offset:36864
	ds_read_b128 v[200:203], v147 offset:37888
	ds_read_b128 v[204:207], v147 offset:38912
	ds_read_b128 v[208:211], v147 offset:39936
	global_load_lds_dwordx4 v[220:221], off
	v_lshl_add_u64 v[220:221], s[40:41], 0, v[132:133]
	s_mov_b32 m0, s50
	s_nop 0
	global_load_lds_dwordx4 v[220:221], off
	s_waitcnt vmcnt(8)
	s_waitcnt lgkmcnt(0)
	s_setprio 1
	s_barrier
	v_mfma_f32_16x16x32_bf16 v[126:129], v[148:151], v[180:183], v[126:129]
	v_mfma_f32_16x16x32_bf16 v[122:125], v[156:159], v[180:183], v[122:125]
	v_mfma_f32_16x16x32_bf16 v[118:121], v[148:151], v[188:191], v[118:121]
	v_mfma_f32_16x16x32_bf16 v[114:117], v[156:159], v[188:191], v[114:117]
	v_mfma_f32_16x16x32_bf16 v[102:105], v[148:151], v[196:199], v[102:105]
	v_mfma_f32_16x16x32_bf16 v[98:101], v[156:159], v[196:199], v[98:101]
	v_mfma_f32_16x16x32_bf16 v[86:89], v[148:151], v[204:207], v[86:89]
	v_mfma_f32_16x16x32_bf16 v[82:85], v[156:159], v[204:207], v[82:85]
	v_mfma_f32_16x16x32_bf16 v[126:129], v[152:155], v[184:187], v[126:129]
	v_mfma_f32_16x16x32_bf16 v[122:125], v[160:163], v[184:187], v[122:125]
	v_mfma_f32_16x16x32_bf16 v[118:121], v[152:155], v[192:195], v[118:121]
	v_mfma_f32_16x16x32_bf16 v[114:117], v[160:163], v[192:195], v[114:117]
	v_mfma_f32_16x16x32_bf16 v[102:105], v[152:155], v[200:203], v[102:105]
	v_mfma_f32_16x16x32_bf16 v[98:101], v[160:163], v[200:203], v[98:101]
	v_mfma_f32_16x16x32_bf16 v[86:89], v[152:155], v[208:211], v[86:89]
	v_mfma_f32_16x16x32_bf16 v[82:85], v[160:163], v[208:211], v[82:85]
	v_mfma_f32_16x16x32_bf16 v[110:113], v[164:167], v[180:183], v[110:113]
	v_mfma_f32_16x16x32_bf16 v[106:109], v[172:175], v[180:183], v[106:109]
	v_mfma_f32_16x16x32_bf16 v[94:97], v[164:167], v[188:191], v[94:97]
	v_mfma_f32_16x16x32_bf16 v[90:93], v[172:175], v[188:191], v[90:93]
	v_mfma_f32_16x16x32_bf16 v[78:81], v[164:167], v[196:199], v[78:81]
	v_mfma_f32_16x16x32_bf16 v[74:77], v[172:175], v[196:199], v[74:77]
	v_mfma_f32_16x16x32_bf16 v[70:73], v[164:167], v[204:207], v[70:73]
	v_mfma_f32_16x16x32_bf16 v[66:69], v[172:175], v[204:207], v[66:69]
	v_mfma_f32_16x16x32_bf16 v[110:113], v[168:171], v[184:187], v[110:113]
	v_mfma_f32_16x16x32_bf16 v[106:109], v[176:179], v[184:187], v[106:109]
	v_mfma_f32_16x16x32_bf16 v[94:97], v[168:171], v[192:195], v[94:97]
	v_mfma_f32_16x16x32_bf16 v[90:93], v[176:179], v[192:195], v[90:93]
	v_mfma_f32_16x16x32_bf16 v[78:81], v[168:171], v[200:203], v[78:81]
	v_mfma_f32_16x16x32_bf16 v[74:77], v[176:179], v[200:203], v[74:77]
	v_mfma_f32_16x16x32_bf16 v[70:73], v[168:171], v[208:211], v[70:73]
	v_mfma_f32_16x16x32_bf16 v[66:69], v[176:179], v[208:211], v[66:69]
	s_barrier
; #define PG8_STAGE(bufoff, gbase, VO) do { _Pragma("unroll") for (int _i = 0; _i < 2; ++_i) \
;         __builtin_amdgcn_global_load_lds((const unsigned*)((const char*)(gbase) + VO[_i]), (LAS unsigned*)(lds + (bufoff) + ldsw + _i * 8192), 16, 0, 0); } while (0)
; #define PG8_LDA(dst, b, h) do { _Pragma("unroll") for (int m = 0; m < 4; ++m) _Pragma("unroll") for (int k = 0; k < 2; ++k) dst[m][k] = *(const LAS bf16x8*)(lds + PG8_SA(b, h) + aoff + m * 2048 + k * 1024); } while (0)
; #define PG8_MMA(ai, bj, At, Bt) do { __builtin_amdgcn_s_setprio(1); _Pragma("unroll") for (int m = 0; m < 4; ++m) _Pragma("unroll") for (int n = 0; n < 2; ++n) _Pragma("unroll") for (int k = 0; k < 2; ++k) \
;         acc[ai][bj][m][n] = __builtin_amdgcn_mfma_f32_16x16x32_bf16(Bt[n][k], At[m][k], acc[ai][bj][m][n], 0, 0, 0); __builtin_amdgcn_s_setprio(0); } while (0)
; #define PG8_WAIT_V(n) asm volatile("s_waitcnt vmcnt(" #n ")" ::: "memory")
; #define PG8_WAIT_L(n) asm volatile("s_waitcnt lgkmcnt(" #n ")" ::: "memory")
; #define PG8_BAR __builtin_amdgcn_s_barrier()
; #define PG8_SCHED __builtin_amdgcn_sched_barrier(0)
; template <int NSEG, class Epi, bool ALIGN_EPI = PG8_ALIGN, bool SP2 = PG8_SP2>
; DI void gemm_phase(LAS unsigned char* lds, const Gemm g, const StaticOrder& S, const Epi& E) {
;     ...
;             PG8_LDA(At, 1, 1); PG8_STAGE(PG8_SB(1, 0), b3, v2); PG8_STAGE(PG8_SB(1, 1), b3 + h2, v2); PG8_STAGE(PG8_SA(1, 0), a3, v2);
;             PG8_WAIT_V(8); PG8_WAIT_L(0); PG8_BAR; PG8_MMA(1, 0, At, B0); PG8_MMA(1, 1, At, B1); PG8_BAR; PG8_SCHED;
	s_setprio 0
	s_add_i32 s40, s62, s47
	v_lshl_add_u64 v[212:213], v[212:213], 0, s[12:13]
	s_mov_b32 m0, s40
	ds_read_b128 v[180:183], v147 offset:49152
	ds_read_b128 v[184:187], v147 offset:50176
	ds_read_b128 v[188:191], v147 offset:51200
	ds_read_b128 v[192:195], v147 offset:52224
	ds_read_b128 v[196:199], v147 offset:53248
	ds_read_b128 v[200:203], v147 offset:54272
	ds_read_b128 v[204:207], v147 offset:55296
	ds_read_b128 v[208:211], v147 offset:56320
	global_load_lds_dwordx4 v[212:213], off
	s_add_i32 m0, s40, 0x2000
	s_add_u32 s38, s38, 0x80080
	v_lshl_add_u64 v[212:213], v[214:215], 0, s[12:13]
	s_addc_u32 s39, s39, 0
	s_add_i32 s40, s63, s47
	global_load_lds_dwordx4 v[212:213], off
	v_lshl_add_u64 v[212:213], s[38:39], 0, v[130:131]
	s_mov_b32 m0, s40
	s_nop 0
	global_load_lds_dwordx4 v[212:213], off
	v_lshl_add_u64 v[212:213], s[38:39], 0, v[132:133]
	s_add_i32 m0, s40, 0x2000
	s_nop 0
	global_load_lds_dwordx4 v[212:213], off
	v_lshl_add_u64 v[212:213], v[216:217], 0, s[12:13]
	s_mov_b32 m0, s53
	s_nop 0
	global_load_lds_dwordx4 v[212:213], off
	v_lshl_add_u64 v[212:213], v[218:219], 0, s[12:13]
	s_mov_b32 m0, s54
	s_nop 0
	global_load_lds_dwordx4 v[212:213], off
	s_waitcnt vmcnt(8)
	s_waitcnt lgkmcnt(0)
	s_setprio 1
	s_barrier
	v_mfma_f32_16x16x32_bf16 v[54:57], v[148:151], v[180:183], v[54:57]
	v_mfma_f32_16x16x32_bf16 v[46:49], v[156:159], v[180:183], v[46:49]
	v_mfma_f32_16x16x32_bf16 v[38:41], v[148:151], v[188:191], v[38:41]
	v_mfma_f32_16x16x32_bf16 v[34:37], v[156:159], v[188:191], v[34:37]
	v_mfma_f32_16x16x32_bf16 v[22:25], v[148:151], v[196:199], v[22:25]
	v_mfma_f32_16x16x32_bf16 v[18:21], v[156:159], v[196:199], v[18:21]
	v_mfma_f32_16x16x32_bf16 v[6:9], v[148:151], v[204:207], v[6:9]
	v_mfma_f32_16x16x32_bf16 v[2:5], v[156:159], v[204:207], v[2:5]
	v_mfma_f32_16x16x32_bf16 v[54:57], v[152:155], v[184:187], v[54:57]
	v_mfma_f32_16x16x32_bf16 v[46:49], v[160:163], v[184:187], v[46:49]
	v_mfma_f32_16x16x32_bf16 v[38:41], v[152:155], v[192:195], v[38:41]
	v_mfma_f32_16x16x32_bf16 v[34:37], v[160:163], v[192:195], v[34:37]
	v_mfma_f32_16x16x32_bf16 v[22:25], v[152:155], v[200:203], v[22:25]
	v_mfma_f32_16x16x32_bf16 v[18:21], v[160:163], v[200:203], v[18:21]
	v_mfma_f32_16x16x32_bf16 v[6:9], v[152:155], v[208:211], v[6:9]
	v_mfma_f32_16x16x32_bf16 v[2:5], v[160:163], v[208:211], v[2:5]
	v_mfma_f32_16x16x32_bf16 v[30:33], v[164:167], v[180:183], v[30:33]
	v_mfma_f32_16x16x32_bf16 v[26:29], v[172:175], v[180:183], v[26:29]
	v_mfma_f32_16x16x32_bf16 v[14:17], v[164:167], v[188:191], v[14:17]
	v_mfma_f32_16x16x32_bf16 v[10:13], v[172:175], v[188:191], v[10:13]
	v_mfma_f32_16x16x32_bf16 v[58:61], v[164:167], v[196:199], v[58:61]
	v_mfma_f32_16x16x32_bf16 v[62:65], v[172:175], v[196:199], v[62:65]
	v_mfma_f32_16x16x32_bf16 v[42:45], v[164:167], v[204:207], v[42:45]
	v_mfma_f32_16x16x32_bf16 v[50:53], v[172:175], v[204:207], v[50:53]
	v_mfma_f32_16x16x32_bf16 v[30:33], v[168:171], v[184:187], v[30:33]
	v_mfma_f32_16x16x32_bf16 v[26:29], v[176:179], v[184:187], v[26:29]
	v_mfma_f32_16x16x32_bf16 v[14:17], v[168:171], v[192:195], v[14:17]
	v_mfma_f32_16x16x32_bf16 v[10:13], v[176:179], v[192:195], v[10:13]
	v_mfma_f32_16x16x32_bf16 v[58:61], v[168:171], v[200:203], v[58:61]
	v_mfma_f32_16x16x32_bf16 v[62:65], v[176:179], v[200:203], v[62:65]
	v_mfma_f32_16x16x32_bf16 v[42:45], v[168:171], v[208:211], v[42:45]
	v_mfma_f32_16x16x32_bf16 v[50:53], v[176:179], v[208:211], v[50:53]
	s_barrier
	s_setprio 0
	s_add_i32 s61, s61, 2
	s_add_u32 s36, s36, 0x100
	s_addc_u32 s37, s37, 0
	s_add_u32 s25, s25, 0x100
	s_addc_u32 s27, s27, 0
	s_cmp_gt_u32 s61, 29
	s_cbranch_scc0 .LBB0_427
	s_and_b64 vcc, exec, s[14:15]
	s_cbranch_vccz .LBB0_430
	s_barrier

; #define PG8_STAGE(bufoff, gbase, VO) do { _Pragma("unroll") for (int _i = 0; _i < 2; ++_i) \
;         __builtin_amdgcn_global_load_lds((const unsigned*)((const char*)(gbase) + VO[_i]), (LAS unsigned*)(lds + (bufoff) + ldsw + _i * 8192), 16, 0, 0); } while (0)
; #define PG8_LDA(dst, b, h) do { _Pragma("unroll") for (int m = 0; m < 4; ++m) _Pragma("unroll") for (int k = 0; k < 2; ++k) dst[m][k] = *(const LAS bf16x8*)(lds + PG8_SA(b, h) + aoff + m * 2048 + k * 1024); } while (0)
; #define PG8_LDB(dst, b, h) do { _Pragma("unroll") for (int n = 0; n < 2; ++n) _Pragma("unroll") for (int k = 0; k < 2; ++k) dst[n][k] = *(const LAS bf16x8*)(lds + PG8_SB(b, h) + boff + n * 2048 + k * 1024); } while (0)
; #define PG8_MMA(ai, bj, At, Bt) do { __builtin_amdgcn_s_setprio(1); _Pragma("unroll") for (int m = 0; m < 4; ++m) _Pragma("unroll") for (int n = 0; n < 2; ++n) _Pragma("unroll") for (int k = 0; k < 2; ++k) \
;         acc[ai][bj][m][n] = __builtin_amdgcn_mfma_f32_16x16x32_bf16(Bt[n][k], At[m][k], acc[ai][bj][m][n], 0, 0, 0); __builtin_amdgcn_s_setprio(0); } while (0)
; #define PG8_WAIT_V(n) asm volatile("s_waitcnt vmcnt(" #n ")" ::: "memory")
; #define PG8_WAIT_L(n) asm volatile("s_waitcnt lgkmcnt(" #n ")" ::: "memory")
; #define PG8_BAR __builtin_amdgcn_s_barrier()
; #define PG8_SCHED __builtin_amdgcn_sched_barrier(0)
; template <int NSEG, class Epi, bool ALIGN_EPI = PG8_ALIGN, bool SP2 = PG8_SP2>
; DI void gemm_phase(LAS unsigned char* lds, const Gemm g, const StaticOrder& S, const Epi& E) {
;     ...
;             PG8_LDB(B0, 0, 0); PG8_LDB(B1, 0, 1); PG8_SCHED; PG8_LDA(At, 0, 0); PG8_STAGE(PG8_SA(1, 1), a1 + hstepC, voffC);
;             PG8_WAIT_V(8); PG8_WAIT_L(0); PG8_BAR; PG8_MMA(0, 0, At, B0); PG8_MMA(0, 1, At, B1); PG8_BAR; PG8_SCHED;
;             PG8_LDA(At, 0, 1); PG8_STAGE(PG8_SB(0, 0), b2, v2); PG8_STAGE(PG8_SB(0, 1), b2 + h2, v2); PG8_STAGE(PG8_SA(0, 0), a2, v2);
.LBB0_501:
	ds_read_b128 v[148:151], v145
	ds_read_b128 v[152:155], v145 offset:1024
	ds_read_b128 v[156:159], v145 offset:2048
	ds_read_b128 v[160:163], v145 offset:3072
	ds_read_b128 v[164:167], v146
	ds_read_b128 v[168:171], v146 offset:1024
	ds_read_b128 v[172:175], v146 offset:2048
	ds_read_b128 v[176:179], v146 offset:3072
	s_add_u32 s24, s22, 0xfff80080
	s_addc_u32 s25, s23, -1
	s_cmp_eq_u32 s52, 28
	s_cselect_b32 s27, s5, s25
	s_cselect_b32 s26, s4, s24
	s_cselect_b32 s25, s21, s19
	s_cselect_b32 s24, s20, s17
	v_lshl_add_u64 v[212:213], s[22:23], 0, v[134:135]
	s_add_i32 m0, s15, 0xc000
	ds_read_b128 v[180:183], v147
	ds_read_b128 v[184:187], v147 offset:1024
	ds_read_b128 v[188:191], v147 offset:2048
	ds_read_b128 v[192:195], v147 offset:3072
	ds_read_b128 v[196:199], v147 offset:4096
	ds_read_b128 v[200:203], v147 offset:5120
	ds_read_b128 v[204:207], v147 offset:6144
	ds_read_b128 v[208:211], v147 offset:7168
	global_load_lds_dwordx4 v[212:213], off
	v_lshl_add_u64 v[212:213], s[22:23], 0, v[136:137]
	s_add_i32 m0, s15, 0xe000
	s_nop 0
	global_load_lds_dwordx4 v[212:213], off
	s_waitcnt vmcnt(8)
	s_waitcnt lgkmcnt(0)
	s_setprio 1
	s_barrier
	v_mfma_f32_16x16x32_bf16 v[126:129], v[148:151], v[180:183], v[126:129]
	v_mfma_f32_16x16x32_bf16 v[122:125], v[156:159], v[180:183], v[122:125]
	v_mfma_f32_16x16x32_bf16 v[118:121], v[148:151], v[188:191], v[118:121]
	v_mfma_f32_16x16x32_bf16 v[114:117], v[156:159], v[188:191], v[114:117]
	v_mfma_f32_16x16x32_bf16 v[102:105], v[148:151], v[196:199], v[102:105]
	v_mfma_f32_16x16x32_bf16 v[98:101], v[156:159], v[196:199], v[98:101]
	v_mfma_f32_16x16x32_bf16 v[86:89], v[148:151], v[204:207], v[86:89]
	v_mfma_f32_16x16x32_bf16 v[82:85], v[156:159], v[204:207], v[82:85]
	v_mfma_f32_16x16x32_bf16 v[126:129], v[152:155], v[184:187], v[126:129]
	v_mfma_f32_16x16x32_bf16 v[122:125], v[160:163], v[184:187], v[122:125]
	v_mfma_f32_16x16x32_bf16 v[118:121], v[152:155], v[192:195], v[118:121]
	v_mfma_f32_16x16x32_bf16 v[114:117], v[160:163], v[192:195], v[114:117]
	v_mfma_f32_16x16x32_bf16 v[102:105], v[152:155], v[200:203], v[102:105]
	v_mfma_f32_16x16x32_bf16 v[98:101], v[160:163], v[200:203], v[98:101]
	v_mfma_f32_16x16x32_bf16 v[86:89], v[152:155], v[208:211], v[86:89]
	v_mfma_f32_16x16x32_bf16 v[82:85], v[160:163], v[208:211], v[82:85]
	v_mfma_f32_16x16x32_bf16 v[110:113], v[164:167], v[180:183], v[110:113]
	v_mfma_f32_16x16x32_bf16 v[106:109], v[172:175], v[180:183], v[106:109]
	v_mfma_f32_16x16x32_bf16 v[94:97], v[164:167], v[188:191], v[94:97]
	v_mfma_f32_16x16x32_bf16 v[90:93], v[172:175], v[188:191], v[90:93]
	v_mfma_f32_16x16x32_bf16 v[78:81], v[164:167], v[196:199], v[78:81]
	v_mfma_f32_16x16x32_bf16 v[74:77], v[172:175], v[196:199], v[74:77]
	v_mfma_f32_16x16x32_bf16 v[70:73], v[164:167], v[204:207], v[70:73]
	v_mfma_f32_16x16x32_bf16 v[58:61], v[172:175], v[204:207], v[58:61]
	v_mfma_f32_16x16x32_bf16 v[110:113], v[168:171], v[184:187], v[110:113]
	v_mfma_f32_16x16x32_bf16 v[106:109], v[176:179], v[184:187], v[106:109]
	v_mfma_f32_16x16x32_bf16 v[94:97], v[168:171], v[192:195], v[94:97]
	v_mfma_f32_16x16x32_bf16 v[90:93], v[176:179], v[192:195], v[90:93]
	v_mfma_f32_16x16x32_bf16 v[78:81], v[168:171], v[200:203], v[78:81]
	v_mfma_f32_16x16x32_bf16 v[74:77], v[176:179], v[200:203], v[74:77]
	v_mfma_f32_16x16x32_bf16 v[70:73], v[168:171], v[208:211], v[70:73]
	v_mfma_f32_16x16x32_bf16 v[58:61], v[176:179], v[208:211], v[58:61]
	s_barrier
	s_setprio 0
	s_add_i32 s53, s48, s38
	v_lshl_add_u64 v[212:213], s[24:25], 0, v[130:131]
	s_mov_b32 m0, s53
	ds_read_b128 v[180:183], v147 offset:16384
	ds_read_b128 v[184:187], v147 offset:17408
	ds_read_b128 v[188:191], v147 offset:18432
	ds_read_b128 v[192:195], v147 offset:19456
	ds_read_b128 v[196:199], v147 offset:20480
	ds_read_b128 v[200:203], v147 offset:21504
	ds_read_b128 v[204:207], v147 offset:22528
	ds_read_b128 v[208:211], v147 offset:23552
	global_load_lds_dwordx4 v[212:213], off
	s_add_i32 m0, s53, 0x2000
	s_add_u32 s54, s24, 0x80000
	v_lshl_add_u64 v[214:215], s[24:25], 0, v[132:133]
	s_addc_u32 s55, s25, 0
	s_add_i32 s53, s49, s38
	global_load_lds_dwordx4 v[214:215], off
	v_lshl_add_u64 v[216:217], s[54:55], 0, v[130:131]
	s_mov_b32 m0, s53
	v_lshl_add_u64 v[218:219], s[26:27], 0, v[132:133]
	global_load_lds_dwordx4 v[216:217], off
	v_lshl_add_u64 v[216:217], s[54:55], 0, v[132:133]
	s_add_i32 m0, s53, 0x2000
	s_nop 0
	global_load_lds_dwordx4 v[216:217], off
	v_lshl_add_u64 v[216:217], s[26:27], 0, v[130:131]
	s_mov_b32 m0, s15
	s_nop 0
	global_load_lds_dwordx4 v[216:217], off
	s_mov_b32 m0, s41
	s_nop 0
	global_load_lds_dwordx4 v[218:219], off
	s_waitcnt vmcnt(8)
	s_waitcnt lgkmcnt(0)
	s_setprio 1
	s_barrier
; #define PG8_STAGE(bufoff, gbase, VO) do { _Pragma("unroll") for (int _i = 0; _i < 2; ++_i) \
;         __builtin_amdgcn_global_load_lds((const unsigned*)((const char*)(gbase) + VO[_i]), (LAS unsigned*)(lds + (bufoff) + ldsw + _i * 8192), 16, 0, 0); } while (0)
; #define PG8_LDA(dst, b, h) do { _Pragma("unroll") for (int m = 0; m < 4; ++m) _Pragma("unroll") for (int k = 0; k < 2; ++k) dst[m][k] = *(const LAS bf16x8*)(lds + PG8_SA(b, h) + aoff + m * 2048 + k * 1024); } while (0)
; #define PG8_LDB(dst, b, h) do { _Pragma("unroll") for (int n = 0; n < 2; ++n) _Pragma("unroll") for (int k = 0; k < 2; ++k) dst[n][k] = *(const LAS bf16x8*)(lds + PG8_SB(b, h) + boff + n * 2048 + k * 1024); } while (0)
; #define PG8_MMA(ai, bj, At, Bt) do { __builtin_amdgcn_s_setprio(1); _Pragma("unroll") for (int m = 0; m < 4; ++m) _Pragma("unroll") for (int n = 0; n < 2; ++n) _Pragma("unroll") for (int k = 0; k < 2; ++k) \
;         acc[ai][bj][m][n] = __builtin_amdgcn_mfma_f32_16x16x32_bf16(Bt[n][k], At[m][k], acc[ai][bj][m][n], 0, 0, 0); __builtin_amdgcn_s_setprio(0); } while (0)
; #define PG8_WAIT_V(n) asm volatile("s_waitcnt vmcnt(" #n ")" ::: "memory")
; #define PG8_WAIT_L(n) asm volatile("s_waitcnt lgkmcnt(" #n ")" ::: "memory")
; #define PG8_BAR __builtin_amdgcn_s_barrier()
; #define PG8_SCHED __builtin_amdgcn_sched_barrier(0)
; template <int NSEG, class Epi, bool ALIGN_EPI = PG8_ALIGN, bool SP2 = PG8_SP2>
; DI void gemm_phase(LAS unsigned char* lds, const Gemm g, const StaticOrder& S, const Epi& E) {
;     ...
;             PG8_WAIT_V(8); PG8_WAIT_L(0); PG8_BAR; PG8_MMA(1, 0, At, B0); PG8_MMA(1, 1, At, B1); PG8_BAR; PG8_SCHED;
;             PG8_LDB(B0, 1, 0); PG8_LDB(B1, 1, 1); PG8_SCHED; PG8_LDA(At, 1, 0); PG8_STAGE(PG8_SA(0, 1), a2 + h2, v2);
;             PG8_WAIT_V(8); PG8_WAIT_L(0); PG8_BAR; PG8_MMA(0, 0, At, B0); PG8_MMA(0, 1, At, B1); PG8_BAR; PG8_SCHED;
	v_mfma_f32_16x16x32_bf16 v[46:49], v[148:151], v[180:183], v[46:49]
	v_mfma_f32_16x16x32_bf16 v[42:45], v[156:159], v[180:183], v[42:45]
	v_mfma_f32_16x16x32_bf16 v[38:41], v[148:151], v[188:191], v[38:41]
	v_mfma_f32_16x16x32_bf16 v[34:37], v[156:159], v[188:191], v[34:37]
	v_mfma_f32_16x16x32_bf16 v[22:25], v[148:151], v[196:199], v[22:25]
	v_mfma_f32_16x16x32_bf16 v[18:21], v[156:159], v[196:199], v[18:21]
	v_mfma_f32_16x16x32_bf16 v[6:9], v[148:151], v[204:207], v[6:9]
	v_mfma_f32_16x16x32_bf16 v[2:5], v[156:159], v[204:207], v[2:5]
	v_mfma_f32_16x16x32_bf16 v[46:49], v[152:155], v[184:187], v[46:49]
	v_mfma_f32_16x16x32_bf16 v[42:45], v[160:163], v[184:187], v[42:45]
	v_mfma_f32_16x16x32_bf16 v[38:41], v[152:155], v[192:195], v[38:41]
	v_mfma_f32_16x16x32_bf16 v[34:37], v[160:163], v[192:195], v[34:37]
	v_mfma_f32_16x16x32_bf16 v[22:25], v[152:155], v[200:203], v[22:25]
	v_mfma_f32_16x16x32_bf16 v[18:21], v[160:163], v[200:203], v[18:21]
	v_mfma_f32_16x16x32_bf16 v[6:9], v[152:155], v[208:211], v[6:9]
	v_mfma_f32_16x16x32_bf16 v[2:5], v[160:163], v[208:211], v[2:5]
	v_mfma_f32_16x16x32_bf16 v[30:33], v[164:167], v[180:183], v[30:33]
	v_mfma_f32_16x16x32_bf16 v[26:29], v[172:175], v[180:183], v[26:29]
	v_mfma_f32_16x16x32_bf16 v[14:17], v[164:167], v[188:191], v[14:17]
	v_mfma_f32_16x16x32_bf16 v[10:13], v[172:175], v[188:191], v[10:13]
	v_mfma_f32_16x16x32_bf16 v[62:65], v[164:167], v[196:199], v[62:65]
	v_mfma_f32_16x16x32_bf16 v[66:69], v[172:175], v[196:199], v[66:69]
	v_mfma_f32_16x16x32_bf16 v[50:53], v[164:167], v[204:207], v[50:53]
	v_mfma_f32_16x16x32_bf16 v[54:57], v[172:175], v[204:207], v[54:57]
	v_mfma_f32_16x16x32_bf16 v[30:33], v[168:171], v[184:187], v[30:33]
	v_mfma_f32_16x16x32_bf16 v[26:29], v[176:179], v[184:187], v[26:29]
	v_mfma_f32_16x16x32_bf16 v[14:17], v[168:171], v[192:195], v[14:17]
	v_mfma_f32_16x16x32_bf16 v[10:13], v[176:179], v[192:195], v[10:13]
	v_mfma_f32_16x16x32_bf16 v[62:65], v[168:171], v[200:203], v[62:65]
	v_mfma_f32_16x16x32_bf16 v[66:69], v[176:179], v[200:203], v[66:69]
	v_mfma_f32_16x16x32_bf16 v[50:53], v[168:171], v[208:211], v[50:53]
	v_mfma_f32_16x16x32_bf16 v[54:57], v[176:179], v[208:211], v[54:57]
	s_barrier
	s_setprio 0
	s_add_i32 s53, 0, 0x18000
	s_add_i32 s54, 0, 0x1c000
	v_add_u32_e32 v160, s53, v143
	v_add_u32_e32 v176, s54, v143
	ds_read_b128 v[148:151], v160
	ds_read_b128 v[152:155], v160 offset:1024
	ds_read_b128 v[156:159], v160 offset:2048
	ds_read_b128 v[160:163], v160 offset:3072
	ds_read_b128 v[164:167], v176
	ds_read_b128 v[168:171], v176 offset:1024
	ds_read_b128 v[172:175], v176 offset:2048
	ds_read_b128 v[176:179], v176 offset:3072
	s_add_u32 s26, s26, 0x80000
	s_addc_u32 s27, s27, 0
	s_mov_b32 m0, s42
	v_lshl_add_u64 v[220:221], s[26:27], 0, v[130:131]
	ds_read_b128 v[180:183], v147 offset:32768
	ds_read_b128 v[184:187], v147 offset:33792
	ds_read_b128 v[188:191], v147 offset:34816
	ds_read_b128 v[192:195], v147 offset:35840
	ds_read_b128 v[196:199], v147 offset:36864
	ds_read_b128 v[200:203], v147 offset:37888
	ds_read_b128 v[204:207], v147 offset:38912
	ds_read_b128 v[208:211], v147 offset:39936
	global_load_lds_dwordx4 v[220:221], off
	v_lshl_add_u64 v[220:221], s[26:27], 0, v[132:133]
	s_mov_b32 m0, s43
	s_nop 0
	global_load_lds_dwordx4 v[220:221], off
	s_waitcnt vmcnt(8)
	s_waitcnt lgkmcnt(0)
	s_setprio 1
	s_barrier
	v_mfma_f32_16x16x32_bf16 v[126:129], v[148:151], v[180:183], v[126:129]
	v_mfma_f32_16x16x32_bf16 v[122:125], v[156:159], v[180:183], v[122:125]
	v_mfma_f32_16x16x32_bf16 v[118:121], v[148:151], v[188:191], v[118:121]
	v_mfma_f32_16x16x32_bf16 v[114:117], v[156:159], v[188:191], v[114:117]
	v_mfma_f32_16x16x32_bf16 v[102:105], v[148:151], v[196:199], v[102:105]
	v_mfma_f32_16x16x32_bf16 v[98:101], v[156:159], v[196:199], v[98:101]
	v_mfma_f32_16x16x32_bf16 v[86:89], v[148:151], v[204:207], v[86:89]
	v_mfma_f32_16x16x32_bf16 v[82:85], v[156:159], v[204:207], v[82:85]
	v_mfma_f32_16x16x32_bf16 v[126:129], v[152:155], v[184:187], v[126:129]
	v_mfma_f32_16x16x32_bf16 v[122:125], v[160:163], v[184:187], v[122:125]
	v_mfma_f32_16x16x32_bf16 v[118:121], v[152:155], v[192:195], v[118:121]
	v_mfma_f32_16x16x32_bf16 v[114:117], v[160:163], v[192:195], v[114:117]
	v_mfma_f32_16x16x32_bf16 v[102:105], v[152:155], v[200:203], v[102:105]
	v_mfma_f32_16x16x32_bf16 v[98:101], v[160:163], v[200:203], v[98:101]
	v_mfma_f32_16x16x32_bf16 v[86:89], v[152:155], v[208:211], v[86:89]
	v_mfma_f32_16x16x32_bf16 v[82:85], v[160:163], v[208:211], v[82:85]
	v_mfma_f32_16x16x32_bf16 v[110:113], v[164:167], v[180:183], v[110:113]
	v_mfma_f32_16x16x32_bf16 v[106:109], v[172:175], v[180:183], v[106:109]
	v_mfma_f32_16x16x32_bf16 v[94:97], v[164:167], v[188:191], v[94:97]
	v_mfma_f32_16x16x32_bf16 v[90:93], v[172:175], v[188:191], v[90:93]
	v_mfma_f32_16x16x32_bf16 v[78:81], v[164:167], v[196:199], v[78:81]
	v_mfma_f32_16x16x32_bf16 v[74:77], v[172:175], v[196:199], v[74:77]
	v_mfma_f32_16x16x32_bf16 v[70:73], v[164:167], v[204:207], v[70:73]
	v_mfma_f32_16x16x32_bf16 v[58:61], v[172:175], v[204:207], v[58:61]
	v_mfma_f32_16x16x32_bf16 v[110:113], v[168:171], v[184:187], v[110:113]
	v_mfma_f32_16x16x32_bf16 v[106:109], v[176:179], v[184:187], v[106:109]
	v_mfma_f32_16x16x32_bf16 v[94:97], v[168:171], v[192:195], v[94:97]
	v_mfma_f32_16x16x32_bf16 v[90:93], v[176:179], v[192:195], v[90:93]
	v_mfma_f32_16x16x32_bf16 v[78:81], v[168:171], v[200:203], v[78:81]
	v_mfma_f32_16x16x32_bf16 v[74:77], v[176:179], v[200:203], v[74:77]
	v_mfma_f32_16x16x32_bf16 v[70:73], v[168:171], v[208:211], v[70:73]
	v_mfma_f32_16x16x32_bf16 v[58:61], v[176:179], v[208:211], v[58:61]
	s_barrier
; #define PG8_STAGE(bufoff, gbase, VO) do { _Pragma("unroll") for (int _i = 0; _i < 2; ++_i) \
;         __builtin_amdgcn_global_load_lds((const unsigned*)((const char*)(gbase) + VO[_i]), (LAS unsigned*)(lds + (bufoff) + ldsw + _i * 8192), 16, 0, 0); } while (0)
; #define PG8_LDA(dst, b, h) do { _Pragma("unroll") for (int m = 0; m < 4; ++m) _Pragma("unroll") for (int k = 0; k < 2; ++k) dst[m][k] = *(const LAS bf16x8*)(lds + PG8_SA(b, h) + aoff + m * 2048 + k * 1024); } while (0)
; #define PG8_MMA(ai, bj, At, Bt) do { __builtin_amdgcn_s_setprio(1); _Pragma("unroll") for (int m = 0; m < 4; ++m) _Pragma("unroll") for (int n = 0; n < 2; ++n) _Pragma("unroll") for (int k = 0; k < 2; ++k) \
;         acc[ai][bj][m][n] = __builtin_amdgcn_mfma_f32_16x16x32_bf16(Bt[n][k], At[m][k], acc[ai][bj][m][n], 0, 0, 0); __builtin_amdgcn_s_setprio(0); } while (0)
; #define PG8_WAIT_V(n) asm volatile("s_waitcnt vmcnt(" #n ")" ::: "memory")
; #define PG8_WAIT_L(n) asm volatile("s_waitcnt lgkmcnt(" #n ")" ::: "memory")
; #define PG8_BAR __builtin_amdgcn_s_barrier()
; #define PG8_SCHED __builtin_amdgcn_sched_barrier(0)
; template <int NSEG, class Epi, bool ALIGN_EPI = PG8_ALIGN, bool SP2 = PG8_SP2>
; DI void gemm_phase(LAS unsigned char* lds, const Gemm g, const StaticOrder& S, const Epi& E) {
;     ...
;             PG8_LDA(At, 1, 1); PG8_STAGE(PG8_SB(1, 0), b3, v2); PG8_STAGE(PG8_SB(1, 1), b3 + h2, v2); PG8_STAGE(PG8_SA(1, 0), a3, v2);
;             PG8_WAIT_V(8); PG8_WAIT_L(0); PG8_BAR; PG8_MMA(1, 0, At, B0); PG8_MMA(1, 1, At, B1); PG8_BAR; PG8_SCHED;
	s_setprio 0
	s_add_i32 s26, s53, s38
	v_lshl_add_u64 v[212:213], v[212:213], 0, s[10:11]
	s_mov_b32 m0, s26
	ds_read_b128 v[180:183], v147 offset:49152
	ds_read_b128 v[184:187], v147 offset:50176
	ds_read_b128 v[188:191], v147 offset:51200
	ds_read_b128 v[192:195], v147 offset:52224
	ds_read_b128 v[196:199], v147 offset:53248
	ds_read_b128 v[200:203], v147 offset:54272
	ds_read_b128 v[204:207], v147 offset:55296
	ds_read_b128 v[208:211], v147 offset:56320
	global_load_lds_dwordx4 v[212:213], off
	s_add_i32 m0, s26, 0x2000
	s_add_u32 s24, s24, 0x80080
	v_lshl_add_u64 v[212:213], v[214:215], 0, s[10:11]
	s_addc_u32 s25, s25, 0
	s_add_i32 s26, s54, s38
	global_load_lds_dwordx4 v[212:213], off
	v_lshl_add_u64 v[212:213], s[24:25], 0, v[130:131]
	s_mov_b32 m0, s26
	s_nop 0
	global_load_lds_dwordx4 v[212:213], off
	v_lshl_add_u64 v[212:213], s[24:25], 0, v[132:133]
	s_add_i32 m0, s26, 0x2000
	s_nop 0
	global_load_lds_dwordx4 v[212:213], off
	v_lshl_add_u64 v[212:213], v[216:217], 0, s[10:11]
	s_mov_b32 m0, s46
	s_nop 0
	global_load_lds_dwordx4 v[212:213], off
	v_lshl_add_u64 v[212:213], v[218:219], 0, s[10:11]
	s_mov_b32 m0, s47
	s_nop 0
	global_load_lds_dwordx4 v[212:213], off
	s_waitcnt vmcnt(8)
	s_waitcnt lgkmcnt(0)
	s_setprio 1
	s_barrier
	v_mfma_f32_16x16x32_bf16 v[46:49], v[148:151], v[180:183], v[46:49]
	v_mfma_f32_16x16x32_bf16 v[42:45], v[156:159], v[180:183], v[42:45]
	v_mfma_f32_16x16x32_bf16 v[38:41], v[148:151], v[188:191], v[38:41]
	v_mfma_f32_16x16x32_bf16 v[34:37], v[156:159], v[188:191], v[34:37]
	v_mfma_f32_16x16x32_bf16 v[22:25], v[148:151], v[196:199], v[22:25]
	v_mfma_f32_16x16x32_bf16 v[18:21], v[156:159], v[196:199], v[18:21]
	v_mfma_f32_16x16x32_bf16 v[6:9], v[148:151], v[204:207], v[6:9]
	v_mfma_f32_16x16x32_bf16 v[2:5], v[156:159], v[204:207], v[2:5]
	v_mfma_f32_16x16x32_bf16 v[46:49], v[152:155], v[184:187], v[46:49]
	v_mfma_f32_16x16x32_bf16 v[42:45], v[160:163], v[184:187], v[42:45]
	v_mfma_f32_16x16x32_bf16 v[38:41], v[152:155], v[192:195], v[38:41]
	v_mfma_f32_16x16x32_bf16 v[34:37], v[160:163], v[192:195], v[34:37]
	v_mfma_f32_16x16x32_bf16 v[22:25], v[152:155], v[200:203], v[22:25]
	v_mfma_f32_16x16x32_bf16 v[18:21], v[160:163], v[200:203], v[18:21]
	v_mfma_f32_16x16x32_bf16 v[6:9], v[152:155], v[208:211], v[6:9]
	v_mfma_f32_16x16x32_bf16 v[2:5], v[160:163], v[208:211], v[2:5]
	v_mfma_f32_16x16x32_bf16 v[30:33], v[164:167], v[180:183], v[30:33]
	v_mfma_f32_16x16x32_bf16 v[26:29], v[172:175], v[180:183], v[26:29]
	v_mfma_f32_16x16x32_bf16 v[14:17], v[164:167], v[188:191], v[14:17]
	v_mfma_f32_16x16x32_bf16 v[10:13], v[172:175], v[188:191], v[10:13]
	v_mfma_f32_16x16x32_bf16 v[62:65], v[164:167], v[196:199], v[62:65]
	v_mfma_f32_16x16x32_bf16 v[66:69], v[172:175], v[196:199], v[66:69]
	v_mfma_f32_16x16x32_bf16 v[50:53], v[164:167], v[204:207], v[50:53]
	v_mfma_f32_16x16x32_bf16 v[54:57], v[172:175], v[204:207], v[54:57]
	v_mfma_f32_16x16x32_bf16 v[30:33], v[168:171], v[184:187], v[30:33]
	v_mfma_f32_16x16x32_bf16 v[26:29], v[176:179], v[184:187], v[26:29]
	v_mfma_f32_16x16x32_bf16 v[14:17], v[168:171], v[192:195], v[14:17]
	v_mfma_f32_16x16x32_bf16 v[10:13], v[176:179], v[192:195], v[10:13]
	v_mfma_f32_16x16x32_bf16 v[62:65], v[168:171], v[200:203], v[62:65]
	v_mfma_f32_16x16x32_bf16 v[66:69], v[176:179], v[200:203], v[66:69]
	v_mfma_f32_16x16x32_bf16 v[50:53], v[168:171], v[208:211], v[50:53]
	v_mfma_f32_16x16x32_bf16 v[54:57], v[176:179], v[208:211], v[54:57]
	s_barrier
	s_setprio 0
	s_add_i32 s52, s52, 2
	s_add_u32 s22, s22, 0x100
	s_addc_u32 s23, s23, 0
	s_add_u32 s17, s17, 0x100
	s_addc_u32 s19, s19, 0
	s_cmp_gt_u32 s52, 29
	s_cbranch_scc0 .LBB0_501
	s_and_b64 vcc, exec, s[12:13]
	s_cbranch_vccz .LBB0_504
	s_barrier

; #define PG8_STAGE(bufoff, gbase, VO) do { _Pragma("unroll") for (int _i = 0; _i < 2; ++_i) \
;         __builtin_amdgcn_global_load_lds((const unsigned*)((const char*)(gbase) + VO[_i]), (LAS unsigned*)(lds + (bufoff) + ldsw + _i * 8192), 16, 0, 0); } while (0)
; #define PG8_LDA(dst, b, h) do { _Pragma("unroll") for (int m = 0; m < 4; ++m) _Pragma("unroll") for (int k = 0; k < 2; ++k) dst[m][k] = *(const LAS bf16x8*)(lds + PG8_SA(b, h) + aoff + m * 2048 + k * 1024); } while (0)
; #define PG8_LDB(dst, b, h) do { _Pragma("unroll") for (int n = 0; n < 2; ++n) _Pragma("unroll") for (int k = 0; k < 2; ++k) dst[n][k] = *(const LAS bf16x8*)(lds + PG8_SB(b, h) + boff + n * 2048 + k * 1024); } while (0)
; #define PG8_MMA(ai, bj, At, Bt) do { __builtin_amdgcn_s_setprio(1); _Pragma("unroll") for (int m = 0; m < 4; ++m) _Pragma("unroll") for (int n = 0; n < 2; ++n) _Pragma("unroll") for (int k = 0; k < 2; ++k) \
;         acc[ai][bj][m][n] = __builtin_amdgcn_mfma_f32_16x16x32_bf16(Bt[n][k], At[m][k], acc[ai][bj][m][n], 0, 0, 0); __builtin_amdgcn_s_setprio(0); } while (0)
; #define PG8_WAIT_V(n) asm volatile("s_waitcnt vmcnt(" #n ")" ::: "memory")
; #define PG8_WAIT_L(n) asm volatile("s_waitcnt lgkmcnt(" #n ")" ::: "memory")
; #define PG8_BAR __builtin_amdgcn_s_barrier()
; #define PG8_SCHED __builtin_amdgcn_sched_barrier(0)
; template <int NSEG, class Epi, bool ALIGN_EPI = PG8_ALIGN, bool SP2 = PG8_SP2>
; DI void gemm_phase(LAS unsigned char* lds, const Gemm g, const StaticOrder& S, const Epi& E) {
;     ...
;             PG8_LDB(B0, 0, 0); PG8_LDB(B1, 0, 1); PG8_SCHED; PG8_LDA(At, 0, 0); PG8_STAGE(PG8_SA(1, 1), a1 + hstepC, voffC);
;             PG8_WAIT_V(8); PG8_WAIT_L(0); PG8_BAR; PG8_MMA(0, 0, At, B0); PG8_MMA(0, 1, At, B1); PG8_BAR; PG8_SCHED;
;             PG8_LDA(At, 0, 1); PG8_STAGE(PG8_SB(0, 0), b2, v2); PG8_STAGE(PG8_SB(0, 1), b2 + h2, v2); PG8_STAGE(PG8_SA(0, 0), a2, v2);
.LBB0_545:
	ds_read_b128 v[102:105], v207
	ds_read_b128 v[106:109], v207 offset:1024
	ds_read_b128 v[110:113], v207 offset:2048
	ds_read_b128 v[114:117], v207 offset:3072
	ds_read_b128 v[118:121], v208
	ds_read_b128 v[122:125], v208 offset:1024
	ds_read_b128 v[126:129], v208 offset:2048
	ds_read_b128 v[130:133], v208 offset:3072
	s_add_u32 s34, s4, 0xfff80080
	s_addc_u32 s35, s5, -1
	s_cmp_eq_u32 s67, 28
	s_cselect_b32 s39, s1, s35
	s_cselect_b32 s38, s25, s34
	s_cselect_b32 s35, s27, s66
	s_cselect_b32 s34, s64, s65
	v_lshl_add_u64 v[204:205], s[4:5], 0, v[178:179]
	s_add_i32 m0, s3, 0xc000
	ds_read_b128 v[162:165], v209
	ds_read_b128 v[166:169], v209 offset:1024
	ds_read_b128 v[170:173], v209 offset:2048
	ds_read_b128 v[188:191], v209 offset:3072
	ds_read_b128 v[192:195], v209 offset:4096
	ds_read_b128 v[196:199], v209 offset:5120
	ds_read_b128 v[200:203], v209 offset:6144
	ds_read_b128 v[212:215], v209 offset:7168
	global_load_lds_dwordx4 v[204:205], off
	v_lshl_add_u64 v[204:205], s[4:5], 0, v[180:181]
	s_add_i32 m0, s3, 0xe000
	s_nop 0
	global_load_lds_dwordx4 v[204:205], off
	s_waitcnt vmcnt(8)
	s_waitcnt lgkmcnt(0)
	s_setprio 1
	s_barrier
	v_mfma_f32_16x16x32_bf16 v[158:161], v[102:105], v[162:165], v[158:161]
	v_mfma_f32_16x16x32_bf16 v[154:157], v[110:113], v[162:165], v[154:157]
	v_mfma_f32_16x16x32_bf16 v[150:153], v[102:105], v[170:173], v[150:153]
	v_mfma_f32_16x16x32_bf16 v[146:149], v[110:113], v[170:173], v[146:149]
	v_mfma_f32_16x16x32_bf16 v[142:145], v[102:105], v[192:195], v[142:145]
	v_mfma_f32_16x16x32_bf16 v[138:141], v[110:113], v[192:195], v[138:141]
	v_mfma_f32_16x16x32_bf16 v[134:137], v[102:105], v[200:203], v[134:137]
	v_mfma_f32_16x16x32_bf16 v[98:101], v[110:113], v[200:203], v[98:101]
	v_mfma_f32_16x16x32_bf16 v[158:161], v[106:109], v[166:169], v[158:161]
	v_mfma_f32_16x16x32_bf16 v[154:157], v[114:117], v[166:169], v[154:157]
	v_mfma_f32_16x16x32_bf16 v[150:153], v[106:109], v[188:191], v[150:153]
	v_mfma_f32_16x16x32_bf16 v[146:149], v[114:117], v[188:191], v[146:149]
	v_mfma_f32_16x16x32_bf16 v[142:145], v[106:109], v[196:199], v[142:145]
	v_mfma_f32_16x16x32_bf16 v[138:141], v[114:117], v[196:199], v[138:141]
	v_mfma_f32_16x16x32_bf16 v[134:137], v[106:109], v[212:215], v[134:137]
	v_mfma_f32_16x16x32_bf16 v[98:101], v[114:117], v[212:215], v[98:101]
	v_mfma_f32_16x16x32_bf16 v[62:65], v[118:121], v[162:165], v[62:65]
	v_mfma_f32_16x16x32_bf16 v[58:61], v[126:129], v[162:165], v[58:61]
	v_mfma_f32_16x16x32_bf16 v[54:57], v[118:121], v[170:173], v[54:57]
	v_mfma_f32_16x16x32_bf16 v[50:53], v[126:129], v[170:173], v[50:53]
	v_mfma_f32_16x16x32_bf16 v[46:49], v[118:121], v[192:195], v[46:49]
	v_mfma_f32_16x16x32_bf16 v[42:45], v[126:129], v[192:195], v[42:45]
	v_mfma_f32_16x16x32_bf16 v[38:41], v[118:121], v[200:203], v[38:41]
	v_mfma_f32_16x16x32_bf16 v[34:37], v[126:129], v[200:203], v[34:37]
	v_mfma_f32_16x16x32_bf16 v[62:65], v[122:125], v[166:169], v[62:65]
	v_mfma_f32_16x16x32_bf16 v[58:61], v[130:133], v[166:169], v[58:61]
	v_mfma_f32_16x16x32_bf16 v[54:57], v[122:125], v[188:191], v[54:57]
	v_mfma_f32_16x16x32_bf16 v[50:53], v[130:133], v[188:191], v[50:53]
	v_mfma_f32_16x16x32_bf16 v[46:49], v[122:125], v[196:199], v[46:49]
	v_mfma_f32_16x16x32_bf16 v[42:45], v[130:133], v[196:199], v[42:45]
	v_mfma_f32_16x16x32_bf16 v[38:41], v[122:125], v[212:215], v[38:41]
	v_mfma_f32_16x16x32_bf16 v[34:37], v[130:133], v[212:215], v[34:37]
	s_barrier
	s_setprio 0
	s_add_i32 s68, s58, s50
	v_lshl_add_u64 v[204:205], s[34:35], 0, v[174:175]
	s_mov_b32 m0, s68
	ds_read_b128 v[162:165], v209 offset:16384
	ds_read_b128 v[166:169], v209 offset:17408
	ds_read_b128 v[170:173], v209 offset:18432
	ds_read_b128 v[188:191], v209 offset:19456
	ds_read_b128 v[192:195], v209 offset:20480
	ds_read_b128 v[196:199], v209 offset:21504
	ds_read_b128 v[200:203], v209 offset:22528
	ds_read_b128 v[212:215], v209 offset:23552
	global_load_lds_dwordx4 v[204:205], off
	s_add_i32 m0, s68, 0x2000
	s_add_u32 s68, s34, 0x80000
	v_lshl_add_u64 v[216:217], s[34:35], 0, v[176:177]
	s_addc_u32 s69, s35, 0
	s_add_i32 s70, s59, s50
	global_load_lds_dwordx4 v[216:217], off
	v_lshl_add_u64 v[218:219], s[68:69], 0, v[174:175]
	s_mov_b32 m0, s70
	v_lshl_add_u64 v[220:221], s[38:39], 0, v[176:177]
	global_load_lds_dwordx4 v[218:219], off
	v_lshl_add_u64 v[218:219], s[68:69], 0, v[176:177]
	s_add_i32 m0, s70, 0x2000
	s_nop 0
	global_load_lds_dwordx4 v[218:219], off
	v_lshl_add_u64 v[218:219], s[38:39], 0, v[174:175]
	s_mov_b32 m0, s3
	s_nop 0
	global_load_lds_dwordx4 v[218:219], off
	s_mov_b32 m0, s52
	s_nop 0
	global_load_lds_dwordx4 v[220:221], off
	s_waitcnt vmcnt(8)
	s_waitcnt lgkmcnt(0)
	s_setprio 1
	s_barrier
; #define PG8_STAGE(bufoff, gbase, VO) do { _Pragma("unroll") for (int _i = 0; _i < 2; ++_i) \
;         __builtin_amdgcn_global_load_lds((const unsigned*)((const char*)(gbase) + VO[_i]), (LAS unsigned*)(lds + (bufoff) + ldsw + _i * 8192), 16, 0, 0); } while (0)
; #define PG8_LDA(dst, b, h) do { _Pragma("unroll") for (int m = 0; m < 4; ++m) _Pragma("unroll") for (int k = 0; k < 2; ++k) dst[m][k] = *(const LAS bf16x8*)(lds + PG8_SA(b, h) + aoff + m * 2048 + k * 1024); } while (0)
; #define PG8_LDB(dst, b, h) do { _Pragma("unroll") for (int n = 0; n < 2; ++n) _Pragma("unroll") for (int k = 0; k < 2; ++k) dst[n][k] = *(const LAS bf16x8*)(lds + PG8_SB(b, h) + boff + n * 2048 + k * 1024); } while (0)
; #define PG8_MMA(ai, bj, At, Bt) do { __builtin_amdgcn_s_setprio(1); _Pragma("unroll") for (int m = 0; m < 4; ++m) _Pragma("unroll") for (int n = 0; n < 2; ++n) _Pragma("unroll") for (int k = 0; k < 2; ++k) \
;         acc[ai][bj][m][n] = __builtin_amdgcn_mfma_f32_16x16x32_bf16(Bt[n][k], At[m][k], acc[ai][bj][m][n], 0, 0, 0); __builtin_amdgcn_s_setprio(0); } while (0)
; #define PG8_WAIT_V(n) asm volatile("s_waitcnt vmcnt(" #n ")" ::: "memory")
; #define PG8_WAIT_L(n) asm volatile("s_waitcnt lgkmcnt(" #n ")" ::: "memory")
; #define PG8_BAR __builtin_amdgcn_s_barrier()
; #define PG8_SCHED __builtin_amdgcn_sched_barrier(0)
; template <int NSEG, class Epi, bool ALIGN_EPI = PG8_ALIGN, bool SP2 = PG8_SP2>
; DI void gemm_phase(LAS unsigned char* lds, const Gemm g, const StaticOrder& S, const Epi& E) {
;     ...
;             PG8_WAIT_V(8); PG8_WAIT_L(0); PG8_BAR; PG8_MMA(1, 0, At, B0); PG8_MMA(1, 1, At, B1); PG8_BAR; PG8_SCHED;
;             PG8_LDB(B0, 1, 0); PG8_LDB(B1, 1, 1); PG8_SCHED; PG8_LDA(At, 1, 0); PG8_STAGE(PG8_SA(0, 1), a2 + h2, v2);
;             PG8_WAIT_V(8); PG8_WAIT_L(0); PG8_BAR; PG8_MMA(0, 0, At, B0); PG8_MMA(0, 1, At, B1); PG8_BAR; PG8_SCHED;
	v_mfma_f32_16x16x32_bf16 v[94:97], v[102:105], v[162:165], v[94:97]
	v_mfma_f32_16x16x32_bf16 v[90:93], v[110:113], v[162:165], v[90:93]
	v_mfma_f32_16x16x32_bf16 v[86:89], v[102:105], v[170:173], v[86:89]
	v_mfma_f32_16x16x32_bf16 v[82:85], v[110:113], v[170:173], v[82:85]
	v_mfma_f32_16x16x32_bf16 v[78:81], v[102:105], v[192:195], v[78:81]
	v_mfma_f32_16x16x32_bf16 v[74:77], v[110:113], v[192:195], v[74:77]
	v_mfma_f32_16x16x32_bf16 v[70:73], v[102:105], v[200:203], v[70:73]
	v_mfma_f32_16x16x32_bf16 v[66:69], v[110:113], v[200:203], v[66:69]
	v_mfma_f32_16x16x32_bf16 v[94:97], v[106:109], v[166:169], v[94:97]
	v_mfma_f32_16x16x32_bf16 v[90:93], v[114:117], v[166:169], v[90:93]
	v_mfma_f32_16x16x32_bf16 v[86:89], v[106:109], v[188:191], v[86:89]
	v_mfma_f32_16x16x32_bf16 v[82:85], v[114:117], v[188:191], v[82:85]
	v_mfma_f32_16x16x32_bf16 v[78:81], v[106:109], v[196:199], v[78:81]
	v_mfma_f32_16x16x32_bf16 v[74:77], v[114:117], v[196:199], v[74:77]
	v_mfma_f32_16x16x32_bf16 v[70:73], v[106:109], v[212:215], v[70:73]
	v_mfma_f32_16x16x32_bf16 v[66:69], v[114:117], v[212:215], v[66:69]
	v_mfma_f32_16x16x32_bf16 v[30:33], v[118:121], v[162:165], v[30:33]
	v_mfma_f32_16x16x32_bf16 v[26:29], v[126:129], v[162:165], v[26:29]
	v_mfma_f32_16x16x32_bf16 v[22:25], v[118:121], v[170:173], v[22:25]
	v_mfma_f32_16x16x32_bf16 v[14:17], v[126:129], v[170:173], v[14:17]
	v_mfma_f32_16x16x32_bf16 v[18:21], v[118:121], v[192:195], v[18:21]
	v_mfma_f32_16x16x32_bf16 v[10:13], v[126:129], v[192:195], v[10:13]
	v_mfma_f32_16x16x32_bf16 v[6:9], v[118:121], v[200:203], v[6:9]
	v_mfma_f32_16x16x32_bf16 v[2:5], v[126:129], v[200:203], v[2:5]
	v_mfma_f32_16x16x32_bf16 v[30:33], v[122:125], v[166:169], v[30:33]
	v_mfma_f32_16x16x32_bf16 v[26:29], v[130:133], v[166:169], v[26:29]
	v_mfma_f32_16x16x32_bf16 v[22:25], v[122:125], v[188:191], v[22:25]
	v_mfma_f32_16x16x32_bf16 v[14:17], v[130:133], v[188:191], v[14:17]
	v_mfma_f32_16x16x32_bf16 v[18:21], v[122:125], v[196:199], v[18:21]
	v_mfma_f32_16x16x32_bf16 v[10:13], v[130:133], v[196:199], v[10:13]
	v_mfma_f32_16x16x32_bf16 v[6:9], v[122:125], v[212:215], v[6:9]
	v_mfma_f32_16x16x32_bf16 v[2:5], v[130:133], v[212:215], v[2:5]
	s_barrier
	s_setprio 0
	s_add_i32 s68, 0, 0x18000
	s_add_i32 s69, 0, 0x1c000
	v_add_u32_e32 v114, s68, v187
	v_add_u32_e32 v130, s69, v187
	ds_read_b128 v[102:105], v114
	ds_read_b128 v[106:109], v114 offset:1024
	ds_read_b128 v[110:113], v114 offset:2048
	ds_read_b128 v[114:117], v114 offset:3072
	ds_read_b128 v[118:121], v130
	ds_read_b128 v[122:125], v130 offset:1024
	ds_read_b128 v[126:129], v130 offset:2048
	ds_read_b128 v[130:133], v130 offset:3072
	s_add_u32 s38, s38, 0x80000
	s_addc_u32 s39, s39, 0
	s_mov_b32 m0, s53
	v_lshl_add_u64 v[222:223], s[38:39], 0, v[174:175]
	ds_read_b128 v[162:165], v209 offset:32768
	ds_read_b128 v[166:169], v209 offset:33792
	ds_read_b128 v[170:173], v209 offset:34816
	ds_read_b128 v[188:191], v209 offset:35840
	ds_read_b128 v[192:195], v209 offset:36864
	ds_read_b128 v[196:199], v209 offset:37888
	ds_read_b128 v[200:203], v209 offset:38912
	ds_read_b128 v[212:215], v209 offset:39936
	global_load_lds_dwordx4 v[222:223], off
	v_lshl_add_u64 v[222:223], s[38:39], 0, v[176:177]
	s_mov_b32 m0, s54
	s_nop 0
	global_load_lds_dwordx4 v[222:223], off
	s_waitcnt vmcnt(8)
	s_waitcnt lgkmcnt(0)
	s_setprio 1
	s_barrier
	v_mfma_f32_16x16x32_bf16 v[158:161], v[102:105], v[162:165], v[158:161]
	v_mfma_f32_16x16x32_bf16 v[154:157], v[110:113], v[162:165], v[154:157]
	v_mfma_f32_16x16x32_bf16 v[150:153], v[102:105], v[170:173], v[150:153]
	v_mfma_f32_16x16x32_bf16 v[146:149], v[110:113], v[170:173], v[146:149]
	v_mfma_f32_16x16x32_bf16 v[142:145], v[102:105], v[192:195], v[142:145]
	v_mfma_f32_16x16x32_bf16 v[138:141], v[110:113], v[192:195], v[138:141]
	v_mfma_f32_16x16x32_bf16 v[134:137], v[102:105], v[200:203], v[134:137]
	v_mfma_f32_16x16x32_bf16 v[98:101], v[110:113], v[200:203], v[98:101]
	v_mfma_f32_16x16x32_bf16 v[158:161], v[106:109], v[166:169], v[158:161]
	v_mfma_f32_16x16x32_bf16 v[154:157], v[114:117], v[166:169], v[154:157]
	v_mfma_f32_16x16x32_bf16 v[150:153], v[106:109], v[188:191], v[150:153]
	v_mfma_f32_16x16x32_bf16 v[146:149], v[114:117], v[188:191], v[146:149]
	v_mfma_f32_16x16x32_bf16 v[142:145], v[106:109], v[196:199], v[142:145]
	v_mfma_f32_16x16x32_bf16 v[138:141], v[114:117], v[196:199], v[138:141]
	v_mfma_f32_16x16x32_bf16 v[134:137], v[106:109], v[212:215], v[134:137]
	v_mfma_f32_16x16x32_bf16 v[98:101], v[114:117], v[212:215], v[98:101]
	v_mfma_f32_16x16x32_bf16 v[62:65], v[118:121], v[162:165], v[62:65]
	v_mfma_f32_16x16x32_bf16 v[58:61], v[126:129], v[162:165], v[58:61]
	v_mfma_f32_16x16x32_bf16 v[54:57], v[118:121], v[170:173], v[54:57]
	v_mfma_f32_16x16x32_bf16 v[50:53], v[126:129], v[170:173], v[50:53]
	v_mfma_f32_16x16x32_bf16 v[46:49], v[118:121], v[192:195], v[46:49]
	v_mfma_f32_16x16x32_bf16 v[42:45], v[126:129], v[192:195], v[42:45]
	v_mfma_f32_16x16x32_bf16 v[38:41], v[118:121], v[200:203], v[38:41]
	v_mfma_f32_16x16x32_bf16 v[34:37], v[126:129], v[200:203], v[34:37]
	v_mfma_f32_16x16x32_bf16 v[62:65], v[122:125], v[166:169], v[62:65]
	v_mfma_f32_16x16x32_bf16 v[58:61], v[130:133], v[166:169], v[58:61]
	v_mfma_f32_16x16x32_bf16 v[54:57], v[122:125], v[188:191], v[54:57]
	v_mfma_f32_16x16x32_bf16 v[50:53], v[130:133], v[188:191], v[50:53]
	v_mfma_f32_16x16x32_bf16 v[46:49], v[122:125], v[196:199], v[46:49]
	v_mfma_f32_16x16x32_bf16 v[42:45], v[130:133], v[196:199], v[42:45]
	v_mfma_f32_16x16x32_bf16 v[38:41], v[122:125], v[212:215], v[38:41]
	v_mfma_f32_16x16x32_bf16 v[34:37], v[130:133], v[212:215], v[34:37]
	s_barrier
; #define PG8_STAGE(bufoff, gbase, VO) do { _Pragma("unroll") for (int _i = 0; _i < 2; ++_i) \
;         __builtin_amdgcn_global_load_lds((const unsigned*)((const char*)(gbase) + VO[_i]), (LAS unsigned*)(lds + (bufoff) + ldsw + _i * 8192), 16, 0, 0); } while (0)
; #define PG8_LDA(dst, b, h) do { _Pragma("unroll") for (int m = 0; m < 4; ++m) _Pragma("unroll") for (int k = 0; k < 2; ++k) dst[m][k] = *(const LAS bf16x8*)(lds + PG8_SA(b, h) + aoff + m * 2048 + k * 1024); } while (0)
; #define PG8_MMA(ai, bj, At, Bt) do { __builtin_amdgcn_s_setprio(1); _Pragma("unroll") for (int m = 0; m < 4; ++m) _Pragma("unroll") for (int n = 0; n < 2; ++n) _Pragma("unroll") for (int k = 0; k < 2; ++k) \
;         acc[ai][bj][m][n] = __builtin_amdgcn_mfma_f32_16x16x32_bf16(Bt[n][k], At[m][k], acc[ai][bj][m][n], 0, 0, 0); __builtin_amdgcn_s_setprio(0); } while (0)
; #define PG8_WAIT_V(n) asm volatile("s_waitcnt vmcnt(" #n ")" ::: "memory")
; #define PG8_WAIT_L(n) asm volatile("s_waitcnt lgkmcnt(" #n ")" ::: "memory")
; #define PG8_BAR __builtin_amdgcn_s_barrier()
; #define PG8_SCHED __builtin_amdgcn_sched_barrier(0)
; template <int NSEG, class Epi, bool ALIGN_EPI = PG8_ALIGN, bool SP2 = PG8_SP2>
; DI void gemm_phase(LAS unsigned char* lds, const Gemm g, const StaticOrder& S, const Epi& E) {
;     ...
;             PG8_LDA(At, 1, 1); PG8_STAGE(PG8_SB(1, 0), b3, v2); PG8_STAGE(PG8_SB(1, 1), b3 + h2, v2); PG8_STAGE(PG8_SA(1, 0), a3, v2);
;             PG8_WAIT_V(8); PG8_WAIT_L(0); PG8_BAR; PG8_MMA(1, 0, At, B0); PG8_MMA(1, 1, At, B1); PG8_BAR; PG8_SCHED;
	s_setprio 0
	s_add_i32 s38, s68, s50
	v_lshl_add_u64 v[204:205], v[204:205], 0, s[16:17]
	s_mov_b32 m0, s38
	ds_read_b128 v[162:165], v209 offset:49152
	ds_read_b128 v[166:169], v209 offset:50176
	ds_read_b128 v[170:173], v209 offset:51200
	ds_read_b128 v[188:191], v209 offset:52224
	ds_read_b128 v[192:195], v209 offset:53248
	ds_read_b128 v[196:199], v209 offset:54272
	ds_read_b128 v[200:203], v209 offset:55296
	ds_read_b128 v[212:215], v209 offset:56320
	global_load_lds_dwordx4 v[204:205], off
	s_add_i32 m0, s38, 0x2000
	s_add_u32 s34, s34, 0x80080
	v_lshl_add_u64 v[204:205], v[216:217], 0, s[16:17]
	s_addc_u32 s35, s35, 0
	s_add_i32 s38, s69, s50
	global_load_lds_dwordx4 v[204:205], off
	v_lshl_add_u64 v[204:205], s[34:35], 0, v[174:175]
	s_mov_b32 m0, s38
	s_nop 0
	global_load_lds_dwordx4 v[204:205], off
	v_lshl_add_u64 v[204:205], s[34:35], 0, v[176:177]
	s_add_i32 m0, s38, 0x2000
	s_nop 0
	global_load_lds_dwordx4 v[204:205], off
	v_lshl_add_u64 v[204:205], v[218:219], 0, s[16:17]
	s_mov_b32 m0, s55
	s_nop 0
	global_load_lds_dwordx4 v[204:205], off
	v_lshl_add_u64 v[204:205], v[220:221], 0, s[16:17]
	s_mov_b32 m0, s56
	s_nop 0
	global_load_lds_dwordx4 v[204:205], off
	s_waitcnt vmcnt(8)
	s_waitcnt lgkmcnt(0)
	s_setprio 1
	s_barrier
	v_mfma_f32_16x16x32_bf16 v[94:97], v[102:105], v[162:165], v[94:97]
	v_mfma_f32_16x16x32_bf16 v[90:93], v[110:113], v[162:165], v[90:93]
	v_mfma_f32_16x16x32_bf16 v[86:89], v[102:105], v[170:173], v[86:89]
	v_mfma_f32_16x16x32_bf16 v[82:85], v[110:113], v[170:173], v[82:85]
	v_mfma_f32_16x16x32_bf16 v[78:81], v[102:105], v[192:195], v[78:81]
	v_mfma_f32_16x16x32_bf16 v[74:77], v[110:113], v[192:195], v[74:77]
	v_mfma_f32_16x16x32_bf16 v[70:73], v[102:105], v[200:203], v[70:73]
	v_mfma_f32_16x16x32_bf16 v[66:69], v[110:113], v[200:203], v[66:69]
	v_mfma_f32_16x16x32_bf16 v[94:97], v[106:109], v[166:169], v[94:97]
	v_mfma_f32_16x16x32_bf16 v[90:93], v[114:117], v[166:169], v[90:93]
	v_mfma_f32_16x16x32_bf16 v[86:89], v[106:109], v[188:191], v[86:89]
	v_mfma_f32_16x16x32_bf16 v[82:85], v[114:117], v[188:191], v[82:85]
	v_mfma_f32_16x16x32_bf16 v[78:81], v[106:109], v[196:199], v[78:81]
	v_mfma_f32_16x16x32_bf16 v[74:77], v[114:117], v[196:199], v[74:77]
	v_mfma_f32_16x16x32_bf16 v[70:73], v[106:109], v[212:215], v[70:73]
	v_mfma_f32_16x16x32_bf16 v[66:69], v[114:117], v[212:215], v[66:69]
	v_mfma_f32_16x16x32_bf16 v[30:33], v[118:121], v[162:165], v[30:33]
	v_mfma_f32_16x16x32_bf16 v[26:29], v[126:129], v[162:165], v[26:29]
	v_mfma_f32_16x16x32_bf16 v[22:25], v[118:121], v[170:173], v[22:25]
	v_mfma_f32_16x16x32_bf16 v[14:17], v[126:129], v[170:173], v[14:17]
	v_mfma_f32_16x16x32_bf16 v[18:21], v[118:121], v[192:195], v[18:21]
	v_mfma_f32_16x16x32_bf16 v[10:13], v[126:129], v[192:195], v[10:13]
	v_mfma_f32_16x16x32_bf16 v[6:9], v[118:121], v[200:203], v[6:9]
	v_mfma_f32_16x16x32_bf16 v[2:5], v[126:129], v[200:203], v[2:5]
	v_mfma_f32_16x16x32_bf16 v[30:33], v[122:125], v[166:169], v[30:33]
	v_mfma_f32_16x16x32_bf16 v[26:29], v[130:133], v[166:169], v[26:29]
	v_mfma_f32_16x16x32_bf16 v[22:25], v[122:125], v[188:191], v[22:25]
	v_mfma_f32_16x16x32_bf16 v[14:17], v[130:133], v[188:191], v[14:17]
	v_mfma_f32_16x16x32_bf16 v[18:21], v[122:125], v[196:199], v[18:21]
	v_mfma_f32_16x16x32_bf16 v[10:13], v[130:133], v[196:199], v[10:13]
	v_mfma_f32_16x16x32_bf16 v[6:9], v[122:125], v[212:215], v[6:9]
	v_mfma_f32_16x16x32_bf16 v[2:5], v[130:133], v[212:215], v[2:5]
	s_barrier
	s_setprio 0
	s_add_i32 s67, s67, 2
	s_add_u32 s4, s4, 0x100
	s_addc_u32 s5, s5, 0
	s_add_u32 s65, s65, 0x100
	s_addc_u32 s66, s66, 0
	s_cmp_gt_u32 s67, 29
	s_cbranch_scc0 .LBB0_545
	s_and_b64 vcc, exec, s[18:19]
	s_cbranch_vccz .LBB0_548
	s_barrier

; #define PG8_STAGE(bufoff, gbase, VO) do { _Pragma("unroll") for (int _i = 0; _i < 2; ++_i) \
;         __builtin_amdgcn_global_load_lds((const unsigned*)((const char*)(gbase) + VO[_i]), (LAS unsigned*)(lds + (bufoff) + ldsw + _i * 8192), 16, 0, 0); } while (0)
; #define PG8_LDA(dst, b, h) do { _Pragma("unroll") for (int m = 0; m < 4; ++m) _Pragma("unroll") for (int k = 0; k < 2; ++k) dst[m][k] = *(const LAS bf16x8*)(lds + PG8_SA(b, h) + aoff + m * 2048 + k * 1024); } while (0)
; #define PG8_LDB(dst, b, h) do { _Pragma("unroll") for (int n = 0; n < 2; ++n) _Pragma("unroll") for (int k = 0; k < 2; ++k) dst[n][k] = *(const LAS bf16x8*)(lds + PG8_SB(b, h) + boff + n * 2048 + k * 1024); } while (0)
; #define PG8_MMA(ai, bj, At, Bt) do { __builtin_amdgcn_s_setprio(1); _Pragma("unroll") for (int m = 0; m < 4; ++m) _Pragma("unroll") for (int n = 0; n < 2; ++n) _Pragma("unroll") for (int k = 0; k < 2; ++k) \
;         acc[ai][bj][m][n] = __builtin_amdgcn_mfma_f32_16x16x32_bf16(Bt[n][k], At[m][k], acc[ai][bj][m][n], 0, 0, 0); __builtin_amdgcn_s_setprio(0); } while (0)
; #define PG8_WAIT_V(n) asm volatile("s_waitcnt vmcnt(" #n ")" ::: "memory")
; #define PG8_WAIT_L(n) asm volatile("s_waitcnt lgkmcnt(" #n ")" ::: "memory")
; #define PG8_BAR __builtin_amdgcn_s_barrier()
; #define PG8_SCHED __builtin_amdgcn_sched_barrier(0)
; template <int NSEG, class Epi, bool ALIGN_EPI = PG8_ALIGN, bool SP2 = PG8_SP2>
; DI void gemm_phase(LAS unsigned char* lds, const Gemm g, const StaticOrder& S, const Epi& E) {
;     ...
;             PG8_LDB(B0, 0, 0); PG8_LDB(B1, 0, 1); PG8_SCHED; PG8_LDA(At, 0, 0); PG8_STAGE(PG8_SA(1, 1), a1 + hstepC, voffC);
;             PG8_WAIT_V(8); PG8_WAIT_L(0); PG8_BAR; PG8_MMA(0, 0, At, B0); PG8_MMA(0, 1, At, B1); PG8_BAR; PG8_SCHED;
;             PG8_LDA(At, 0, 1); PG8_STAGE(PG8_SB(0, 0), b2, v2); PG8_STAGE(PG8_SB(0, 1), b2 + h2, v2); PG8_STAGE(PG8_SA(0, 0), a2, v2);
.LBB0_599:
	ds_read_b128 v[146:149], v143
	ds_read_b128 v[150:153], v143 offset:1024
	ds_read_b128 v[154:157], v143 offset:2048
	ds_read_b128 v[158:161], v143 offset:3072
	ds_read_b128 v[162:165], v144
	ds_read_b128 v[166:169], v144 offset:1024
	ds_read_b128 v[170:173], v144 offset:2048
	ds_read_b128 v[174:177], v144 offset:3072
	s_add_u32 s34, s26, 0xffea0080
	s_addc_u32 s35, s27, -1
	s_cmpk_eq_i32 s64, 0x54
	s_cselect_b32 s37, s23, s35
	s_cselect_b32 s36, s22, s34
	s_cselect_b32 s35, s25, s63
	s_cselect_b32 s34, s24, s62
	v_lshl_add_u64 v[210:211], s[26:27], 0, v[134:135]
	s_add_i32 m0, s45, 0xc000
	ds_read_b128 v[178:181], v145
	ds_read_b128 v[182:185], v145 offset:1024
	ds_read_b128 v[186:189], v145 offset:2048
	ds_read_b128 v[190:193], v145 offset:3072
	ds_read_b128 v[194:197], v145 offset:4096
	ds_read_b128 v[198:201], v145 offset:5120
	ds_read_b128 v[202:205], v145 offset:6144
	ds_read_b128 v[206:209], v145 offset:7168
	global_load_lds_dwordx4 v[210:211], off
	v_lshl_add_u64 v[210:211], s[26:27], 0, v[136:137]
	s_add_i32 m0, s45, 0xe000
	s_nop 0
	global_load_lds_dwordx4 v[210:211], off
	s_waitcnt vmcnt(8)
	s_waitcnt lgkmcnt(0)
	s_setprio 1
	s_barrier
	v_mfma_f32_16x16x32_bf16 v[126:129], v[146:149], v[178:181], v[126:129]
	v_mfma_f32_16x16x32_bf16 v[122:125], v[154:157], v[178:181], v[122:125]
	v_mfma_f32_16x16x32_bf16 v[118:121], v[146:149], v[186:189], v[118:121]
	v_mfma_f32_16x16x32_bf16 v[114:117], v[154:157], v[186:189], v[114:117]
	v_mfma_f32_16x16x32_bf16 v[102:105], v[146:149], v[194:197], v[102:105]
	v_mfma_f32_16x16x32_bf16 v[98:101], v[154:157], v[194:197], v[98:101]
	v_mfma_f32_16x16x32_bf16 v[86:89], v[146:149], v[202:205], v[86:89]
	v_mfma_f32_16x16x32_bf16 v[82:85], v[154:157], v[202:205], v[82:85]
	v_mfma_f32_16x16x32_bf16 v[126:129], v[150:153], v[182:185], v[126:129]
	v_mfma_f32_16x16x32_bf16 v[122:125], v[158:161], v[182:185], v[122:125]
	v_mfma_f32_16x16x32_bf16 v[118:121], v[150:153], v[190:193], v[118:121]
	v_mfma_f32_16x16x32_bf16 v[114:117], v[158:161], v[190:193], v[114:117]
	v_mfma_f32_16x16x32_bf16 v[102:105], v[150:153], v[198:201], v[102:105]
	v_mfma_f32_16x16x32_bf16 v[98:101], v[158:161], v[198:201], v[98:101]
	v_mfma_f32_16x16x32_bf16 v[86:89], v[150:153], v[206:209], v[86:89]
	v_mfma_f32_16x16x32_bf16 v[82:85], v[158:161], v[206:209], v[82:85]
	v_mfma_f32_16x16x32_bf16 v[110:113], v[162:165], v[178:181], v[110:113]
	v_mfma_f32_16x16x32_bf16 v[106:109], v[170:173], v[178:181], v[106:109]
	v_mfma_f32_16x16x32_bf16 v[94:97], v[162:165], v[186:189], v[94:97]
	v_mfma_f32_16x16x32_bf16 v[90:93], v[170:173], v[186:189], v[90:93]
	v_mfma_f32_16x16x32_bf16 v[78:81], v[162:165], v[194:197], v[78:81]
	v_mfma_f32_16x16x32_bf16 v[74:77], v[170:173], v[194:197], v[74:77]
	v_mfma_f32_16x16x32_bf16 v[70:73], v[162:165], v[202:205], v[70:73]
	v_mfma_f32_16x16x32_bf16 v[66:69], v[170:173], v[202:205], v[66:69]
	v_mfma_f32_16x16x32_bf16 v[110:113], v[166:169], v[182:185], v[110:113]
	v_mfma_f32_16x16x32_bf16 v[106:109], v[174:177], v[182:185], v[106:109]
	v_mfma_f32_16x16x32_bf16 v[94:97], v[166:169], v[190:193], v[94:97]
	v_mfma_f32_16x16x32_bf16 v[90:93], v[174:177], v[190:193], v[90:93]
	v_mfma_f32_16x16x32_bf16 v[78:81], v[166:169], v[198:201], v[78:81]
	v_mfma_f32_16x16x32_bf16 v[74:77], v[174:177], v[198:201], v[74:77]
	v_mfma_f32_16x16x32_bf16 v[70:73], v[166:169], v[206:209], v[70:73]
	v_mfma_f32_16x16x32_bf16 v[66:69], v[174:177], v[206:209], v[66:69]
	s_barrier
	s_setprio 0
	s_add_i32 s65, s52, s44
	v_lshl_add_u64 v[210:211], s[34:35], 0, v[130:131]
	s_mov_b32 m0, s65
	ds_read_b128 v[178:181], v145 offset:16384
	ds_read_b128 v[182:185], v145 offset:17408
	ds_read_b128 v[186:189], v145 offset:18432
	ds_read_b128 v[190:193], v145 offset:19456
	ds_read_b128 v[194:197], v145 offset:20480
	ds_read_b128 v[198:201], v145 offset:21504
	ds_read_b128 v[202:205], v145 offset:22528
	ds_read_b128 v[206:209], v145 offset:23552
	global_load_lds_dwordx4 v[210:211], off
	s_add_i32 m0, s65, 0x2000
	s_add_u32 s66, s34, 0x160000
	v_lshl_add_u64 v[212:213], s[34:35], 0, v[132:133]
	s_addc_u32 s67, s35, 0
	s_add_i32 s65, s53, s44
	global_load_lds_dwordx4 v[212:213], off
	v_lshl_add_u64 v[214:215], s[66:67], 0, v[130:131]
	s_mov_b32 m0, s65
	v_lshl_add_u64 v[216:217], s[36:37], 0, v[132:133]
	global_load_lds_dwordx4 v[214:215], off
	v_lshl_add_u64 v[214:215], s[66:67], 0, v[132:133]
	s_add_i32 m0, s65, 0x2000
	s_nop 0
	global_load_lds_dwordx4 v[214:215], off
	v_lshl_add_u64 v[214:215], s[36:37], 0, v[130:131]
	s_mov_b32 m0, s45
	s_nop 0
	global_load_lds_dwordx4 v[214:215], off
	s_mov_b32 m0, s46
	s_nop 0
	global_load_lds_dwordx4 v[216:217], off
	s_waitcnt vmcnt(8)
	s_waitcnt lgkmcnt(0)
	s_setprio 1
	s_barrier
; #define PG8_STAGE(bufoff, gbase, VO) do { _Pragma("unroll") for (int _i = 0; _i < 2; ++_i) \
;         __builtin_amdgcn_global_load_lds((const unsigned*)((const char*)(gbase) + VO[_i]), (LAS unsigned*)(lds + (bufoff) + ldsw + _i * 8192), 16, 0, 0); } while (0)
; #define PG8_LDA(dst, b, h) do { _Pragma("unroll") for (int m = 0; m < 4; ++m) _Pragma("unroll") for (int k = 0; k < 2; ++k) dst[m][k] = *(const LAS bf16x8*)(lds + PG8_SA(b, h) + aoff + m * 2048 + k * 1024); } while (0)
; #define PG8_LDB(dst, b, h) do { _Pragma("unroll") for (int n = 0; n < 2; ++n) _Pragma("unroll") for (int k = 0; k < 2; ++k) dst[n][k] = *(const LAS bf16x8*)(lds + PG8_SB(b, h) + boff + n * 2048 + k * 1024); } while (0)
; #define PG8_MMA(ai, bj, At, Bt) do { __builtin_amdgcn_s_setprio(1); _Pragma("unroll") for (int m = 0; m < 4; ++m) _Pragma("unroll") for (int n = 0; n < 2; ++n) _Pragma("unroll") for (int k = 0; k < 2; ++k) \
;         acc[ai][bj][m][n] = __builtin_amdgcn_mfma_f32_16x16x32_bf16(Bt[n][k], At[m][k], acc[ai][bj][m][n], 0, 0, 0); __builtin_amdgcn_s_setprio(0); } while (0)
; #define PG8_WAIT_V(n) asm volatile("s_waitcnt vmcnt(" #n ")" ::: "memory")
; #define PG8_WAIT_L(n) asm volatile("s_waitcnt lgkmcnt(" #n ")" ::: "memory")
; #define PG8_BAR __builtin_amdgcn_s_barrier()
; #define PG8_SCHED __builtin_amdgcn_sched_barrier(0)
; template <int NSEG, class Epi, bool ALIGN_EPI = PG8_ALIGN, bool SP2 = PG8_SP2>
; DI void gemm_phase(LAS unsigned char* lds, const Gemm g, const StaticOrder& S, const Epi& E) {
;     ...
;             PG8_WAIT_V(8); PG8_WAIT_L(0); PG8_BAR; PG8_MMA(1, 0, At, B0); PG8_MMA(1, 1, At, B1); PG8_BAR; PG8_SCHED;
;             PG8_LDB(B0, 1, 0); PG8_LDB(B1, 1, 1); PG8_SCHED; PG8_LDA(At, 1, 0); PG8_STAGE(PG8_SA(0, 1), a2 + h2, v2);
;             PG8_WAIT_V(8); PG8_WAIT_L(0); PG8_BAR; PG8_MMA(0, 0, At, B0); PG8_MMA(0, 1, At, B1); PG8_BAR; PG8_SCHED;
	v_mfma_f32_16x16x32_bf16 v[54:57], v[146:149], v[178:181], v[54:57]
	v_mfma_f32_16x16x32_bf16 v[46:49], v[154:157], v[178:181], v[46:49]
	v_mfma_f32_16x16x32_bf16 v[38:41], v[146:149], v[186:189], v[38:41]
	v_mfma_f32_16x16x32_bf16 v[34:37], v[154:157], v[186:189], v[34:37]
	v_mfma_f32_16x16x32_bf16 v[22:25], v[146:149], v[194:197], v[22:25]
	v_mfma_f32_16x16x32_bf16 v[18:21], v[154:157], v[194:197], v[18:21]
	v_mfma_f32_16x16x32_bf16 v[6:9], v[146:149], v[202:205], v[6:9]
	v_mfma_f32_16x16x32_bf16 v[2:5], v[154:157], v[202:205], v[2:5]
	v_mfma_f32_16x16x32_bf16 v[54:57], v[150:153], v[182:185], v[54:57]
	v_mfma_f32_16x16x32_bf16 v[46:49], v[158:161], v[182:185], v[46:49]
	v_mfma_f32_16x16x32_bf16 v[38:41], v[150:153], v[190:193], v[38:41]
	v_mfma_f32_16x16x32_bf16 v[34:37], v[158:161], v[190:193], v[34:37]
	v_mfma_f32_16x16x32_bf16 v[22:25], v[150:153], v[198:201], v[22:25]
	v_mfma_f32_16x16x32_bf16 v[18:21], v[158:161], v[198:201], v[18:21]
	v_mfma_f32_16x16x32_bf16 v[6:9], v[150:153], v[206:209], v[6:9]
	v_mfma_f32_16x16x32_bf16 v[2:5], v[158:161], v[206:209], v[2:5]
	v_mfma_f32_16x16x32_bf16 v[30:33], v[162:165], v[178:181], v[30:33]
	v_mfma_f32_16x16x32_bf16 v[26:29], v[170:173], v[178:181], v[26:29]
	v_mfma_f32_16x16x32_bf16 v[14:17], v[162:165], v[186:189], v[14:17]
	v_mfma_f32_16x16x32_bf16 v[10:13], v[170:173], v[186:189], v[10:13]
	v_mfma_f32_16x16x32_bf16 v[58:61], v[162:165], v[194:197], v[58:61]
	v_mfma_f32_16x16x32_bf16 v[62:65], v[170:173], v[194:197], v[62:65]
	v_mfma_f32_16x16x32_bf16 v[42:45], v[162:165], v[202:205], v[42:45]
	v_mfma_f32_16x16x32_bf16 v[50:53], v[170:173], v[202:205], v[50:53]
	v_mfma_f32_16x16x32_bf16 v[30:33], v[166:169], v[182:185], v[30:33]
	v_mfma_f32_16x16x32_bf16 v[26:29], v[174:177], v[182:185], v[26:29]
	v_mfma_f32_16x16x32_bf16 v[14:17], v[166:169], v[190:193], v[14:17]
	v_mfma_f32_16x16x32_bf16 v[10:13], v[174:177], v[190:193], v[10:13]
	v_mfma_f32_16x16x32_bf16 v[58:61], v[166:169], v[198:201], v[58:61]
	v_mfma_f32_16x16x32_bf16 v[62:65], v[174:177], v[198:201], v[62:65]
	v_mfma_f32_16x16x32_bf16 v[42:45], v[166:169], v[206:209], v[42:45]
	v_mfma_f32_16x16x32_bf16 v[50:53], v[174:177], v[206:209], v[50:53]
	s_barrier
	s_setprio 0
	s_add_i32 s65, 0, 0x18000
	s_add_i32 s66, 0, 0x1c000
	v_add_u32_e32 v158, s65, v141
	v_add_u32_e32 v174, s66, v141
	ds_read_b128 v[146:149], v158
	ds_read_b128 v[150:153], v158 offset:1024
	ds_read_b128 v[154:157], v158 offset:2048
	ds_read_b128 v[158:161], v158 offset:3072
	ds_read_b128 v[162:165], v174
	ds_read_b128 v[166:169], v174 offset:1024
	ds_read_b128 v[170:173], v174 offset:2048
	ds_read_b128 v[174:177], v174 offset:3072
	s_add_u32 s36, s36, 0x160000
	s_addc_u32 s37, s37, 0
	s_mov_b32 m0, s47
	v_lshl_add_u64 v[218:219], s[36:37], 0, v[130:131]
	ds_read_b128 v[178:181], v145 offset:32768
	ds_read_b128 v[182:185], v145 offset:33792
	ds_read_b128 v[186:189], v145 offset:34816
	ds_read_b128 v[190:193], v145 offset:35840
	ds_read_b128 v[194:197], v145 offset:36864
	ds_read_b128 v[198:201], v145 offset:37888
	ds_read_b128 v[202:205], v145 offset:38912
	ds_read_b128 v[206:209], v145 offset:39936
	global_load_lds_dwordx4 v[218:219], off
	v_lshl_add_u64 v[218:219], s[36:37], 0, v[132:133]
	s_mov_b32 m0, s48
	s_nop 0
	global_load_lds_dwordx4 v[218:219], off
	s_waitcnt vmcnt(8)
	s_waitcnt lgkmcnt(0)
	s_setprio 1
	s_barrier
	v_mfma_f32_16x16x32_bf16 v[126:129], v[146:149], v[178:181], v[126:129]
	v_mfma_f32_16x16x32_bf16 v[122:125], v[154:157], v[178:181], v[122:125]
	v_mfma_f32_16x16x32_bf16 v[118:121], v[146:149], v[186:189], v[118:121]
	v_mfma_f32_16x16x32_bf16 v[114:117], v[154:157], v[186:189], v[114:117]
	v_mfma_f32_16x16x32_bf16 v[102:105], v[146:149], v[194:197], v[102:105]
	v_mfma_f32_16x16x32_bf16 v[98:101], v[154:157], v[194:197], v[98:101]
	v_mfma_f32_16x16x32_bf16 v[86:89], v[146:149], v[202:205], v[86:89]
	v_mfma_f32_16x16x32_bf16 v[82:85], v[154:157], v[202:205], v[82:85]
	v_mfma_f32_16x16x32_bf16 v[126:129], v[150:153], v[182:185], v[126:129]
	v_mfma_f32_16x16x32_bf16 v[122:125], v[158:161], v[182:185], v[122:125]
	v_mfma_f32_16x16x32_bf16 v[118:121], v[150:153], v[190:193], v[118:121]
	v_mfma_f32_16x16x32_bf16 v[114:117], v[158:161], v[190:193], v[114:117]
	v_mfma_f32_16x16x32_bf16 v[102:105], v[150:153], v[198:201], v[102:105]
	v_mfma_f32_16x16x32_bf16 v[98:101], v[158:161], v[198:201], v[98:101]
	v_mfma_f32_16x16x32_bf16 v[86:89], v[150:153], v[206:209], v[86:89]
	v_mfma_f32_16x16x32_bf16 v[82:85], v[158:161], v[206:209], v[82:85]
	v_mfma_f32_16x16x32_bf16 v[110:113], v[162:165], v[178:181], v[110:113]
	v_mfma_f32_16x16x32_bf16 v[106:109], v[170:173], v[178:181], v[106:109]
	v_mfma_f32_16x16x32_bf16 v[94:97], v[162:165], v[186:189], v[94:97]
	v_mfma_f32_16x16x32_bf16 v[90:93], v[170:173], v[186:189], v[90:93]
	v_mfma_f32_16x16x32_bf16 v[78:81], v[162:165], v[194:197], v[78:81]
	v_mfma_f32_16x16x32_bf16 v[74:77], v[170:173], v[194:197], v[74:77]
	v_mfma_f32_16x16x32_bf16 v[70:73], v[162:165], v[202:205], v[70:73]
	v_mfma_f32_16x16x32_bf16 v[66:69], v[170:173], v[202:205], v[66:69]
	v_mfma_f32_16x16x32_bf16 v[110:113], v[166:169], v[182:185], v[110:113]
	v_mfma_f32_16x16x32_bf16 v[106:109], v[174:177], v[182:185], v[106:109]
	v_mfma_f32_16x16x32_bf16 v[94:97], v[166:169], v[190:193], v[94:97]
	v_mfma_f32_16x16x32_bf16 v[90:93], v[174:177], v[190:193], v[90:93]
	v_mfma_f32_16x16x32_bf16 v[78:81], v[166:169], v[198:201], v[78:81]
	v_mfma_f32_16x16x32_bf16 v[74:77], v[174:177], v[198:201], v[74:77]
	v_mfma_f32_16x16x32_bf16 v[70:73], v[166:169], v[206:209], v[70:73]
	v_mfma_f32_16x16x32_bf16 v[66:69], v[174:177], v[206:209], v[66:69]
	s_barrier
; #define PG8_STAGE(bufoff, gbase, VO) do { _Pragma("unroll") for (int _i = 0; _i < 2; ++_i) \
;         __builtin_amdgcn_global_load_lds((const unsigned*)((const char*)(gbase) + VO[_i]), (LAS unsigned*)(lds + (bufoff) + ldsw + _i * 8192), 16, 0, 0); } while (0)
; #define PG8_LDA(dst, b, h) do { _Pragma("unroll") for (int m = 0; m < 4; ++m) _Pragma("unroll") for (int k = 0; k < 2; ++k) dst[m][k] = *(const LAS bf16x8*)(lds + PG8_SA(b, h) + aoff + m * 2048 + k * 1024); } while (0)
; #define PG8_MMA(ai, bj, At, Bt) do { __builtin_amdgcn_s_setprio(1); _Pragma("unroll") for (int m = 0; m < 4; ++m) _Pragma("unroll") for (int n = 0; n < 2; ++n) _Pragma("unroll") for (int k = 0; k < 2; ++k) \
;         acc[ai][bj][m][n] = __builtin_amdgcn_mfma_f32_16x16x32_bf16(Bt[n][k], At[m][k], acc[ai][bj][m][n], 0, 0, 0); __builtin_amdgcn_s_setprio(0); } while (0)
; #define PG8_WAIT_V(n) asm volatile("s_waitcnt vmcnt(" #n ")" ::: "memory")
; #define PG8_WAIT_L(n) asm volatile("s_waitcnt lgkmcnt(" #n ")" ::: "memory")
; #define PG8_BAR __builtin_amdgcn_s_barrier()
; #define PG8_SCHED __builtin_amdgcn_sched_barrier(0)
; template <int NSEG, class Epi, bool ALIGN_EPI = PG8_ALIGN, bool SP2 = PG8_SP2>
; DI void gemm_phase(LAS unsigned char* lds, const Gemm g, const StaticOrder& S, const Epi& E) {
;     ...
;             PG8_LDA(At, 1, 1); PG8_STAGE(PG8_SB(1, 0), b3, v2); PG8_STAGE(PG8_SB(1, 1), b3 + h2, v2); PG8_STAGE(PG8_SA(1, 0), a3, v2);
;             PG8_WAIT_V(8); PG8_WAIT_L(0); PG8_BAR; PG8_MMA(1, 0, At, B0); PG8_MMA(1, 1, At, B1); PG8_BAR; PG8_SCHED;
	s_setprio 0
	s_add_i32 s36, s65, s44
	v_lshl_add_u64 v[210:211], v[210:211], 0, s[10:11]
	s_mov_b32 m0, s36
	ds_read_b128 v[178:181], v145 offset:49152
	ds_read_b128 v[182:185], v145 offset:50176
	ds_read_b128 v[186:189], v145 offset:51200
	ds_read_b128 v[190:193], v145 offset:52224
	ds_read_b128 v[194:197], v145 offset:53248
	ds_read_b128 v[198:201], v145 offset:54272
	ds_read_b128 v[202:205], v145 offset:55296
	ds_read_b128 v[206:209], v145 offset:56320
	global_load_lds_dwordx4 v[210:211], off
	s_add_i32 m0, s36, 0x2000
	s_add_u32 s34, s34, 0x160080
	v_lshl_add_u64 v[210:211], v[212:213], 0, s[10:11]
	s_addc_u32 s35, s35, 0
	s_add_i32 s36, s66, s44
	global_load_lds_dwordx4 v[210:211], off
	v_lshl_add_u64 v[210:211], s[34:35], 0, v[130:131]
	s_mov_b32 m0, s36
	s_nop 0
	global_load_lds_dwordx4 v[210:211], off
	v_lshl_add_u64 v[210:211], s[34:35], 0, v[132:133]
	s_add_i32 m0, s36, 0x2000
	s_nop 0
	global_load_lds_dwordx4 v[210:211], off
	v_lshl_add_u64 v[210:211], v[214:215], 0, s[10:11]
	s_mov_b32 m0, s49
	s_nop 0
	global_load_lds_dwordx4 v[210:211], off
	v_lshl_add_u64 v[210:211], v[216:217], 0, s[10:11]
	s_mov_b32 m0, s50
	s_nop 0
	global_load_lds_dwordx4 v[210:211], off
	s_waitcnt vmcnt(8)
	s_waitcnt lgkmcnt(0)
	s_setprio 1
	s_barrier
	v_mfma_f32_16x16x32_bf16 v[54:57], v[146:149], v[178:181], v[54:57]
	v_mfma_f32_16x16x32_bf16 v[46:49], v[154:157], v[178:181], v[46:49]
	v_mfma_f32_16x16x32_bf16 v[38:41], v[146:149], v[186:189], v[38:41]
	v_mfma_f32_16x16x32_bf16 v[34:37], v[154:157], v[186:189], v[34:37]
	v_mfma_f32_16x16x32_bf16 v[22:25], v[146:149], v[194:197], v[22:25]
	v_mfma_f32_16x16x32_bf16 v[18:21], v[154:157], v[194:197], v[18:21]
	v_mfma_f32_16x16x32_bf16 v[6:9], v[146:149], v[202:205], v[6:9]
	v_mfma_f32_16x16x32_bf16 v[2:5], v[154:157], v[202:205], v[2:5]
	v_mfma_f32_16x16x32_bf16 v[54:57], v[150:153], v[182:185], v[54:57]
	v_mfma_f32_16x16x32_bf16 v[46:49], v[158:161], v[182:185], v[46:49]
	v_mfma_f32_16x16x32_bf16 v[38:41], v[150:153], v[190:193], v[38:41]
	v_mfma_f32_16x16x32_bf16 v[34:37], v[158:161], v[190:193], v[34:37]
	v_mfma_f32_16x16x32_bf16 v[22:25], v[150:153], v[198:201], v[22:25]
	v_mfma_f32_16x16x32_bf16 v[18:21], v[158:161], v[198:201], v[18:21]
	v_mfma_f32_16x16x32_bf16 v[6:9], v[150:153], v[206:209], v[6:9]
	v_mfma_f32_16x16x32_bf16 v[2:5], v[158:161], v[206:209], v[2:5]
	v_mfma_f32_16x16x32_bf16 v[30:33], v[162:165], v[178:181], v[30:33]
	v_mfma_f32_16x16x32_bf16 v[26:29], v[170:173], v[178:181], v[26:29]
	v_mfma_f32_16x16x32_bf16 v[14:17], v[162:165], v[186:189], v[14:17]
	v_mfma_f32_16x16x32_bf16 v[10:13], v[170:173], v[186:189], v[10:13]
	v_mfma_f32_16x16x32_bf16 v[58:61], v[162:165], v[194:197], v[58:61]
	v_mfma_f32_16x16x32_bf16 v[62:65], v[170:173], v[194:197], v[62:65]
	v_mfma_f32_16x16x32_bf16 v[42:45], v[162:165], v[202:205], v[42:45]
	v_mfma_f32_16x16x32_bf16 v[50:53], v[170:173], v[202:205], v[50:53]
	v_mfma_f32_16x16x32_bf16 v[30:33], v[166:169], v[182:185], v[30:33]
	v_mfma_f32_16x16x32_bf16 v[26:29], v[174:177], v[182:185], v[26:29]
	v_mfma_f32_16x16x32_bf16 v[14:17], v[166:169], v[190:193], v[14:17]
	v_mfma_f32_16x16x32_bf16 v[10:13], v[174:177], v[190:193], v[10:13]
	v_mfma_f32_16x16x32_bf16 v[58:61], v[166:169], v[198:201], v[58:61]
	v_mfma_f32_16x16x32_bf16 v[62:65], v[174:177], v[198:201], v[62:65]
	v_mfma_f32_16x16x32_bf16 v[42:45], v[166:169], v[206:209], v[42:45]
	v_mfma_f32_16x16x32_bf16 v[50:53], v[174:177], v[206:209], v[50:53]
	s_barrier
	s_setprio 0
	s_add_i32 s64, s64, 2
	s_add_u32 s26, s26, 0x100
	s_addc_u32 s27, s27, 0
	s_add_u32 s62, s62, 0x100
	s_addc_u32 s63, s63, 0
	s_cmpk_gt_u32 s64, 0x55
	s_cbranch_scc0 .LBB0_599
	s_and_b64 vcc, exec, s[12:13]
	s_cbranch_vccz .LBB0_602
	s_barrier
